# v18 + first K-iteration of every GEMM loop peeled (zero-C MFMAs inline) instead of a per-iteration flag test and branch in two MFMA segments
# speedup vs baseline: 1.0122x; 1.0122x over previous
; #define PG8_STAGE(bufoff, gbase, voff) do { _Pragma("unroll") for (int _i = 0; _i < 2; ++_i) \
;         __builtin_amdgcn_global_load_lds((const unsigned*)((const char*)(gbase) + (voff)[_i]), (PG8_LAS unsigned*)(lds + (bufoff) + ldsw + _i * 8192), 16, 0, 0); } while (0)
; #define PG8_LDA(dst, b, h) do { _Pragma("unroll") for (int m = 0; m < 4; ++m) _Pragma("unroll") for (int k = 0; k < 2; ++k) dst[m][k] = *(const PG8_LAS bf16x8*)(lds + PG8_SA(b, h) + aoff + m * 2048 + k * 1024); } while (0)
; #define PG8_LDB(dst, b, h) do { _Pragma("unroll") for (int n = 0; n < 2; ++n) _Pragma("unroll") for (int k = 0; k < 2; ++k) dst[n][k] = *(const PG8_LAS bf16x8*)(lds + PG8_SB(b, h) + boff + n * 2048 + k * 1024); } while (0)
; #define PG8_WAIT_V(n) asm volatile("s_waitcnt vmcnt(" #n ")" ::: "memory")
; #define PG8_WAIT_L(n) asm volatile("s_waitcnt lgkmcnt(" #n ")" ::: "memory")
; template <class Epi, class Sched, bool ALIGN_EPI = false>
; __device__ __forceinline__ void gemm_phase8(PG8_LAS unsigned char* lds, const Gemm g, const Sched& S, const Epi& E) {
;     ...
;         const bool has_next = S.next(ui + 1, nxt);
;         const size_t nko = (has_next && nxt.kp > 0) ? (size_t)nxt.kp * g.kpiece : 0;
;         const char* nA = has_next ? (const char*)g.A + (size_t)nxt.pm * tstepA + (size_t)nxt.pn * astep + nko : cA; const char* nB = has_next ? (const char*)g.Bt + (size_t)nxt.pn * tstepB + nko : cB;
;         const int nt = (cur.kp < 0 ? g.K : g.kpiece) / 128;
;         for (int t = 0; t < nt; t += 2) {
;             const bool last = (t == nt - 2);
;             const char* a1 = cA + (size_t)(t + 1) * kstep;
;             const char* a2 = last ? nA : cA + (size_t)(t + 2) * kstep; const char* b2 = last ? nB : cB + (size_t)(t + 2) * kstep;
;             const char* a3 = a2 + kstep; const char* b3 = b2 + kstep;
;             if (last && has_next) S.a_ready(nxt);
;             PG8_LDB(B0, 0, 0); PG8_LDB(B1, 0, 1); PG8_SCHED; PG8_LDA(At, 0, 0); PG8_STAGE(PG8_SA(1, 1), a1 + hstepA, voffA);
;             PG8_WAIT_V(8); PG8_WAIT_L(0); PG8_BAR; PG8_MMA(0, 0, At, B0); PG8_MMA(0, 1, At, B1); PG8_BAR; PG8_SCHED;
;             PG8_LDA(At, 0, 1); PG8_STAGE(PG8_SB(0, 0), b2, voffB); PG8_STAGE(PG8_SB(0, 1), b2 + hstepB, voffB); PG8_STAGE(PG8_SA(0, 0), a2, voffA);
;             PG8_WAIT_V(8); PG8_WAIT_L(0); PG8_BAR; PG8_MMA(1, 0, At, B0); PG8_MMA(1, 1, At, B1); PG8_BAR; PG8_SCHED;
.LBB0_324:
	s_ashr_i32 s15, s14, 31
	s_lshl_b64 s[16:17], s[14:15], 19
	s_add_u32 s16, s28, s16
	s_addc_u32 s17, s29, s17
	s_and_b64 s[18:19], s[2:3], exec
	s_cselect_b32 s15, s17, s23
	s_cselect_b32 s61, s16, s22
	s_ashr_i32 s13, s12, 31
	s_lshl_b64 s[18:19], s[12:13], 19
	s_add_u32 s18, s4, s18
	s_addc_u32 s19, s5, s19
	s_and_b64 s[26:27], s[2:3], exec
	s_cselect_b32 s13, s19, s25
	s_cselect_b32 s62, s18, s24
	s_add_u32 s22, s22, 0x40080
	s_addc_u32 s23, s23, 0
	s_add_u32 s63, s24, 0x100
	s_addc_u32 s64, s25, 0
	s_mov_b32 s65, -2
	ds_read_b128 v[18:21], v191
	ds_read_b128 v[26:29], v191 offset:2048
	ds_read_b128 v[22:25], v192
	ds_read_b128 v[30:33], v192 offset:2048
	ds_read_b128 v[2:5], v193
	ds_read_b128 v[10:13], v193 offset:2048
	ds_read_b128 v[6:9], v194
	ds_read_b128 v[14:17], v194 offset:2048
	s_add_u32 s24, s22, 0xfffc0080
	s_addc_u32 s25, s23, -1
	s_cmp_eq_u32 s65, 12
	s_cselect_b32 s27, s15, s25
	s_cselect_b32 s26, s61, s24
	s_cselect_b32 s25, s13, s64
	s_cselect_b32 s24, s62, s63
	s_add_i32 m0, s21, 0xc000
	ds_read_b128 v[178:181], v195
	ds_read_b128 v[198:201], v195 offset:2048
	ds_read_b128 v[182:185], v196
	ds_read_b128 v[202:205], v196 offset:2048
	ds_read_b128 v[206:209], v195 offset:4096
	ds_read_b128 v[214:217], v195 offset:6144
	ds_read_b128 v[210:213], v196 offset:4096
	ds_read_b128 v[218:221], v196 offset:6144
	global_load_lds_dwordx4 v170, s[22:23]
	s_add_i32 m0, s21, 0xe000
	s_nop 0
	global_load_lds_dwordx4 v172, s[22:23]
	s_waitcnt vmcnt(8)
	s_waitcnt lgkmcnt(0)
	s_barrier
	s_setprio 1
	s_waitcnt lgkmcnt(0)
	v_mfma_scale_f32_16x16x128_f8f6f4 v[158:161], v[18:25], v[178:185], 0, v1, v186 op_sel_hi:[0,0,0]
	v_mfma_scale_f32_16x16x128_f8f6f4 v[150:153], v[26:33], v[178:185], 0, v1, v186 op_sel_hi:[0,0,0]
	v_mfma_scale_f32_16x16x128_f8f6f4 v[142:145], v[18:25], v[198:205], 0, v1, v186 op_sel_hi:[0,0,0]
	v_mfma_scale_f32_16x16x128_f8f6f4 v[134:137], v[26:33], v[198:205], 0, v1, v186 op_sel_hi:[0,0,0]
	v_mfma_scale_f32_16x16x128_f8f6f4 v[126:129], v[18:25], v[206:213], 0, v1, v186 op_sel_hi:[0,0,0]
	v_mfma_scale_f32_16x16x128_f8f6f4 v[118:121], v[26:33], v[206:213], 0, v1, v186 op_sel_hi:[0,0,0]
	v_mfma_scale_f32_16x16x128_f8f6f4 v[110:113], v[18:25], v[214:221], 0, v1, v186 op_sel_hi:[0,0,0]
	v_mfma_scale_f32_16x16x128_f8f6f4 v[102:105], v[26:33], v[214:221], 0, v1, v186 op_sel_hi:[0,0,0]
	s_setprio 0
	s_setprio 1
	v_mfma_scale_f32_16x16x128_f8f6f4 v[154:157], v[2:9], v[178:185], 0, v1, v186 op_sel_hi:[0,0,0]
	v_mfma_scale_f32_16x16x128_f8f6f4 v[146:149], v[10:17], v[178:185], 0, v1, v186 op_sel_hi:[0,0,0]
	v_mfma_scale_f32_16x16x128_f8f6f4 v[138:141], v[2:9], v[198:205], 0, v1, v186 op_sel_hi:[0,0,0]
	v_mfma_scale_f32_16x16x128_f8f6f4 v[130:133], v[10:17], v[198:205], 0, v1, v186 op_sel_hi:[0,0,0]
	v_mfma_scale_f32_16x16x128_f8f6f4 v[122:125], v[2:9], v[206:213], 0, v1, v186 op_sel_hi:[0,0,0]
	v_mfma_scale_f32_16x16x128_f8f6f4 v[114:117], v[10:17], v[206:213], 0, v1, v186 op_sel_hi:[0,0,0]
	v_mfma_scale_f32_16x16x128_f8f6f4 v[106:109], v[2:9], v[214:221], 0, v1, v186 op_sel_hi:[0,0,0]
	v_mfma_scale_f32_16x16x128_f8f6f4 v[98:101], v[10:17], v[214:221], 0, v1, v186 op_sel_hi:[0,0,0]
	s_setprio 0
	s_barrier
	s_add_i32 s66, s57, s30
	s_mov_b32 m0, s66
	ds_read_b128 v[198:201], v195 offset:16384
	ds_read_b128 v[206:209], v195 offset:18432
	ds_read_b128 v[202:205], v196 offset:16384
	ds_read_b128 v[210:213], v196 offset:18432
	ds_read_b128 v[214:217], v195 offset:20480
	ds_read_b128 v[222:225], v195 offset:22528
	ds_read_b128 v[218:221], v196 offset:20480
	ds_read_b128 v[226:229], v196 offset:22528
	global_load_lds_dwordx4 v164, s[24:25]
	s_add_i32 m0, s66, 0x2000
	s_add_u32 s66, s24, 0x40000
	s_addc_u32 s67, s25, 0
	s_add_i32 s72, s58, s30
	global_load_lds_dwordx4 v168, s[24:25]
	s_mov_b32 m0, s72
	s_nop 0
	global_load_lds_dwordx4 v164, s[66:67]
	s_add_i32 m0, s72, 0x2000
	s_nop 0
	global_load_lds_dwordx4 v168, s[66:67]
	s_mov_b32 m0, s21
	s_nop 0
	global_load_lds_dwordx4 v162, s[26:27]
	s_mov_b32 m0, s34
	s_nop 0
	global_load_lds_dwordx4 v166, s[26:27]
	s_waitcnt vmcnt(8)
	s_waitcnt lgkmcnt(0)
	s_barrier
	s_setprio 1
	s_waitcnt lgkmcnt(0)
	v_mfma_scale_f32_16x16x128_f8f6f4 v[94:97], v[18:25], v[198:205], 0, v1, v186 op_sel_hi:[0,0,0]
	v_mfma_scale_f32_16x16x128_f8f6f4 v[86:89], v[26:33], v[198:205], 0, v1, v186 op_sel_hi:[0,0,0]
	v_mfma_scale_f32_16x16x128_f8f6f4 v[78:81], v[18:25], v[206:213], 0, v1, v186 op_sel_hi:[0,0,0]
	v_mfma_scale_f32_16x16x128_f8f6f4 v[70:73], v[26:33], v[206:213], 0, v1, v186 op_sel_hi:[0,0,0]
	v_mfma_scale_f32_16x16x128_f8f6f4 v[62:65], v[18:25], v[214:221], 0, v1, v186 op_sel_hi:[0,0,0]
	v_mfma_scale_f32_16x16x128_f8f6f4 v[54:57], v[26:33], v[214:221], 0, v1, v186 op_sel_hi:[0,0,0]
	v_mfma_scale_f32_16x16x128_f8f6f4 v[46:49], v[18:25], v[222:229], 0, v1, v186 op_sel_hi:[0,0,0]
	v_mfma_scale_f32_16x16x128_f8f6f4 v[38:41], v[26:33], v[222:229], 0, v1, v186 op_sel_hi:[0,0,0]
	s_setprio 0
	s_setprio 1
	v_mfma_scale_f32_16x16x128_f8f6f4 v[90:93], v[2:9], v[198:205], 0, v1, v186 op_sel_hi:[0,0,0]
	v_mfma_scale_f32_16x16x128_f8f6f4 v[82:85], v[10:17], v[198:205], 0, v1, v186 op_sel_hi:[0,0,0]
	v_mfma_scale_f32_16x16x128_f8f6f4 v[74:77], v[2:9], v[206:213], 0, v1, v186 op_sel_hi:[0,0,0]
	v_mfma_scale_f32_16x16x128_f8f6f4 v[66:69], v[10:17], v[206:213], 0, v1, v186 op_sel_hi:[0,0,0]
	v_mfma_scale_f32_16x16x128_f8f6f4 v[58:61], v[2:9], v[214:221], 0, v1, v186 op_sel_hi:[0,0,0]
	v_mfma_scale_f32_16x16x128_f8f6f4 v[50:53], v[10:17], v[214:221], 0, v1, v186 op_sel_hi:[0,0,0]
	v_mfma_scale_f32_16x16x128_f8f6f4 v[42:45], v[2:9], v[222:229], 0, v1, v186 op_sel_hi:[0,0,0]
	v_mfma_scale_f32_16x16x128_f8f6f4 v[34:37], v[10:17], v[222:229], 0, v1, v186 op_sel_hi:[0,0,0]
	s_setprio 0
	s_barrier
; #define PG8_STAGE(bufoff, gbase, voff) do { _Pragma("unroll") for (int _i = 0; _i < 2; ++_i) \
;         __builtin_amdgcn_global_load_lds((const unsigned*)((const char*)(gbase) + (voff)[_i]), (PG8_LAS unsigned*)(lds + (bufoff) + ldsw + _i * 8192), 16, 0, 0); } while (0)
; #define PG8_LDA(dst, b, h) do { _Pragma("unroll") for (int m = 0; m < 4; ++m) _Pragma("unroll") for (int k = 0; k < 2; ++k) dst[m][k] = *(const PG8_LAS bf16x8*)(lds + PG8_SA(b, h) + aoff + m * 2048 + k * 1024); } while (0)
; #define PG8_LDB(dst, b, h) do { _Pragma("unroll") for (int n = 0; n < 2; ++n) _Pragma("unroll") for (int k = 0; k < 2; ++k) dst[n][k] = *(const PG8_LAS bf16x8*)(lds + PG8_SB(b, h) + boff + n * 2048 + k * 1024); } while (0)
; #define PG8_MMA(ai, bj, At, Bt) do { __builtin_amdgcn_s_setprio(1); _Pragma("unroll") for (int m = 0; m < 4; ++m) _Pragma("unroll") for (int n = 0; n < 2; ++n) _Pragma("unroll") for (int k = 0; k < 2; ++k) \
;         acc[ai][bj][m][n] = __builtin_amdgcn_mfma_f32_16x16x32_bf16(Bt[n][k], At[m][k], acc[ai][bj][m][n], 0, 0, 0); __builtin_amdgcn_s_setprio(0); } while (0)
; #define PG8_WAIT_V(n) asm volatile("s_waitcnt vmcnt(" #n ")" ::: "memory")
; #define PG8_WAIT_L(n) asm volatile("s_waitcnt lgkmcnt(" #n ")" ::: "memory")
; #define PG8_BAR __builtin_amdgcn_s_barrier()
; #define PG8_SCHED __builtin_amdgcn_sched_barrier(0)
; #define PG8_STAGE(bufoff, gbase, voff) do { _Pragma("unroll") for (int _i = 0; _i < 2; ++_i) \
;         __builtin_amdgcn_global_load_lds((const unsigned*)((const char*)(gbase) + (voff)[_i]), (PG8_LAS unsigned*)(lds + (bufoff) + ldsw + _i * 8192), 16, 0, 0); } while (0)
; #define PG8_WAIT_V(n) asm volatile("s_waitcnt vmcnt(" #n ")" ::: "memory")
; template <class Epi, class Sched, bool ALIGN_EPI = false>
; __device__ __forceinline__ void gemm_phase8(PG8_LAS unsigned char* lds, const Gemm g, const Sched& S, const Epi& E) {
;     ...
;             PG8_LDB(B0, 1, 0); PG8_LDB(B1, 1, 1); PG8_SCHED; PG8_LDA(At, 1, 0); PG8_STAGE(PG8_SA(0, 1), a2 + hstepA, voffA);
;             PG8_WAIT_V(8); PG8_WAIT_L(0); PG8_BAR; PG8_MMA(0, 0, At, B0); PG8_MMA(0, 1, At, B1); PG8_BAR; PG8_SCHED;
;             PG8_LDA(At, 1, 1); PG8_STAGE(PG8_SB(1, 0), b3, voffB); PG8_STAGE(PG8_SB(1, 1), b3 + hstepB, voffB); PG8_STAGE(PG8_SA(1, 0), a3, voffA);
;             PG8_WAIT_V(8); PG8_WAIT_L(0); PG8_BAR; PG8_MMA(1, 0, At, B0); PG8_MMA(1, 1, At, B1); PG8_BAR; PG8_SCHED;
	s_add_i32 s66, 0, 0x18000
	s_add_i32 s67, 0, 0x1c000
	v_add_u32_e32 v6, s66, v187
	v_add_u32_e32 v14, s66, v188
	v_add_u32_e32 v22, s67, v187
	v_add_u32_e32 v30, s67, v188
	ds_read_b128 v[2:5], v6
	ds_read_b128 v[10:13], v6 offset:2048
	ds_read_b128 v[6:9], v14
	ds_read_b128 v[14:17], v14 offset:2048
	ds_read_b128 v[18:21], v22
	ds_read_b128 v[26:29], v22 offset:2048
	ds_read_b128 v[22:25], v30
	ds_read_b128 v[30:33], v30 offset:2048
	s_add_u32 s26, s26, 0x40000
	s_addc_u32 s27, s27, 0
	s_mov_b32 m0, s35
	ds_read_b128 v[198:201], v195 offset:32768
	ds_read_b128 v[206:209], v195 offset:34816
	ds_read_b128 v[202:205], v196 offset:32768
	ds_read_b128 v[210:213], v196 offset:34816
	ds_read_b128 v[214:217], v195 offset:36864
	ds_read_b128 v[222:225], v195 offset:38912
	ds_read_b128 v[218:221], v196 offset:36864
	ds_read_b128 v[226:229], v196 offset:38912
	global_load_lds_dwordx4 v162, s[26:27]
	s_mov_b32 m0, s52
	s_nop 0
	global_load_lds_dwordx4 v166, s[26:27]
	s_waitcnt vmcnt(8)
	s_waitcnt lgkmcnt(0)
	s_barrier
	s_setprio 1
	s_waitcnt lgkmcnt(0)
	v_mfma_scale_f32_16x16x128_f8f6f4 v[158:161], v[2:9], v[198:205], v[158:161], v1, v186 op_sel_hi:[0,0,0]
	v_mfma_scale_f32_16x16x128_f8f6f4 v[150:153], v[10:17], v[198:205], v[150:153], v1, v186 op_sel_hi:[0,0,0]
	v_mfma_scale_f32_16x16x128_f8f6f4 v[142:145], v[2:9], v[206:213], v[142:145], v1, v186 op_sel_hi:[0,0,0]
	v_mfma_scale_f32_16x16x128_f8f6f4 v[134:137], v[10:17], v[206:213], v[134:137], v1, v186 op_sel_hi:[0,0,0]
	v_mfma_scale_f32_16x16x128_f8f6f4 v[126:129], v[2:9], v[214:221], v[126:129], v1, v186 op_sel_hi:[0,0,0]
	v_mfma_scale_f32_16x16x128_f8f6f4 v[118:121], v[10:17], v[214:221], v[118:121], v1, v186 op_sel_hi:[0,0,0]
	v_mfma_scale_f32_16x16x128_f8f6f4 v[110:113], v[2:9], v[222:229], v[110:113], v1, v186 op_sel_hi:[0,0,0]
	v_mfma_scale_f32_16x16x128_f8f6f4 v[102:105], v[10:17], v[222:229], v[102:105], v1, v186 op_sel_hi:[0,0,0]
	s_setprio 0
	s_setprio 1
	v_mfma_scale_f32_16x16x128_f8f6f4 v[154:157], v[18:25], v[198:205], v[154:157], v1, v186 op_sel_hi:[0,0,0]
	v_mfma_scale_f32_16x16x128_f8f6f4 v[146:149], v[26:33], v[198:205], v[146:149], v1, v186 op_sel_hi:[0,0,0]
	v_mfma_scale_f32_16x16x128_f8f6f4 v[138:141], v[18:25], v[206:213], v[138:141], v1, v186 op_sel_hi:[0,0,0]
	v_mfma_scale_f32_16x16x128_f8f6f4 v[130:133], v[26:33], v[206:213], v[130:133], v1, v186 op_sel_hi:[0,0,0]
	v_mfma_scale_f32_16x16x128_f8f6f4 v[122:125], v[18:25], v[214:221], v[122:125], v1, v186 op_sel_hi:[0,0,0]
	v_mfma_scale_f32_16x16x128_f8f6f4 v[114:117], v[26:33], v[214:221], v[114:117], v1, v186 op_sel_hi:[0,0,0]
	v_mfma_scale_f32_16x16x128_f8f6f4 v[106:109], v[18:25], v[222:229], v[106:109], v1, v186 op_sel_hi:[0,0,0]
	v_mfma_scale_f32_16x16x128_f8f6f4 v[98:101], v[26:33], v[222:229], v[98:101], v1, v186 op_sel_hi:[0,0,0]
	s_setprio 0
	s_barrier
	s_add_i32 s101, s66, s30
	s_add_u32 s98, s24, s8
	s_addc_u32 s99, s25, s9
	s_mov_b32 m0, s101
	ds_read_b128 v[198:201], v195 offset:49152
	ds_read_b128 v[206:209], v195 offset:51200
	ds_read_b128 v[202:205], v196 offset:49152
	ds_read_b128 v[210:213], v196 offset:51200
	ds_read_b128 v[214:217], v195 offset:53248
	ds_read_b128 v[222:225], v195 offset:55296
	ds_read_b128 v[218:221], v196 offset:53248
	ds_read_b128 v[226:229], v196 offset:55296
	global_load_lds_dwordx4 v164, s[98:99]
	s_add_i32 m0, s101, 0x2000
	s_add_u32 s24, s24, 0x40080
	s_addc_u32 s25, s25, 0
	s_add_i32 s101, s67, s30
	global_load_lds_dwordx4 v168, s[98:99]
	s_add_u32 s98, s26, s8
	s_addc_u32 s99, s27, s9
	s_sub_u32 s98, s98, 0x40000
	s_subb_u32 s99, s99, 0
	s_mov_b32 m0, s101
	s_nop 0
	global_load_lds_dwordx4 v164, s[24:25]
	s_add_i32 m0, s101, 0x2000
	s_nop 0
	global_load_lds_dwordx4 v168, s[24:25]
	s_mov_b32 m0, s55
	s_nop 0
	global_load_lds_dwordx4 v162, s[98:99]
	s_mov_b32 m0, s56
	s_nop 0
	global_load_lds_dwordx4 v166, s[98:99]
	s_waitcnt vmcnt(8)
	s_waitcnt lgkmcnt(0)
	s_barrier
	s_setprio 1
	s_waitcnt lgkmcnt(0)
	v_mfma_scale_f32_16x16x128_f8f6f4 v[94:97], v[2:9], v[198:205], v[94:97], v1, v186 op_sel_hi:[0,0,0]
	v_mfma_scale_f32_16x16x128_f8f6f4 v[86:89], v[10:17], v[198:205], v[86:89], v1, v186 op_sel_hi:[0,0,0]
	v_mfma_scale_f32_16x16x128_f8f6f4 v[78:81], v[2:9], v[206:213], v[78:81], v1, v186 op_sel_hi:[0,0,0]
	v_mfma_scale_f32_16x16x128_f8f6f4 v[70:73], v[10:17], v[206:213], v[70:73], v1, v186 op_sel_hi:[0,0,0]
	v_mfma_scale_f32_16x16x128_f8f6f4 v[62:65], v[2:9], v[214:221], v[62:65], v1, v186 op_sel_hi:[0,0,0]
	v_mfma_scale_f32_16x16x128_f8f6f4 v[54:57], v[10:17], v[214:221], v[54:57], v1, v186 op_sel_hi:[0,0,0]
	v_mfma_scale_f32_16x16x128_f8f6f4 v[46:49], v[2:9], v[222:229], v[46:49], v1, v186 op_sel_hi:[0,0,0]
	v_mfma_scale_f32_16x16x128_f8f6f4 v[38:41], v[10:17], v[222:229], v[38:41], v1, v186 op_sel_hi:[0,0,0]
	s_setprio 0
	s_setprio 1
	v_mfma_scale_f32_16x16x128_f8f6f4 v[90:93], v[18:25], v[198:205], v[90:93], v1, v186 op_sel_hi:[0,0,0]
	v_mfma_scale_f32_16x16x128_f8f6f4 v[82:85], v[26:33], v[198:205], v[82:85], v1, v186 op_sel_hi:[0,0,0]
	v_mfma_scale_f32_16x16x128_f8f6f4 v[74:77], v[18:25], v[206:213], v[74:77], v1, v186 op_sel_hi:[0,0,0]
	v_mfma_scale_f32_16x16x128_f8f6f4 v[66:69], v[26:33], v[206:213], v[66:69], v1, v186 op_sel_hi:[0,0,0]
	v_mfma_scale_f32_16x16x128_f8f6f4 v[58:61], v[18:25], v[214:221], v[58:61], v1, v186 op_sel_hi:[0,0,0]
	v_mfma_scale_f32_16x16x128_f8f6f4 v[50:53], v[26:33], v[214:221], v[50:53], v1, v186 op_sel_hi:[0,0,0]
	v_mfma_scale_f32_16x16x128_f8f6f4 v[42:45], v[18:25], v[222:229], v[42:45], v1, v186 op_sel_hi:[0,0,0]
	v_mfma_scale_f32_16x16x128_f8f6f4 v[34:37], v[26:33], v[222:229], v[34:37], v1, v186 op_sel_hi:[0,0,0]
	s_setprio 0
	s_barrier
	s_add_i32 s65, s65, 2
	s_add_u32 s22, s22, 0x100
	s_addc_u32 s23, s23, 0
	s_add_u32 s63, s63, 0x100
	s_addc_u32 s64, s64, 0
	s_cmp_gt_u32 s65, 13
; #define PG8_STAGE(bufoff, gbase, voff) do { _Pragma("unroll") for (int _i = 0; _i < 2; ++_i) \
;         __builtin_amdgcn_global_load_lds((const unsigned*)((const char*)(gbase) + (voff)[_i]), (PG8_LAS unsigned*)(lds + (bufoff) + ldsw + _i * 8192), 16, 0, 0); } while (0)
; #define PG8_LDA(dst, b, h) do { _Pragma("unroll") for (int m = 0; m < 4; ++m) _Pragma("unroll") for (int k = 0; k < 2; ++k) dst[m][k] = *(const PG8_LAS bf16x8*)(lds + PG8_SA(b, h) + aoff + m * 2048 + k * 1024); } while (0)
; #define PG8_LDB(dst, b, h) do { _Pragma("unroll") for (int n = 0; n < 2; ++n) _Pragma("unroll") for (int k = 0; k < 2; ++k) dst[n][k] = *(const PG8_LAS bf16x8*)(lds + PG8_SB(b, h) + boff + n * 2048 + k * 1024); } while (0)
; #define PG8_MMA(ai, bj, At, Bt) do { __builtin_amdgcn_s_setprio(1); _Pragma("unroll") for (int m = 0; m < 4; ++m) _Pragma("unroll") for (int n = 0; n < 2; ++n) _Pragma("unroll") for (int k = 0; k < 2; ++k) \
;         acc[ai][bj][m][n] = __builtin_amdgcn_mfma_f32_16x16x32_bf16(Bt[n][k], At[m][k], acc[ai][bj][m][n], 0, 0, 0); __builtin_amdgcn_s_setprio(0); } while (0)
; #define PG8_WAIT_V(n) asm volatile("s_waitcnt vmcnt(" #n ")" ::: "memory")
; #define PG8_WAIT_L(n) asm volatile("s_waitcnt lgkmcnt(" #n ")" ::: "memory")
; #define PG8_BAR __builtin_amdgcn_s_barrier()
; #define PG8_SCHED __builtin_amdgcn_sched_barrier(0)
; #define PG8_STAGE(bufoff, gbase, voff) do { _Pragma("unroll") for (int _i = 0; _i < 2; ++_i) \
;         __builtin_amdgcn_global_load_lds((const unsigned*)((const char*)(gbase) + (voff)[_i]), (PG8_LAS unsigned*)(lds + (bufoff) + ldsw + _i * 8192), 16, 0, 0); } while (0)
; #define PG8_WAIT_V(n) asm volatile("s_waitcnt vmcnt(" #n ")" ::: "memory")
; template <class Epi, class Sched, bool ALIGN_EPI = false>
; __device__ __forceinline__ void gemm_phase8(PG8_LAS unsigned char* lds, const Gemm g, const Sched& S, const Epi& E) {
;     ...
;             PG8_LDB(B0, 0, 0); PG8_LDB(B1, 0, 1); PG8_SCHED; PG8_LDA(At, 0, 0); PG8_STAGE(PG8_SA(1, 1), a1 + hstepA, voffA);
;             PG8_WAIT_V(8); PG8_WAIT_L(0); PG8_BAR; PG8_MMA(0, 0, At, B0); PG8_MMA(0, 1, At, B1); PG8_BAR; PG8_SCHED;
;             PG8_LDA(At, 0, 1); PG8_STAGE(PG8_SB(0, 0), b2, voffB); PG8_STAGE(PG8_SB(0, 1), b2 + hstepB, voffB); PG8_STAGE(PG8_SA(0, 0), a2, voffA);
;             PG8_WAIT_V(8); PG8_WAIT_L(0); PG8_BAR; PG8_MMA(1, 0, At, B0); PG8_MMA(1, 1, At, B1); PG8_BAR; PG8_SCHED;
.LBB0_325:
	ds_read_b128 v[18:21], v191
	ds_read_b128 v[26:29], v191 offset:2048
	ds_read_b128 v[22:25], v192
	ds_read_b128 v[30:33], v192 offset:2048
	ds_read_b128 v[2:5], v193
	ds_read_b128 v[10:13], v193 offset:2048
	ds_read_b128 v[6:9], v194
	ds_read_b128 v[14:17], v194 offset:2048
	s_add_u32 s24, s22, 0xfffc0080
	s_addc_u32 s25, s23, -1
	s_cmp_eq_u32 s65, 12
	s_cselect_b32 s27, s15, s25
	s_cselect_b32 s26, s61, s24
	s_cselect_b32 s25, s13, s64
	s_cselect_b32 s24, s62, s63
	s_add_i32 m0, s21, 0xc000
	ds_read_b128 v[178:181], v195
	ds_read_b128 v[198:201], v195 offset:2048
	ds_read_b128 v[182:185], v196
	ds_read_b128 v[202:205], v196 offset:2048
	ds_read_b128 v[206:209], v195 offset:4096
	ds_read_b128 v[214:217], v195 offset:6144
	ds_read_b128 v[210:213], v196 offset:4096
	ds_read_b128 v[218:221], v196 offset:6144
	global_load_lds_dwordx4 v170, s[22:23]
	s_add_i32 m0, s21, 0xe000
	s_nop 0
	global_load_lds_dwordx4 v172, s[22:23]
	s_waitcnt vmcnt(8)
	s_waitcnt lgkmcnt(0)
	s_barrier
	s_setprio 1
	s_waitcnt lgkmcnt(0)
	v_mfma_scale_f32_16x16x128_f8f6f4 v[158:161], v[18:25], v[178:185], v[158:161], v1, v186 op_sel_hi:[0,0,0]
	v_mfma_scale_f32_16x16x128_f8f6f4 v[150:153], v[26:33], v[178:185], v[150:153], v1, v186 op_sel_hi:[0,0,0]
	v_mfma_scale_f32_16x16x128_f8f6f4 v[142:145], v[18:25], v[198:205], v[142:145], v1, v186 op_sel_hi:[0,0,0]
	v_mfma_scale_f32_16x16x128_f8f6f4 v[134:137], v[26:33], v[198:205], v[134:137], v1, v186 op_sel_hi:[0,0,0]
	v_mfma_scale_f32_16x16x128_f8f6f4 v[126:129], v[18:25], v[206:213], v[126:129], v1, v186 op_sel_hi:[0,0,0]
	v_mfma_scale_f32_16x16x128_f8f6f4 v[118:121], v[26:33], v[206:213], v[118:121], v1, v186 op_sel_hi:[0,0,0]
	v_mfma_scale_f32_16x16x128_f8f6f4 v[110:113], v[18:25], v[214:221], v[110:113], v1, v186 op_sel_hi:[0,0,0]
	v_mfma_scale_f32_16x16x128_f8f6f4 v[102:105], v[26:33], v[214:221], v[102:105], v1, v186 op_sel_hi:[0,0,0]
	s_setprio 0
	s_setprio 1
	v_mfma_scale_f32_16x16x128_f8f6f4 v[154:157], v[2:9], v[178:185], v[154:157], v1, v186 op_sel_hi:[0,0,0]
	v_mfma_scale_f32_16x16x128_f8f6f4 v[146:149], v[10:17], v[178:185], v[146:149], v1, v186 op_sel_hi:[0,0,0]
	v_mfma_scale_f32_16x16x128_f8f6f4 v[138:141], v[2:9], v[198:205], v[138:141], v1, v186 op_sel_hi:[0,0,0]
	v_mfma_scale_f32_16x16x128_f8f6f4 v[130:133], v[10:17], v[198:205], v[130:133], v1, v186 op_sel_hi:[0,0,0]
	v_mfma_scale_f32_16x16x128_f8f6f4 v[122:125], v[2:9], v[206:213], v[122:125], v1, v186 op_sel_hi:[0,0,0]
	v_mfma_scale_f32_16x16x128_f8f6f4 v[114:117], v[10:17], v[206:213], v[114:117], v1, v186 op_sel_hi:[0,0,0]
	v_mfma_scale_f32_16x16x128_f8f6f4 v[106:109], v[2:9], v[214:221], v[106:109], v1, v186 op_sel_hi:[0,0,0]
	v_mfma_scale_f32_16x16x128_f8f6f4 v[98:101], v[10:17], v[214:221], v[98:101], v1, v186 op_sel_hi:[0,0,0]
	s_setprio 0
	s_barrier
	s_add_i32 s66, s57, s30
	s_mov_b32 m0, s66
	ds_read_b128 v[198:201], v195 offset:16384
	ds_read_b128 v[206:209], v195 offset:18432
	ds_read_b128 v[202:205], v196 offset:16384
	ds_read_b128 v[210:213], v196 offset:18432
	ds_read_b128 v[214:217], v195 offset:20480
	ds_read_b128 v[222:225], v195 offset:22528
	ds_read_b128 v[218:221], v196 offset:20480
	ds_read_b128 v[226:229], v196 offset:22528
	global_load_lds_dwordx4 v164, s[24:25]
	s_add_i32 m0, s66, 0x2000
	s_add_u32 s66, s24, 0x40000
	s_addc_u32 s67, s25, 0
	s_add_i32 s72, s58, s30
	global_load_lds_dwordx4 v168, s[24:25]
	s_mov_b32 m0, s72
	s_nop 0
	global_load_lds_dwordx4 v164, s[66:67]
	s_add_i32 m0, s72, 0x2000
	s_nop 0
	global_load_lds_dwordx4 v168, s[66:67]
	s_mov_b32 m0, s21
	s_nop 0
	global_load_lds_dwordx4 v162, s[26:27]
	s_mov_b32 m0, s34
	s_nop 0
	global_load_lds_dwordx4 v166, s[26:27]
	s_waitcnt vmcnt(8)
	s_waitcnt lgkmcnt(0)
	s_barrier
	s_setprio 1
	s_waitcnt lgkmcnt(0)
	v_mfma_scale_f32_16x16x128_f8f6f4 v[94:97], v[18:25], v[198:205], v[94:97], v1, v186 op_sel_hi:[0,0,0]
	v_mfma_scale_f32_16x16x128_f8f6f4 v[86:89], v[26:33], v[198:205], v[86:89], v1, v186 op_sel_hi:[0,0,0]
	v_mfma_scale_f32_16x16x128_f8f6f4 v[78:81], v[18:25], v[206:213], v[78:81], v1, v186 op_sel_hi:[0,0,0]
	v_mfma_scale_f32_16x16x128_f8f6f4 v[70:73], v[26:33], v[206:213], v[70:73], v1, v186 op_sel_hi:[0,0,0]
	v_mfma_scale_f32_16x16x128_f8f6f4 v[62:65], v[18:25], v[214:221], v[62:65], v1, v186 op_sel_hi:[0,0,0]
	v_mfma_scale_f32_16x16x128_f8f6f4 v[54:57], v[26:33], v[214:221], v[54:57], v1, v186 op_sel_hi:[0,0,0]
	v_mfma_scale_f32_16x16x128_f8f6f4 v[46:49], v[18:25], v[222:229], v[46:49], v1, v186 op_sel_hi:[0,0,0]
	v_mfma_scale_f32_16x16x128_f8f6f4 v[38:41], v[26:33], v[222:229], v[38:41], v1, v186 op_sel_hi:[0,0,0]
	s_setprio 0
	s_setprio 1
	v_mfma_scale_f32_16x16x128_f8f6f4 v[90:93], v[2:9], v[198:205], v[90:93], v1, v186 op_sel_hi:[0,0,0]
	v_mfma_scale_f32_16x16x128_f8f6f4 v[82:85], v[10:17], v[198:205], v[82:85], v1, v186 op_sel_hi:[0,0,0]
	v_mfma_scale_f32_16x16x128_f8f6f4 v[74:77], v[2:9], v[206:213], v[74:77], v1, v186 op_sel_hi:[0,0,0]
	v_mfma_scale_f32_16x16x128_f8f6f4 v[66:69], v[10:17], v[206:213], v[66:69], v1, v186 op_sel_hi:[0,0,0]
	v_mfma_scale_f32_16x16x128_f8f6f4 v[58:61], v[2:9], v[214:221], v[58:61], v1, v186 op_sel_hi:[0,0,0]
	v_mfma_scale_f32_16x16x128_f8f6f4 v[50:53], v[10:17], v[214:221], v[50:53], v1, v186 op_sel_hi:[0,0,0]
	v_mfma_scale_f32_16x16x128_f8f6f4 v[42:45], v[2:9], v[222:229], v[42:45], v1, v186 op_sel_hi:[0,0,0]
	v_mfma_scale_f32_16x16x128_f8f6f4 v[34:37], v[10:17], v[222:229], v[34:37], v1, v186 op_sel_hi:[0,0,0]
	s_setprio 0
	s_barrier
; #define PG8_STAGE(bufoff, gbase, voff) do { _Pragma("unroll") for (int _i = 0; _i < 2; ++_i) \
;         __builtin_amdgcn_global_load_lds((const unsigned*)((const char*)(gbase) + (voff)[_i]), (PG8_LAS unsigned*)(lds + (bufoff) + ldsw + _i * 8192), 16, 0, 0); } while (0)
; #define PG8_LDA(dst, b, h) do { _Pragma("unroll") for (int m = 0; m < 4; ++m) _Pragma("unroll") for (int k = 0; k < 2; ++k) dst[m][k] = *(const PG8_LAS bf16x8*)(lds + PG8_SA(b, h) + aoff + m * 2048 + k * 1024); } while (0)
; #define PG8_LDB(dst, b, h) do { _Pragma("unroll") for (int n = 0; n < 2; ++n) _Pragma("unroll") for (int k = 0; k < 2; ++k) dst[n][k] = *(const PG8_LAS bf16x8*)(lds + PG8_SB(b, h) + boff + n * 2048 + k * 1024); } while (0)
; #define PG8_MMA(ai, bj, At, Bt) do { __builtin_amdgcn_s_setprio(1); _Pragma("unroll") for (int m = 0; m < 4; ++m) _Pragma("unroll") for (int n = 0; n < 2; ++n) _Pragma("unroll") for (int k = 0; k < 2; ++k) \
;         acc[ai][bj][m][n] = __builtin_amdgcn_mfma_f32_16x16x32_bf16(Bt[n][k], At[m][k], acc[ai][bj][m][n], 0, 0, 0); __builtin_amdgcn_s_setprio(0); } while (0)
; #define PG8_WAIT_V(n) asm volatile("s_waitcnt vmcnt(" #n ")" ::: "memory")
; #define PG8_WAIT_L(n) asm volatile("s_waitcnt lgkmcnt(" #n ")" ::: "memory")
; #define PG8_BAR __builtin_amdgcn_s_barrier()
; #define PG8_SCHED __builtin_amdgcn_sched_barrier(0)
; #define PG8_STAGE(bufoff, gbase, voff) do { _Pragma("unroll") for (int _i = 0; _i < 2; ++_i) \
;         __builtin_amdgcn_global_load_lds((const unsigned*)((const char*)(gbase) + (voff)[_i]), (PG8_LAS unsigned*)(lds + (bufoff) + ldsw + _i * 8192), 16, 0, 0); } while (0)
; #define PG8_BAR __builtin_amdgcn_s_barrier()
; template <class Epi, class Sched, bool ALIGN_EPI = false>
; __device__ __forceinline__ void gemm_phase8(PG8_LAS unsigned char* lds, const Gemm g, const Sched& S, const Epi& E) {
;     ...
;             PG8_LDB(B0, 1, 0); PG8_LDB(B1, 1, 1); PG8_SCHED; PG8_LDA(At, 1, 0); PG8_STAGE(PG8_SA(0, 1), a2 + hstepA, voffA);
;             PG8_WAIT_V(8); PG8_WAIT_L(0); PG8_BAR; PG8_MMA(0, 0, At, B0); PG8_MMA(0, 1, At, B1); PG8_BAR; PG8_SCHED;
;             PG8_LDA(At, 1, 1); PG8_STAGE(PG8_SB(1, 0), b3, voffB); PG8_STAGE(PG8_SB(1, 1), b3 + hstepB, voffB); PG8_STAGE(PG8_SA(1, 0), a3, voffA);
;             PG8_WAIT_V(8); PG8_WAIT_L(0); PG8_BAR; PG8_MMA(1, 0, At, B0); PG8_MMA(1, 1, At, B1); PG8_BAR; PG8_SCHED;
;         }
	s_add_i32 s66, 0, 0x18000
	s_add_i32 s67, 0, 0x1c000
	v_add_u32_e32 v6, s66, v187
	v_add_u32_e32 v14, s66, v188
	v_add_u32_e32 v22, s67, v187
	v_add_u32_e32 v30, s67, v188
	ds_read_b128 v[2:5], v6
	ds_read_b128 v[10:13], v6 offset:2048
	ds_read_b128 v[6:9], v14
	ds_read_b128 v[14:17], v14 offset:2048
	ds_read_b128 v[18:21], v22
	ds_read_b128 v[26:29], v22 offset:2048
	ds_read_b128 v[22:25], v30
	ds_read_b128 v[30:33], v30 offset:2048
	s_add_u32 s26, s26, 0x40000
	s_addc_u32 s27, s27, 0
	s_mov_b32 m0, s35
	ds_read_b128 v[198:201], v195 offset:32768
	ds_read_b128 v[206:209], v195 offset:34816
	ds_read_b128 v[202:205], v196 offset:32768
	ds_read_b128 v[210:213], v196 offset:34816
	ds_read_b128 v[214:217], v195 offset:36864
	ds_read_b128 v[222:225], v195 offset:38912
	ds_read_b128 v[218:221], v196 offset:36864
	ds_read_b128 v[226:229], v196 offset:38912
	global_load_lds_dwordx4 v162, s[26:27]
	s_mov_b32 m0, s52
	s_nop 0
	global_load_lds_dwordx4 v166, s[26:27]
	s_waitcnt vmcnt(8)
	s_waitcnt lgkmcnt(0)
	s_barrier
	s_setprio 1
	s_waitcnt lgkmcnt(0)
	v_mfma_scale_f32_16x16x128_f8f6f4 v[158:161], v[2:9], v[198:205], v[158:161], v1, v186 op_sel_hi:[0,0,0]
	v_mfma_scale_f32_16x16x128_f8f6f4 v[150:153], v[10:17], v[198:205], v[150:153], v1, v186 op_sel_hi:[0,0,0]
	v_mfma_scale_f32_16x16x128_f8f6f4 v[142:145], v[2:9], v[206:213], v[142:145], v1, v186 op_sel_hi:[0,0,0]
	v_mfma_scale_f32_16x16x128_f8f6f4 v[134:137], v[10:17], v[206:213], v[134:137], v1, v186 op_sel_hi:[0,0,0]
	v_mfma_scale_f32_16x16x128_f8f6f4 v[126:129], v[2:9], v[214:221], v[126:129], v1, v186 op_sel_hi:[0,0,0]
	v_mfma_scale_f32_16x16x128_f8f6f4 v[118:121], v[10:17], v[214:221], v[118:121], v1, v186 op_sel_hi:[0,0,0]
	v_mfma_scale_f32_16x16x128_f8f6f4 v[110:113], v[2:9], v[222:229], v[110:113], v1, v186 op_sel_hi:[0,0,0]
	v_mfma_scale_f32_16x16x128_f8f6f4 v[102:105], v[10:17], v[222:229], v[102:105], v1, v186 op_sel_hi:[0,0,0]
	s_setprio 0
	s_setprio 1
	v_mfma_scale_f32_16x16x128_f8f6f4 v[154:157], v[18:25], v[198:205], v[154:157], v1, v186 op_sel_hi:[0,0,0]
	v_mfma_scale_f32_16x16x128_f8f6f4 v[146:149], v[26:33], v[198:205], v[146:149], v1, v186 op_sel_hi:[0,0,0]
	v_mfma_scale_f32_16x16x128_f8f6f4 v[138:141], v[18:25], v[206:213], v[138:141], v1, v186 op_sel_hi:[0,0,0]
	v_mfma_scale_f32_16x16x128_f8f6f4 v[130:133], v[26:33], v[206:213], v[130:133], v1, v186 op_sel_hi:[0,0,0]
	v_mfma_scale_f32_16x16x128_f8f6f4 v[122:125], v[18:25], v[214:221], v[122:125], v1, v186 op_sel_hi:[0,0,0]
	v_mfma_scale_f32_16x16x128_f8f6f4 v[114:117], v[26:33], v[214:221], v[114:117], v1, v186 op_sel_hi:[0,0,0]
	v_mfma_scale_f32_16x16x128_f8f6f4 v[106:109], v[18:25], v[222:229], v[106:109], v1, v186 op_sel_hi:[0,0,0]
	v_mfma_scale_f32_16x16x128_f8f6f4 v[98:101], v[26:33], v[222:229], v[98:101], v1, v186 op_sel_hi:[0,0,0]
	s_setprio 0
	s_barrier
	s_add_i32 s101, s66, s30
	s_add_u32 s98, s24, s8
	s_addc_u32 s99, s25, s9
	s_mov_b32 m0, s101
	ds_read_b128 v[198:201], v195 offset:49152
	ds_read_b128 v[206:209], v195 offset:51200
	ds_read_b128 v[202:205], v196 offset:49152
	ds_read_b128 v[210:213], v196 offset:51200
	ds_read_b128 v[214:217], v195 offset:53248
	ds_read_b128 v[222:225], v195 offset:55296
	ds_read_b128 v[218:221], v196 offset:53248
	ds_read_b128 v[226:229], v196 offset:55296
	global_load_lds_dwordx4 v164, s[98:99]
	s_add_i32 m0, s101, 0x2000
	s_add_u32 s24, s24, 0x40080
	s_addc_u32 s25, s25, 0
	s_add_i32 s101, s67, s30
	global_load_lds_dwordx4 v168, s[98:99]
	s_add_u32 s98, s26, s8
	s_addc_u32 s99, s27, s9
	s_sub_u32 s98, s98, 0x40000
	s_subb_u32 s99, s99, 0
	s_mov_b32 m0, s101
	s_nop 0
	global_load_lds_dwordx4 v164, s[24:25]
	s_add_i32 m0, s101, 0x2000
	s_nop 0
	global_load_lds_dwordx4 v168, s[24:25]
	s_mov_b32 m0, s55
	s_nop 0
	global_load_lds_dwordx4 v162, s[98:99]
	s_mov_b32 m0, s56
	s_nop 0
	global_load_lds_dwordx4 v166, s[98:99]
	s_waitcnt vmcnt(8)
	s_waitcnt lgkmcnt(0)
	s_barrier
	s_setprio 1
	s_waitcnt lgkmcnt(0)
	v_mfma_scale_f32_16x16x128_f8f6f4 v[94:97], v[2:9], v[198:205], v[94:97], v1, v186 op_sel_hi:[0,0,0]
	v_mfma_scale_f32_16x16x128_f8f6f4 v[86:89], v[10:17], v[198:205], v[86:89], v1, v186 op_sel_hi:[0,0,0]
	v_mfma_scale_f32_16x16x128_f8f6f4 v[78:81], v[2:9], v[206:213], v[78:81], v1, v186 op_sel_hi:[0,0,0]
	v_mfma_scale_f32_16x16x128_f8f6f4 v[70:73], v[10:17], v[206:213], v[70:73], v1, v186 op_sel_hi:[0,0,0]
	v_mfma_scale_f32_16x16x128_f8f6f4 v[62:65], v[2:9], v[214:221], v[62:65], v1, v186 op_sel_hi:[0,0,0]
	v_mfma_scale_f32_16x16x128_f8f6f4 v[54:57], v[10:17], v[214:221], v[54:57], v1, v186 op_sel_hi:[0,0,0]
	v_mfma_scale_f32_16x16x128_f8f6f4 v[46:49], v[2:9], v[222:229], v[46:49], v1, v186 op_sel_hi:[0,0,0]
	v_mfma_scale_f32_16x16x128_f8f6f4 v[38:41], v[10:17], v[222:229], v[38:41], v1, v186 op_sel_hi:[0,0,0]
	s_setprio 0
	s_setprio 1
	v_mfma_scale_f32_16x16x128_f8f6f4 v[90:93], v[18:25], v[198:205], v[90:93], v1, v186 op_sel_hi:[0,0,0]
	v_mfma_scale_f32_16x16x128_f8f6f4 v[82:85], v[26:33], v[198:205], v[82:85], v1, v186 op_sel_hi:[0,0,0]
	v_mfma_scale_f32_16x16x128_f8f6f4 v[74:77], v[18:25], v[206:213], v[74:77], v1, v186 op_sel_hi:[0,0,0]
	v_mfma_scale_f32_16x16x128_f8f6f4 v[66:69], v[26:33], v[206:213], v[66:69], v1, v186 op_sel_hi:[0,0,0]
	v_mfma_scale_f32_16x16x128_f8f6f4 v[58:61], v[18:25], v[214:221], v[58:61], v1, v186 op_sel_hi:[0,0,0]
	v_mfma_scale_f32_16x16x128_f8f6f4 v[50:53], v[26:33], v[214:221], v[50:53], v1, v186 op_sel_hi:[0,0,0]
	v_mfma_scale_f32_16x16x128_f8f6f4 v[42:45], v[18:25], v[222:229], v[42:45], v1, v186 op_sel_hi:[0,0,0]
	v_mfma_scale_f32_16x16x128_f8f6f4 v[34:37], v[26:33], v[222:229], v[34:37], v1, v186 op_sel_hi:[0,0,0]
	s_setprio 0
	s_barrier
	s_add_i32 s65, s65, 2
	s_add_u32 s22, s22, 0x100
	s_addc_u32 s23, s23, 0
	s_add_u32 s63, s63, 0x100
	s_addc_u32 s64, s64, 0
	s_cmp_gt_u32 s65, 13
	s_cbranch_scc0 .LBB0_325
	s_and_b64 vcc, exec, s[10:11]
	s_cbranch_vccz .LBB0_328
	s_barrier

; #define PG8_STAGE(bufoff, gbase, voff) do { _Pragma("unroll") for (int _i = 0; _i < 2; ++_i) \
;         __builtin_amdgcn_global_load_lds((const unsigned*)((const char*)(gbase) + (voff)[_i]), (PG8_LAS unsigned*)(lds + (bufoff) + ldsw + _i * 8192), 16, 0, 0); } while (0)
; #define PG8_LDA(dst, b, h) do { _Pragma("unroll") for (int m = 0; m < 4; ++m) _Pragma("unroll") for (int k = 0; k < 2; ++k) dst[m][k] = *(const PG8_LAS bf16x8*)(lds + PG8_SA(b, h) + aoff + m * 2048 + k * 1024); } while (0)
; #define PG8_LDB(dst, b, h) do { _Pragma("unroll") for (int n = 0; n < 2; ++n) _Pragma("unroll") for (int k = 0; k < 2; ++k) dst[n][k] = *(const PG8_LAS bf16x8*)(lds + PG8_SB(b, h) + boff + n * 2048 + k * 1024); } while (0)
; #define PG8_WAIT_V(n) asm volatile("s_waitcnt vmcnt(" #n ")" ::: "memory")
; #define PG8_WAIT_L(n) asm volatile("s_waitcnt lgkmcnt(" #n ")" ::: "memory")
; template <class Epi, class Sched, bool ALIGN_EPI = false>
; __device__ __forceinline__ void gemm_phase8(PG8_LAS unsigned char* lds, const Gemm g, const Sched& S, const Epi& E) {
;     ...
;         const bool has_next = S.next(ui + 1, nxt);
;         const size_t nko = (has_next && nxt.kp > 0) ? (size_t)nxt.kp * g.kpiece : 0;
;         const char* nA = has_next ? (const char*)g.A + (size_t)nxt.pm * tstepA + (size_t)nxt.pn * astep + nko : cA; const char* nB = has_next ? (const char*)g.Bt + (size_t)nxt.pn * tstepB + nko : cB;
;         const int nt = (cur.kp < 0 ? g.K : g.kpiece) / 128;
;         for (int t = 0; t < nt; t += 2) {
;             const bool last = (t == nt - 2);
;             const char* a1 = cA + (size_t)(t + 1) * kstep;
;             const char* a2 = last ? nA : cA + (size_t)(t + 2) * kstep; const char* b2 = last ? nB : cB + (size_t)(t + 2) * kstep;
;             const char* a3 = a2 + kstep; const char* b3 = b2 + kstep;
;             if (last && has_next) S.a_ready(nxt);
;             PG8_LDB(B0, 0, 0); PG8_LDB(B1, 0, 1); PG8_SCHED; PG8_LDA(At, 0, 0); PG8_STAGE(PG8_SA(1, 1), a1 + hstepA, voffA);
;             PG8_WAIT_V(8); PG8_WAIT_L(0); PG8_BAR; PG8_MMA(0, 0, At, B0); PG8_MMA(0, 1, At, B1); PG8_BAR; PG8_SCHED;
;             PG8_LDA(At, 0, 1); PG8_STAGE(PG8_SB(0, 0), b2, voffB); PG8_STAGE(PG8_SB(0, 1), b2 + hstepB, voffB); PG8_STAGE(PG8_SA(0, 0), a2, voffA);
;             PG8_WAIT_V(8); PG8_WAIT_L(0); PG8_BAR; PG8_MMA(1, 0, At, B0); PG8_MMA(1, 1, At, B1); PG8_BAR; PG8_SCHED;
.LBB0_501:
	s_cmp_gt_i32 s24, -1
	s_cselect_b64 s[26:27], -1, 0
	s_cmp_lt_i32 s24, 0
	s_cselect_b32 s25, 44, 4
	s_add_i32 s81, s25, -2
	s_add_u32 s28, s28, 0xb0080
	s_addc_u32 s29, s29, 0
	s_add_u32 s82, s30, 0x100
	s_mov_b32 s34, 0
	s_addc_u32 s83, s31, 0
	ds_read_b128 v[18:21], v187
	ds_read_b128 v[26:29], v187 offset:2048
	ds_read_b128 v[22:25], v188
	ds_read_b128 v[30:33], v188 offset:2048
	ds_read_b128 v[2:5], v189
	ds_read_b128 v[10:13], v189 offset:2048
	ds_read_b128 v[6:9], v190
	ds_read_b128 v[14:17], v190 offset:2048
	s_add_i32 s84, s34, 2
	s_add_u32 s30, s28, 0xfff50080
	s_addc_u32 s31, s29, -1
	s_cmp_eq_u32 s81, s34
	s_cselect_b32 s34, s20, s30
	s_cselect_b32 s35, s21, s31
	s_cselect_b32 s31, s23, s83
	s_cselect_b32 s30, s22, s82
	s_add_i32 m0, s54, 0xc000
	ds_read_b128 v[174:177], v191
	ds_read_b128 v[194:197], v191 offset:2048
	ds_read_b128 v[178:181], v192
	ds_read_b128 v[198:201], v192 offset:2048
	ds_read_b128 v[202:205], v191 offset:4096
	ds_read_b128 v[210:213], v191 offset:6144
	ds_read_b128 v[206:209], v192 offset:4096
	ds_read_b128 v[214:217], v192 offset:6144
	global_load_lds_dwordx4 v170, s[28:29]
	s_add_i32 m0, s54, 0xe000
	s_nop 0
	global_load_lds_dwordx4 v172, s[28:29]
	s_waitcnt vmcnt(8)
	s_waitcnt lgkmcnt(0)
	s_barrier
	s_setprio 1
	s_waitcnt lgkmcnt(0)
	v_mfma_scale_f32_16x16x128_f8f6f4 v[158:161], v[18:25], v[174:181], 0, v1, v182 op_sel_hi:[0,0,0]
	v_mfma_scale_f32_16x16x128_f8f6f4 v[154:157], v[26:33], v[174:181], 0, v1, v182 op_sel_hi:[0,0,0]
	v_mfma_scale_f32_16x16x128_f8f6f4 v[142:145], v[18:25], v[194:201], 0, v1, v182 op_sel_hi:[0,0,0]
	v_mfma_scale_f32_16x16x128_f8f6f4 v[138:141], v[26:33], v[194:201], 0, v1, v182 op_sel_hi:[0,0,0]
	v_mfma_scale_f32_16x16x128_f8f6f4 v[126:129], v[18:25], v[202:209], 0, v1, v182 op_sel_hi:[0,0,0]
	v_mfma_scale_f32_16x16x128_f8f6f4 v[122:125], v[26:33], v[202:209], 0, v1, v182 op_sel_hi:[0,0,0]
	v_mfma_scale_f32_16x16x128_f8f6f4 v[110:113], v[18:25], v[210:217], 0, v1, v182 op_sel_hi:[0,0,0]
	v_mfma_scale_f32_16x16x128_f8f6f4 v[106:109], v[26:33], v[210:217], 0, v1, v182 op_sel_hi:[0,0,0]
	s_setprio 0
	s_setprio 1
	v_mfma_scale_f32_16x16x128_f8f6f4 v[150:153], v[2:9], v[174:181], 0, v1, v182 op_sel_hi:[0,0,0]
	v_mfma_scale_f32_16x16x128_f8f6f4 v[146:149], v[10:17], v[174:181], 0, v1, v182 op_sel_hi:[0,0,0]
	v_mfma_scale_f32_16x16x128_f8f6f4 v[134:137], v[2:9], v[194:201], 0, v1, v182 op_sel_hi:[0,0,0]
	v_mfma_scale_f32_16x16x128_f8f6f4 v[130:133], v[10:17], v[194:201], 0, v1, v182 op_sel_hi:[0,0,0]
	v_mfma_scale_f32_16x16x128_f8f6f4 v[118:121], v[2:9], v[202:209], 0, v1, v182 op_sel_hi:[0,0,0]
	v_mfma_scale_f32_16x16x128_f8f6f4 v[114:117], v[10:17], v[202:209], 0, v1, v182 op_sel_hi:[0,0,0]
	v_mfma_scale_f32_16x16x128_f8f6f4 v[102:105], v[2:9], v[210:217], 0, v1, v182 op_sel_hi:[0,0,0]
	v_mfma_scale_f32_16x16x128_f8f6f4 v[98:101], v[10:17], v[210:217], 0, v1, v182 op_sel_hi:[0,0,0]
	s_setprio 0
	s_barrier
	s_add_i32 s85, s65, s53
	s_mov_b32 m0, s85
	ds_read_b128 v[194:197], v191 offset:16384
	ds_read_b128 v[202:205], v191 offset:18432
	ds_read_b128 v[198:201], v192 offset:16384
	ds_read_b128 v[206:209], v192 offset:18432
	ds_read_b128 v[210:213], v191 offset:20480
	ds_read_b128 v[218:221], v191 offset:22528
	ds_read_b128 v[214:217], v192 offset:20480
	ds_read_b128 v[222:225], v192 offset:22528
	global_load_lds_dwordx4 v164, s[30:31]
	s_add_i32 m0, s85, 0x2000
	s_add_u32 s88, s30, 0xb0000
	s_addc_u32 s89, s31, 0
	s_add_i32 s85, s66, s53
	global_load_lds_dwordx4 v168, s[30:31]
	s_mov_b32 m0, s85
	s_nop 0
	global_load_lds_dwordx4 v164, s[88:89]
	s_add_i32 m0, s85, 0x2000
	s_nop 0
	global_load_lds_dwordx4 v168, s[88:89]
	s_mov_b32 m0, s54
	s_nop 0
	global_load_lds_dwordx4 v162, s[34:35]
	s_mov_b32 m0, s55
	s_nop 0
	global_load_lds_dwordx4 v166, s[34:35]
	s_waitcnt vmcnt(8)
	s_waitcnt lgkmcnt(0)
	s_barrier
	s_setprio 1
	s_waitcnt lgkmcnt(0)
	v_mfma_scale_f32_16x16x128_f8f6f4 v[94:97], v[18:25], v[194:201], 0, v1, v182 op_sel_hi:[0,0,0]
	v_mfma_scale_f32_16x16x128_f8f6f4 v[90:93], v[26:33], v[194:201], 0, v1, v182 op_sel_hi:[0,0,0]
	v_mfma_scale_f32_16x16x128_f8f6f4 v[78:81], v[18:25], v[202:209], 0, v1, v182 op_sel_hi:[0,0,0]
	v_mfma_scale_f32_16x16x128_f8f6f4 v[74:77], v[26:33], v[202:209], 0, v1, v182 op_sel_hi:[0,0,0]
	v_mfma_scale_f32_16x16x128_f8f6f4 v[62:65], v[18:25], v[210:217], 0, v1, v182 op_sel_hi:[0,0,0]
	v_mfma_scale_f32_16x16x128_f8f6f4 v[58:61], v[26:33], v[210:217], 0, v1, v182 op_sel_hi:[0,0,0]
	v_mfma_scale_f32_16x16x128_f8f6f4 v[46:49], v[18:25], v[218:225], 0, v1, v182 op_sel_hi:[0,0,0]
	v_mfma_scale_f32_16x16x128_f8f6f4 v[42:45], v[26:33], v[218:225], 0, v1, v182 op_sel_hi:[0,0,0]
	s_setprio 0
	s_setprio 1
	v_mfma_scale_f32_16x16x128_f8f6f4 v[86:89], v[2:9], v[194:201], 0, v1, v182 op_sel_hi:[0,0,0]
	v_mfma_scale_f32_16x16x128_f8f6f4 v[82:85], v[10:17], v[194:201], 0, v1, v182 op_sel_hi:[0,0,0]
	v_mfma_scale_f32_16x16x128_f8f6f4 v[70:73], v[2:9], v[202:209], 0, v1, v182 op_sel_hi:[0,0,0]
	v_mfma_scale_f32_16x16x128_f8f6f4 v[66:69], v[10:17], v[202:209], 0, v1, v182 op_sel_hi:[0,0,0]
	v_mfma_scale_f32_16x16x128_f8f6f4 v[54:57], v[2:9], v[210:217], 0, v1, v182 op_sel_hi:[0,0,0]
	v_mfma_scale_f32_16x16x128_f8f6f4 v[50:53], v[10:17], v[210:217], 0, v1, v182 op_sel_hi:[0,0,0]
	v_mfma_scale_f32_16x16x128_f8f6f4 v[38:41], v[2:9], v[218:225], 0, v1, v182 op_sel_hi:[0,0,0]
	v_mfma_scale_f32_16x16x128_f8f6f4 v[34:37], v[10:17], v[218:225], 0, v1, v182 op_sel_hi:[0,0,0]
	s_setprio 0
	s_barrier
; #define PG8_STAGE(bufoff, gbase, voff) do { _Pragma("unroll") for (int _i = 0; _i < 2; ++_i) \
;         __builtin_amdgcn_global_load_lds((const unsigned*)((const char*)(gbase) + (voff)[_i]), (PG8_LAS unsigned*)(lds + (bufoff) + ldsw + _i * 8192), 16, 0, 0); } while (0)
; #define PG8_LDA(dst, b, h) do { _Pragma("unroll") for (int m = 0; m < 4; ++m) _Pragma("unroll") for (int k = 0; k < 2; ++k) dst[m][k] = *(const PG8_LAS bf16x8*)(lds + PG8_SA(b, h) + aoff + m * 2048 + k * 1024); } while (0)
; #define PG8_LDB(dst, b, h) do { _Pragma("unroll") for (int n = 0; n < 2; ++n) _Pragma("unroll") for (int k = 0; k < 2; ++k) dst[n][k] = *(const PG8_LAS bf16x8*)(lds + PG8_SB(b, h) + boff + n * 2048 + k * 1024); } while (0)
; #define PG8_MMA(ai, bj, At, Bt) do { __builtin_amdgcn_s_setprio(1); _Pragma("unroll") for (int m = 0; m < 4; ++m) _Pragma("unroll") for (int n = 0; n < 2; ++n) _Pragma("unroll") for (int k = 0; k < 2; ++k) \
;         acc[ai][bj][m][n] = __builtin_amdgcn_mfma_f32_16x16x32_bf16(Bt[n][k], At[m][k], acc[ai][bj][m][n], 0, 0, 0); __builtin_amdgcn_s_setprio(0); } while (0)
; #define PG8_WAIT_V(n) asm volatile("s_waitcnt vmcnt(" #n ")" ::: "memory")
; #define PG8_WAIT_L(n) asm volatile("s_waitcnt lgkmcnt(" #n ")" ::: "memory")
; #define PG8_BAR __builtin_amdgcn_s_barrier()
; #define PG8_SCHED __builtin_amdgcn_sched_barrier(0)
; #define PG8_STAGE(bufoff, gbase, voff) do { _Pragma("unroll") for (int _i = 0; _i < 2; ++_i) \
;         __builtin_amdgcn_global_load_lds((const unsigned*)((const char*)(gbase) + (voff)[_i]), (PG8_LAS unsigned*)(lds + (bufoff) + ldsw + _i * 8192), 16, 0, 0); } while (0)
; #define PG8_WAIT_V(n) asm volatile("s_waitcnt vmcnt(" #n ")" ::: "memory")
; template <class Epi, class Sched, bool ALIGN_EPI = false>
; __device__ __forceinline__ void gemm_phase8(PG8_LAS unsigned char* lds, const Gemm g, const Sched& S, const Epi& E) {
;     ...
;             PG8_LDB(B0, 1, 0); PG8_LDB(B1, 1, 1); PG8_SCHED; PG8_LDA(At, 1, 0); PG8_STAGE(PG8_SA(0, 1), a2 + hstepA, voffA);
;             PG8_WAIT_V(8); PG8_WAIT_L(0); PG8_BAR; PG8_MMA(0, 0, At, B0); PG8_MMA(0, 1, At, B1); PG8_BAR; PG8_SCHED;
;             PG8_LDA(At, 1, 1); PG8_STAGE(PG8_SB(1, 0), b3, voffB); PG8_STAGE(PG8_SB(1, 1), b3 + hstepB, voffB); PG8_STAGE(PG8_SA(1, 0), a3, voffA);
;             PG8_WAIT_V(8); PG8_WAIT_L(0); PG8_BAR; PG8_MMA(1, 0, At, B0); PG8_MMA(1, 1, At, B1); PG8_BAR; PG8_SCHED;
	s_add_i32 s85, 0, 0x18000
	s_add_i32 s88, 0, 0x1c000
	v_add_u32_e32 v6, s85, v184
	v_add_u32_e32 v14, s85, v185
	v_add_u32_e32 v22, s88, v184
	v_add_u32_e32 v30, s88, v185
	ds_read_b128 v[2:5], v6
	ds_read_b128 v[10:13], v6 offset:2048
	ds_read_b128 v[6:9], v14
	ds_read_b128 v[14:17], v14 offset:2048
	ds_read_b128 v[18:21], v22
	ds_read_b128 v[26:29], v22 offset:2048
	ds_read_b128 v[22:25], v30
	ds_read_b128 v[30:33], v30 offset:2048
	s_add_u32 s34, s34, 0xb0000
	s_addc_u32 s35, s35, 0
	s_mov_b32 m0, s56
	ds_read_b128 v[194:197], v191 offset:32768
	ds_read_b128 v[202:205], v191 offset:34816
	ds_read_b128 v[198:201], v192 offset:32768
	ds_read_b128 v[206:209], v192 offset:34816
	ds_read_b128 v[210:213], v191 offset:36864
	ds_read_b128 v[218:221], v191 offset:38912
	ds_read_b128 v[214:217], v192 offset:36864
	ds_read_b128 v[222:225], v192 offset:38912
	global_load_lds_dwordx4 v162, s[34:35]
	s_mov_b32 m0, s57
	s_nop 0
	global_load_lds_dwordx4 v166, s[34:35]
	s_waitcnt vmcnt(8)
	s_waitcnt lgkmcnt(0)
	s_barrier
	s_setprio 1
	s_waitcnt lgkmcnt(0)
	v_mfma_scale_f32_16x16x128_f8f6f4 v[158:161], v[2:9], v[194:201], v[158:161], v1, v182 op_sel_hi:[0,0,0]
	v_mfma_scale_f32_16x16x128_f8f6f4 v[154:157], v[10:17], v[194:201], v[154:157], v1, v182 op_sel_hi:[0,0,0]
	v_mfma_scale_f32_16x16x128_f8f6f4 v[142:145], v[2:9], v[202:209], v[142:145], v1, v182 op_sel_hi:[0,0,0]
	v_mfma_scale_f32_16x16x128_f8f6f4 v[138:141], v[10:17], v[202:209], v[138:141], v1, v182 op_sel_hi:[0,0,0]
	v_mfma_scale_f32_16x16x128_f8f6f4 v[126:129], v[2:9], v[210:217], v[126:129], v1, v182 op_sel_hi:[0,0,0]
	v_mfma_scale_f32_16x16x128_f8f6f4 v[122:125], v[10:17], v[210:217], v[122:125], v1, v182 op_sel_hi:[0,0,0]
	v_mfma_scale_f32_16x16x128_f8f6f4 v[110:113], v[2:9], v[218:225], v[110:113], v1, v182 op_sel_hi:[0,0,0]
	v_mfma_scale_f32_16x16x128_f8f6f4 v[106:109], v[10:17], v[218:225], v[106:109], v1, v182 op_sel_hi:[0,0,0]
	s_setprio 0
	s_setprio 1
	v_mfma_scale_f32_16x16x128_f8f6f4 v[150:153], v[18:25], v[194:201], v[150:153], v1, v182 op_sel_hi:[0,0,0]
	v_mfma_scale_f32_16x16x128_f8f6f4 v[146:149], v[26:33], v[194:201], v[146:149], v1, v182 op_sel_hi:[0,0,0]
	v_mfma_scale_f32_16x16x128_f8f6f4 v[134:137], v[18:25], v[202:209], v[134:137], v1, v182 op_sel_hi:[0,0,0]
	v_mfma_scale_f32_16x16x128_f8f6f4 v[130:133], v[26:33], v[202:209], v[130:133], v1, v182 op_sel_hi:[0,0,0]
	v_mfma_scale_f32_16x16x128_f8f6f4 v[118:121], v[18:25], v[210:217], v[118:121], v1, v182 op_sel_hi:[0,0,0]
	v_mfma_scale_f32_16x16x128_f8f6f4 v[114:117], v[26:33], v[210:217], v[114:117], v1, v182 op_sel_hi:[0,0,0]
	v_mfma_scale_f32_16x16x128_f8f6f4 v[102:105], v[18:25], v[218:225], v[102:105], v1, v182 op_sel_hi:[0,0,0]
	v_mfma_scale_f32_16x16x128_f8f6f4 v[98:101], v[26:33], v[218:225], v[98:101], v1, v182 op_sel_hi:[0,0,0]
	s_setprio 0
	s_barrier
	s_add_i32 s101, s85, s53
	s_add_u32 s98, s30, s12
	s_addc_u32 s99, s31, s13
	s_mov_b32 m0, s101
	ds_read_b128 v[194:197], v191 offset:49152
	ds_read_b128 v[202:205], v191 offset:51200
	ds_read_b128 v[198:201], v192 offset:49152
	ds_read_b128 v[206:209], v192 offset:51200
	ds_read_b128 v[210:213], v191 offset:53248
	ds_read_b128 v[218:221], v191 offset:55296
	ds_read_b128 v[214:217], v192 offset:53248
	ds_read_b128 v[222:225], v192 offset:55296
	global_load_lds_dwordx4 v164, s[98:99]
	s_add_i32 m0, s101, 0x2000
	s_add_u32 s30, s30, 0xb0080
	s_addc_u32 s31, s31, 0
	s_add_i32 s101, s88, s53
	global_load_lds_dwordx4 v168, s[98:99]
	s_add_u32 s98, s34, s12
	s_addc_u32 s99, s35, s13
	s_sub_u32 s98, s98, 0xb0000
	s_subb_u32 s99, s99, 0
	s_mov_b32 m0, s101
	s_nop 0
	global_load_lds_dwordx4 v164, s[30:31]
	s_add_i32 m0, s101, 0x2000
	s_nop 0
	global_load_lds_dwordx4 v168, s[30:31]
	s_mov_b32 m0, s63
	s_nop 0
	global_load_lds_dwordx4 v162, s[98:99]
	s_mov_b32 m0, s64
	s_nop 0
	global_load_lds_dwordx4 v166, s[98:99]
	s_waitcnt vmcnt(8)
	s_waitcnt lgkmcnt(0)
	s_barrier
	s_setprio 1
	s_waitcnt lgkmcnt(0)
	v_mfma_scale_f32_16x16x128_f8f6f4 v[94:97], v[2:9], v[194:201], v[94:97], v1, v182 op_sel_hi:[0,0,0]
	v_mfma_scale_f32_16x16x128_f8f6f4 v[90:93], v[10:17], v[194:201], v[90:93], v1, v182 op_sel_hi:[0,0,0]
	v_mfma_scale_f32_16x16x128_f8f6f4 v[78:81], v[2:9], v[202:209], v[78:81], v1, v182 op_sel_hi:[0,0,0]
	v_mfma_scale_f32_16x16x128_f8f6f4 v[74:77], v[10:17], v[202:209], v[74:77], v1, v182 op_sel_hi:[0,0,0]
	v_mfma_scale_f32_16x16x128_f8f6f4 v[62:65], v[2:9], v[210:217], v[62:65], v1, v182 op_sel_hi:[0,0,0]
	v_mfma_scale_f32_16x16x128_f8f6f4 v[58:61], v[10:17], v[210:217], v[58:61], v1, v182 op_sel_hi:[0,0,0]
	v_mfma_scale_f32_16x16x128_f8f6f4 v[46:49], v[2:9], v[218:225], v[46:49], v1, v182 op_sel_hi:[0,0,0]
	v_mfma_scale_f32_16x16x128_f8f6f4 v[42:45], v[10:17], v[218:225], v[42:45], v1, v182 op_sel_hi:[0,0,0]
	s_setprio 0
	s_setprio 1
	v_mfma_scale_f32_16x16x128_f8f6f4 v[86:89], v[18:25], v[194:201], v[86:89], v1, v182 op_sel_hi:[0,0,0]
	v_mfma_scale_f32_16x16x128_f8f6f4 v[82:85], v[26:33], v[194:201], v[82:85], v1, v182 op_sel_hi:[0,0,0]
	v_mfma_scale_f32_16x16x128_f8f6f4 v[70:73], v[18:25], v[202:209], v[70:73], v1, v182 op_sel_hi:[0,0,0]
	v_mfma_scale_f32_16x16x128_f8f6f4 v[66:69], v[26:33], v[202:209], v[66:69], v1, v182 op_sel_hi:[0,0,0]
	v_mfma_scale_f32_16x16x128_f8f6f4 v[54:57], v[18:25], v[210:217], v[54:57], v1, v182 op_sel_hi:[0,0,0]
	v_mfma_scale_f32_16x16x128_f8f6f4 v[50:53], v[26:33], v[210:217], v[50:53], v1, v182 op_sel_hi:[0,0,0]
	v_mfma_scale_f32_16x16x128_f8f6f4 v[38:41], v[18:25], v[218:225], v[38:41], v1, v182 op_sel_hi:[0,0,0]
	v_mfma_scale_f32_16x16x128_f8f6f4 v[34:37], v[26:33], v[218:225], v[34:37], v1, v182 op_sel_hi:[0,0,0]
	s_setprio 0
	s_barrier
	s_add_u32 s28, s28, 0x100
	s_addc_u32 s29, s29, 0
	s_add_u32 s82, s82, 0x100
	s_addc_u32 s83, s83, 0
	s_cmp_ge_u32 s84, s25
	s_mov_b32 s34, s84
; #define PG8_STAGE(bufoff, gbase, voff) do { _Pragma("unroll") for (int _i = 0; _i < 2; ++_i) \
;         __builtin_amdgcn_global_load_lds((const unsigned*)((const char*)(gbase) + (voff)[_i]), (PG8_LAS unsigned*)(lds + (bufoff) + ldsw + _i * 8192), 16, 0, 0); } while (0)
; #define PG8_LDA(dst, b, h) do { _Pragma("unroll") for (int m = 0; m < 4; ++m) _Pragma("unroll") for (int k = 0; k < 2; ++k) dst[m][k] = *(const PG8_LAS bf16x8*)(lds + PG8_SA(b, h) + aoff + m * 2048 + k * 1024); } while (0)
; #define PG8_LDB(dst, b, h) do { _Pragma("unroll") for (int n = 0; n < 2; ++n) _Pragma("unroll") for (int k = 0; k < 2; ++k) dst[n][k] = *(const PG8_LAS bf16x8*)(lds + PG8_SB(b, h) + boff + n * 2048 + k * 1024); } while (0)
; #define PG8_MMA(ai, bj, At, Bt) do { __builtin_amdgcn_s_setprio(1); _Pragma("unroll") for (int m = 0; m < 4; ++m) _Pragma("unroll") for (int n = 0; n < 2; ++n) _Pragma("unroll") for (int k = 0; k < 2; ++k) \
;         acc[ai][bj][m][n] = __builtin_amdgcn_mfma_f32_16x16x32_bf16(Bt[n][k], At[m][k], acc[ai][bj][m][n], 0, 0, 0); __builtin_amdgcn_s_setprio(0); } while (0)
; #define PG8_WAIT_V(n) asm volatile("s_waitcnt vmcnt(" #n ")" ::: "memory")
; #define PG8_WAIT_L(n) asm volatile("s_waitcnt lgkmcnt(" #n ")" ::: "memory")
; #define PG8_BAR __builtin_amdgcn_s_barrier()
; #define PG8_SCHED __builtin_amdgcn_sched_barrier(0)
; #define PG8_STAGE(bufoff, gbase, voff) do { _Pragma("unroll") for (int _i = 0; _i < 2; ++_i) \
;         __builtin_amdgcn_global_load_lds((const unsigned*)((const char*)(gbase) + (voff)[_i]), (PG8_LAS unsigned*)(lds + (bufoff) + ldsw + _i * 8192), 16, 0, 0); } while (0)
; #define PG8_WAIT_V(n) asm volatile("s_waitcnt vmcnt(" #n ")" ::: "memory")
; template <class Epi, class Sched, bool ALIGN_EPI = false>
; __device__ __forceinline__ void gemm_phase8(PG8_LAS unsigned char* lds, const Gemm g, const Sched& S, const Epi& E) {
;     ...
;             PG8_LDB(B0, 0, 0); PG8_LDB(B1, 0, 1); PG8_SCHED; PG8_LDA(At, 0, 0); PG8_STAGE(PG8_SA(1, 1), a1 + hstepA, voffA);
;             PG8_WAIT_V(8); PG8_WAIT_L(0); PG8_BAR; PG8_MMA(0, 0, At, B0); PG8_MMA(0, 1, At, B1); PG8_BAR; PG8_SCHED;
;             PG8_LDA(At, 0, 1); PG8_STAGE(PG8_SB(0, 0), b2, voffB); PG8_STAGE(PG8_SB(0, 1), b2 + hstepB, voffB); PG8_STAGE(PG8_SA(0, 0), a2, voffA);
;             PG8_WAIT_V(8); PG8_WAIT_L(0); PG8_BAR; PG8_MMA(1, 0, At, B0); PG8_MMA(1, 1, At, B1); PG8_BAR; PG8_SCHED;
.LBB0_502:
	ds_read_b128 v[18:21], v187
	ds_read_b128 v[26:29], v187 offset:2048
	ds_read_b128 v[22:25], v188
	ds_read_b128 v[30:33], v188 offset:2048
	ds_read_b128 v[2:5], v189
	ds_read_b128 v[10:13], v189 offset:2048
	ds_read_b128 v[6:9], v190
	ds_read_b128 v[14:17], v190 offset:2048
	s_add_i32 s84, s34, 2
	s_add_u32 s30, s28, 0xfff50080
	s_addc_u32 s31, s29, -1
	s_cmp_eq_u32 s81, s34
	s_cselect_b32 s34, s20, s30
	s_cselect_b32 s35, s21, s31
	s_cselect_b32 s31, s23, s83
	s_cselect_b32 s30, s22, s82
	s_add_i32 m0, s54, 0xc000
	ds_read_b128 v[174:177], v191
	ds_read_b128 v[194:197], v191 offset:2048
	ds_read_b128 v[178:181], v192
	ds_read_b128 v[198:201], v192 offset:2048
	ds_read_b128 v[202:205], v191 offset:4096
	ds_read_b128 v[210:213], v191 offset:6144
	ds_read_b128 v[206:209], v192 offset:4096
	ds_read_b128 v[214:217], v192 offset:6144
	global_load_lds_dwordx4 v170, s[28:29]
	s_add_i32 m0, s54, 0xe000
	s_nop 0
	global_load_lds_dwordx4 v172, s[28:29]
	s_waitcnt vmcnt(8)
	s_waitcnt lgkmcnt(0)
	s_barrier
	s_setprio 1
	s_waitcnt lgkmcnt(0)
	v_mfma_scale_f32_16x16x128_f8f6f4 v[158:161], v[18:25], v[174:181], v[158:161], v1, v182 op_sel_hi:[0,0,0]
	v_mfma_scale_f32_16x16x128_f8f6f4 v[154:157], v[26:33], v[174:181], v[154:157], v1, v182 op_sel_hi:[0,0,0]
	v_mfma_scale_f32_16x16x128_f8f6f4 v[142:145], v[18:25], v[194:201], v[142:145], v1, v182 op_sel_hi:[0,0,0]
	v_mfma_scale_f32_16x16x128_f8f6f4 v[138:141], v[26:33], v[194:201], v[138:141], v1, v182 op_sel_hi:[0,0,0]
	v_mfma_scale_f32_16x16x128_f8f6f4 v[126:129], v[18:25], v[202:209], v[126:129], v1, v182 op_sel_hi:[0,0,0]
	v_mfma_scale_f32_16x16x128_f8f6f4 v[122:125], v[26:33], v[202:209], v[122:125], v1, v182 op_sel_hi:[0,0,0]
	v_mfma_scale_f32_16x16x128_f8f6f4 v[110:113], v[18:25], v[210:217], v[110:113], v1, v182 op_sel_hi:[0,0,0]
	v_mfma_scale_f32_16x16x128_f8f6f4 v[106:109], v[26:33], v[210:217], v[106:109], v1, v182 op_sel_hi:[0,0,0]
	s_setprio 0
	s_setprio 1
	v_mfma_scale_f32_16x16x128_f8f6f4 v[150:153], v[2:9], v[174:181], v[150:153], v1, v182 op_sel_hi:[0,0,0]
	v_mfma_scale_f32_16x16x128_f8f6f4 v[146:149], v[10:17], v[174:181], v[146:149], v1, v182 op_sel_hi:[0,0,0]
	v_mfma_scale_f32_16x16x128_f8f6f4 v[134:137], v[2:9], v[194:201], v[134:137], v1, v182 op_sel_hi:[0,0,0]
	v_mfma_scale_f32_16x16x128_f8f6f4 v[130:133], v[10:17], v[194:201], v[130:133], v1, v182 op_sel_hi:[0,0,0]
	v_mfma_scale_f32_16x16x128_f8f6f4 v[118:121], v[2:9], v[202:209], v[118:121], v1, v182 op_sel_hi:[0,0,0]
	v_mfma_scale_f32_16x16x128_f8f6f4 v[114:117], v[10:17], v[202:209], v[114:117], v1, v182 op_sel_hi:[0,0,0]
	v_mfma_scale_f32_16x16x128_f8f6f4 v[102:105], v[2:9], v[210:217], v[102:105], v1, v182 op_sel_hi:[0,0,0]
	v_mfma_scale_f32_16x16x128_f8f6f4 v[98:101], v[10:17], v[210:217], v[98:101], v1, v182 op_sel_hi:[0,0,0]
	s_setprio 0
	s_barrier
	s_add_i32 s85, s65, s53
	s_mov_b32 m0, s85
	ds_read_b128 v[194:197], v191 offset:16384
	ds_read_b128 v[202:205], v191 offset:18432
	ds_read_b128 v[198:201], v192 offset:16384
	ds_read_b128 v[206:209], v192 offset:18432
	ds_read_b128 v[210:213], v191 offset:20480
	ds_read_b128 v[218:221], v191 offset:22528
	ds_read_b128 v[214:217], v192 offset:20480
	ds_read_b128 v[222:225], v192 offset:22528
	global_load_lds_dwordx4 v164, s[30:31]
	s_add_i32 m0, s85, 0x2000
	s_add_u32 s88, s30, 0xb0000
	s_addc_u32 s89, s31, 0
	s_add_i32 s85, s66, s53
	global_load_lds_dwordx4 v168, s[30:31]
	s_mov_b32 m0, s85
	s_nop 0
	global_load_lds_dwordx4 v164, s[88:89]
	s_add_i32 m0, s85, 0x2000
	s_nop 0
	global_load_lds_dwordx4 v168, s[88:89]
	s_mov_b32 m0, s54
	s_nop 0
	global_load_lds_dwordx4 v162, s[34:35]
	s_mov_b32 m0, s55
	s_nop 0
	global_load_lds_dwordx4 v166, s[34:35]
	s_waitcnt vmcnt(8)
	s_waitcnt lgkmcnt(0)
	s_barrier
	s_setprio 1
	s_waitcnt lgkmcnt(0)
	v_mfma_scale_f32_16x16x128_f8f6f4 v[94:97], v[18:25], v[194:201], v[94:97], v1, v182 op_sel_hi:[0,0,0]
	v_mfma_scale_f32_16x16x128_f8f6f4 v[90:93], v[26:33], v[194:201], v[90:93], v1, v182 op_sel_hi:[0,0,0]
	v_mfma_scale_f32_16x16x128_f8f6f4 v[78:81], v[18:25], v[202:209], v[78:81], v1, v182 op_sel_hi:[0,0,0]
	v_mfma_scale_f32_16x16x128_f8f6f4 v[74:77], v[26:33], v[202:209], v[74:77], v1, v182 op_sel_hi:[0,0,0]
	v_mfma_scale_f32_16x16x128_f8f6f4 v[62:65], v[18:25], v[210:217], v[62:65], v1, v182 op_sel_hi:[0,0,0]
	v_mfma_scale_f32_16x16x128_f8f6f4 v[58:61], v[26:33], v[210:217], v[58:61], v1, v182 op_sel_hi:[0,0,0]
	v_mfma_scale_f32_16x16x128_f8f6f4 v[46:49], v[18:25], v[218:225], v[46:49], v1, v182 op_sel_hi:[0,0,0]
	v_mfma_scale_f32_16x16x128_f8f6f4 v[42:45], v[26:33], v[218:225], v[42:45], v1, v182 op_sel_hi:[0,0,0]
	s_setprio 0
	s_setprio 1
	v_mfma_scale_f32_16x16x128_f8f6f4 v[86:89], v[2:9], v[194:201], v[86:89], v1, v182 op_sel_hi:[0,0,0]
	v_mfma_scale_f32_16x16x128_f8f6f4 v[82:85], v[10:17], v[194:201], v[82:85], v1, v182 op_sel_hi:[0,0,0]
	v_mfma_scale_f32_16x16x128_f8f6f4 v[70:73], v[2:9], v[202:209], v[70:73], v1, v182 op_sel_hi:[0,0,0]
	v_mfma_scale_f32_16x16x128_f8f6f4 v[66:69], v[10:17], v[202:209], v[66:69], v1, v182 op_sel_hi:[0,0,0]
	v_mfma_scale_f32_16x16x128_f8f6f4 v[54:57], v[2:9], v[210:217], v[54:57], v1, v182 op_sel_hi:[0,0,0]
	v_mfma_scale_f32_16x16x128_f8f6f4 v[50:53], v[10:17], v[210:217], v[50:53], v1, v182 op_sel_hi:[0,0,0]
	v_mfma_scale_f32_16x16x128_f8f6f4 v[38:41], v[2:9], v[218:225], v[38:41], v1, v182 op_sel_hi:[0,0,0]
	v_mfma_scale_f32_16x16x128_f8f6f4 v[34:37], v[10:17], v[218:225], v[34:37], v1, v182 op_sel_hi:[0,0,0]
	s_setprio 0
	s_barrier
; #define PG8_STAGE(bufoff, gbase, voff) do { _Pragma("unroll") for (int _i = 0; _i < 2; ++_i) \
;         __builtin_amdgcn_global_load_lds((const unsigned*)((const char*)(gbase) + (voff)[_i]), (PG8_LAS unsigned*)(lds + (bufoff) + ldsw + _i * 8192), 16, 0, 0); } while (0)
; #define PG8_LDA(dst, b, h) do { _Pragma("unroll") for (int m = 0; m < 4; ++m) _Pragma("unroll") for (int k = 0; k < 2; ++k) dst[m][k] = *(const PG8_LAS bf16x8*)(lds + PG8_SA(b, h) + aoff + m * 2048 + k * 1024); } while (0)
; #define PG8_LDB(dst, b, h) do { _Pragma("unroll") for (int n = 0; n < 2; ++n) _Pragma("unroll") for (int k = 0; k < 2; ++k) dst[n][k] = *(const PG8_LAS bf16x8*)(lds + PG8_SB(b, h) + boff + n * 2048 + k * 1024); } while (0)
; #define PG8_MMA(ai, bj, At, Bt) do { __builtin_amdgcn_s_setprio(1); _Pragma("unroll") for (int m = 0; m < 4; ++m) _Pragma("unroll") for (int n = 0; n < 2; ++n) _Pragma("unroll") for (int k = 0; k < 2; ++k) \
;         acc[ai][bj][m][n] = __builtin_amdgcn_mfma_f32_16x16x32_bf16(Bt[n][k], At[m][k], acc[ai][bj][m][n], 0, 0, 0); __builtin_amdgcn_s_setprio(0); } while (0)
; #define PG8_WAIT_V(n) asm volatile("s_waitcnt vmcnt(" #n ")" ::: "memory")
; #define PG8_WAIT_L(n) asm volatile("s_waitcnt lgkmcnt(" #n ")" ::: "memory")
; #define PG8_BAR __builtin_amdgcn_s_barrier()
; #define PG8_SCHED __builtin_amdgcn_sched_barrier(0)
; #define PG8_STAGE(bufoff, gbase, voff) do { _Pragma("unroll") for (int _i = 0; _i < 2; ++_i) \
;         __builtin_amdgcn_global_load_lds((const unsigned*)((const char*)(gbase) + (voff)[_i]), (PG8_LAS unsigned*)(lds + (bufoff) + ldsw + _i * 8192), 16, 0, 0); } while (0)
; #define PG8_BAR __builtin_amdgcn_s_barrier()
; template <class Epi, class Sched, bool ALIGN_EPI = false>
; __device__ __forceinline__ void gemm_phase8(PG8_LAS unsigned char* lds, const Gemm g, const Sched& S, const Epi& E) {
;     ...
;             PG8_LDB(B0, 1, 0); PG8_LDB(B1, 1, 1); PG8_SCHED; PG8_LDA(At, 1, 0); PG8_STAGE(PG8_SA(0, 1), a2 + hstepA, voffA);
;             PG8_WAIT_V(8); PG8_WAIT_L(0); PG8_BAR; PG8_MMA(0, 0, At, B0); PG8_MMA(0, 1, At, B1); PG8_BAR; PG8_SCHED;
;             PG8_LDA(At, 1, 1); PG8_STAGE(PG8_SB(1, 0), b3, voffB); PG8_STAGE(PG8_SB(1, 1), b3 + hstepB, voffB); PG8_STAGE(PG8_SA(1, 0), a3, voffA);
;             PG8_WAIT_V(8); PG8_WAIT_L(0); PG8_BAR; PG8_MMA(1, 0, At, B0); PG8_MMA(1, 1, At, B1); PG8_BAR; PG8_SCHED;
;         }
	s_add_i32 s85, 0, 0x18000
	s_add_i32 s88, 0, 0x1c000
	v_add_u32_e32 v6, s85, v184
	v_add_u32_e32 v14, s85, v185
	v_add_u32_e32 v22, s88, v184
	v_add_u32_e32 v30, s88, v185
	ds_read_b128 v[2:5], v6
	ds_read_b128 v[10:13], v6 offset:2048
	ds_read_b128 v[6:9], v14
	ds_read_b128 v[14:17], v14 offset:2048
	ds_read_b128 v[18:21], v22
	ds_read_b128 v[26:29], v22 offset:2048
	ds_read_b128 v[22:25], v30
	ds_read_b128 v[30:33], v30 offset:2048
	s_add_u32 s34, s34, 0xb0000
	s_addc_u32 s35, s35, 0
	s_mov_b32 m0, s56
	ds_read_b128 v[194:197], v191 offset:32768
	ds_read_b128 v[202:205], v191 offset:34816
	ds_read_b128 v[198:201], v192 offset:32768
	ds_read_b128 v[206:209], v192 offset:34816
	ds_read_b128 v[210:213], v191 offset:36864
	ds_read_b128 v[218:221], v191 offset:38912
	ds_read_b128 v[214:217], v192 offset:36864
	ds_read_b128 v[222:225], v192 offset:38912
	global_load_lds_dwordx4 v162, s[34:35]
	s_mov_b32 m0, s57
	s_nop 0
	global_load_lds_dwordx4 v166, s[34:35]
	s_waitcnt vmcnt(8)
	s_waitcnt lgkmcnt(0)
	s_barrier
	s_setprio 1
	s_waitcnt lgkmcnt(0)
	v_mfma_scale_f32_16x16x128_f8f6f4 v[158:161], v[2:9], v[194:201], v[158:161], v1, v182 op_sel_hi:[0,0,0]
	v_mfma_scale_f32_16x16x128_f8f6f4 v[154:157], v[10:17], v[194:201], v[154:157], v1, v182 op_sel_hi:[0,0,0]
	v_mfma_scale_f32_16x16x128_f8f6f4 v[142:145], v[2:9], v[202:209], v[142:145], v1, v182 op_sel_hi:[0,0,0]
	v_mfma_scale_f32_16x16x128_f8f6f4 v[138:141], v[10:17], v[202:209], v[138:141], v1, v182 op_sel_hi:[0,0,0]
	v_mfma_scale_f32_16x16x128_f8f6f4 v[126:129], v[2:9], v[210:217], v[126:129], v1, v182 op_sel_hi:[0,0,0]
	v_mfma_scale_f32_16x16x128_f8f6f4 v[122:125], v[10:17], v[210:217], v[122:125], v1, v182 op_sel_hi:[0,0,0]
	v_mfma_scale_f32_16x16x128_f8f6f4 v[110:113], v[2:9], v[218:225], v[110:113], v1, v182 op_sel_hi:[0,0,0]
	v_mfma_scale_f32_16x16x128_f8f6f4 v[106:109], v[10:17], v[218:225], v[106:109], v1, v182 op_sel_hi:[0,0,0]
	s_setprio 0
	s_setprio 1
	v_mfma_scale_f32_16x16x128_f8f6f4 v[150:153], v[18:25], v[194:201], v[150:153], v1, v182 op_sel_hi:[0,0,0]
	v_mfma_scale_f32_16x16x128_f8f6f4 v[146:149], v[26:33], v[194:201], v[146:149], v1, v182 op_sel_hi:[0,0,0]
	v_mfma_scale_f32_16x16x128_f8f6f4 v[134:137], v[18:25], v[202:209], v[134:137], v1, v182 op_sel_hi:[0,0,0]
	v_mfma_scale_f32_16x16x128_f8f6f4 v[130:133], v[26:33], v[202:209], v[130:133], v1, v182 op_sel_hi:[0,0,0]
	v_mfma_scale_f32_16x16x128_f8f6f4 v[118:121], v[18:25], v[210:217], v[118:121], v1, v182 op_sel_hi:[0,0,0]
	v_mfma_scale_f32_16x16x128_f8f6f4 v[114:117], v[26:33], v[210:217], v[114:117], v1, v182 op_sel_hi:[0,0,0]
	v_mfma_scale_f32_16x16x128_f8f6f4 v[102:105], v[18:25], v[218:225], v[102:105], v1, v182 op_sel_hi:[0,0,0]
	v_mfma_scale_f32_16x16x128_f8f6f4 v[98:101], v[26:33], v[218:225], v[98:101], v1, v182 op_sel_hi:[0,0,0]
	s_setprio 0
	s_barrier
	s_add_i32 s101, s85, s53
	s_add_u32 s98, s30, s12
	s_addc_u32 s99, s31, s13
	s_mov_b32 m0, s101
	ds_read_b128 v[194:197], v191 offset:49152
	ds_read_b128 v[202:205], v191 offset:51200
	ds_read_b128 v[198:201], v192 offset:49152
	ds_read_b128 v[206:209], v192 offset:51200
	ds_read_b128 v[210:213], v191 offset:53248
	ds_read_b128 v[218:221], v191 offset:55296
	ds_read_b128 v[214:217], v192 offset:53248
	ds_read_b128 v[222:225], v192 offset:55296
	global_load_lds_dwordx4 v164, s[98:99]
	s_add_i32 m0, s101, 0x2000
	s_add_u32 s30, s30, 0xb0080
	s_addc_u32 s31, s31, 0
	s_add_i32 s101, s88, s53
	global_load_lds_dwordx4 v168, s[98:99]
	s_add_u32 s98, s34, s12
	s_addc_u32 s99, s35, s13
	s_sub_u32 s98, s98, 0xb0000
	s_subb_u32 s99, s99, 0
	s_mov_b32 m0, s101
	s_nop 0
	global_load_lds_dwordx4 v164, s[30:31]
	s_add_i32 m0, s101, 0x2000
	s_nop 0
	global_load_lds_dwordx4 v168, s[30:31]
	s_mov_b32 m0, s63
	s_nop 0
	global_load_lds_dwordx4 v162, s[98:99]
	s_mov_b32 m0, s64
	s_nop 0
	global_load_lds_dwordx4 v166, s[98:99]
	s_waitcnt vmcnt(8)
	s_waitcnt lgkmcnt(0)
	s_barrier
	s_setprio 1
	s_waitcnt lgkmcnt(0)
	v_mfma_scale_f32_16x16x128_f8f6f4 v[94:97], v[2:9], v[194:201], v[94:97], v1, v182 op_sel_hi:[0,0,0]
	v_mfma_scale_f32_16x16x128_f8f6f4 v[90:93], v[10:17], v[194:201], v[90:93], v1, v182 op_sel_hi:[0,0,0]
	v_mfma_scale_f32_16x16x128_f8f6f4 v[78:81], v[2:9], v[202:209], v[78:81], v1, v182 op_sel_hi:[0,0,0]
	v_mfma_scale_f32_16x16x128_f8f6f4 v[74:77], v[10:17], v[202:209], v[74:77], v1, v182 op_sel_hi:[0,0,0]
	v_mfma_scale_f32_16x16x128_f8f6f4 v[62:65], v[2:9], v[210:217], v[62:65], v1, v182 op_sel_hi:[0,0,0]
	v_mfma_scale_f32_16x16x128_f8f6f4 v[58:61], v[10:17], v[210:217], v[58:61], v1, v182 op_sel_hi:[0,0,0]
	v_mfma_scale_f32_16x16x128_f8f6f4 v[46:49], v[2:9], v[218:225], v[46:49], v1, v182 op_sel_hi:[0,0,0]
	v_mfma_scale_f32_16x16x128_f8f6f4 v[42:45], v[10:17], v[218:225], v[42:45], v1, v182 op_sel_hi:[0,0,0]
	s_setprio 0
	s_setprio 1
	v_mfma_scale_f32_16x16x128_f8f6f4 v[86:89], v[18:25], v[194:201], v[86:89], v1, v182 op_sel_hi:[0,0,0]
	v_mfma_scale_f32_16x16x128_f8f6f4 v[82:85], v[26:33], v[194:201], v[82:85], v1, v182 op_sel_hi:[0,0,0]
	v_mfma_scale_f32_16x16x128_f8f6f4 v[70:73], v[18:25], v[202:209], v[70:73], v1, v182 op_sel_hi:[0,0,0]
	v_mfma_scale_f32_16x16x128_f8f6f4 v[66:69], v[26:33], v[202:209], v[66:69], v1, v182 op_sel_hi:[0,0,0]
	v_mfma_scale_f32_16x16x128_f8f6f4 v[54:57], v[18:25], v[210:217], v[54:57], v1, v182 op_sel_hi:[0,0,0]
	v_mfma_scale_f32_16x16x128_f8f6f4 v[50:53], v[26:33], v[210:217], v[50:53], v1, v182 op_sel_hi:[0,0,0]
	v_mfma_scale_f32_16x16x128_f8f6f4 v[38:41], v[18:25], v[218:225], v[38:41], v1, v182 op_sel_hi:[0,0,0]
	v_mfma_scale_f32_16x16x128_f8f6f4 v[34:37], v[26:33], v[218:225], v[34:37], v1, v182 op_sel_hi:[0,0,0]
	s_setprio 0
	s_barrier
	s_add_u32 s28, s28, 0x100
	s_addc_u32 s29, s29, 0
	s_add_u32 s82, s82, 0x100
	s_addc_u32 s83, s83, 0
	s_cmp_ge_u32 s84, s25
	s_mov_b32 s34, s84
	s_cbranch_scc0 .LBB0_502
	s_and_b64 vcc, exec, s[14:15]
	s_cbranch_vccz .LBB0_505
	s_barrier

; #define PG8_STAGE(bufoff, gbase, voff) do { _Pragma("unroll") for (int _i = 0; _i < 2; ++_i) \
;         __builtin_amdgcn_global_load_lds((const unsigned*)((const char*)(gbase) + (voff)[_i]), (PG8_LAS unsigned*)(lds + (bufoff) + ldsw + _i * 8192), 16, 0, 0); } while (0)
; #define PG8_LDA(dst, b, h) do { _Pragma("unroll") for (int m = 0; m < 4; ++m) _Pragma("unroll") for (int k = 0; k < 2; ++k) dst[m][k] = *(const PG8_LAS bf16x8*)(lds + PG8_SA(b, h) + aoff + m * 2048 + k * 1024); } while (0)
; #define PG8_LDB(dst, b, h) do { _Pragma("unroll") for (int n = 0; n < 2; ++n) _Pragma("unroll") for (int k = 0; k < 2; ++k) dst[n][k] = *(const PG8_LAS bf16x8*)(lds + PG8_SB(b, h) + boff + n * 2048 + k * 1024); } while (0)
; #define PG8_WAIT_V(n) asm volatile("s_waitcnt vmcnt(" #n ")" ::: "memory")
; #define PG8_WAIT_L(n) asm volatile("s_waitcnt lgkmcnt(" #n ")" ::: "memory")
; template <class Epi, class Sched, bool ALIGN_EPI = false>
; __device__ __forceinline__ void gemm_phase(PG8_LAS unsigned char* lds, const Gemm g, const Sched& S, const Epi& E) {
;     ...
;         const bool has_next = S.next(ui + 1, nxt);
;         const size_t nko = (has_next && nxt.kp > 0) ? (size_t)nxt.kp * g.kpiece * 2 : 0;
;         const char* nA = has_next ? (const char*)g.A + (size_t)nxt.pm * tstepA + (size_t)nxt.pn * astep + nko : cA; const char* nB = has_next ? (const char*)g.Bt + (size_t)nxt.pn * tstepB + nko : cB;
;         const int nt = (cur.kp < 0 ? g.K : g.kpiece) / BK;
;         for (int t = 0; t < nt; t += 2) {
;             const bool last = (t == nt - 2);
;             const char* a1 = cA + (size_t)(t + 1) * kstep;
;             const char* a2 = last ? nA : cA + (size_t)(t + 2) * kstep; const char* b2 = last ? nB : cB + (size_t)(t + 2) * kstep;
;             const char* a3 = a2 + kstep; const char* b3 = b2 + kstep;
;             if (last && has_next) S.a_ready(nxt);
;             PG8_LDB(B0, 0, 0); PG8_LDB(B1, 0, 1); PG8_SCHED; PG8_LDA(At, 0, 0); PG8_STAGE(PG8_SA(1, 1), a1 + hstepA, voffA);
;             PG8_WAIT_V(8); PG8_WAIT_L(0); PG8_BAR; PG8_MMA(0, 0, At, B0); PG8_MMA(0, 1, At, B1); PG8_BAR; PG8_SCHED;
;             PG8_LDA(At, 0, 1); PG8_STAGE(PG8_SB(0, 0), b2, voffB); PG8_STAGE(PG8_SB(0, 1), b2 + hstepB, voffB); PG8_STAGE(PG8_SA(0, 0), a2, voffA);
;             PG8_WAIT_V(8); PG8_WAIT_L(0); PG8_BAR; PG8_MMA(1, 0, At, B0); PG8_MMA(1, 1, At, B1); PG8_BAR; PG8_SCHED;
.LBB0_733:
	s_ashr_i32 s27, s26, 31
	s_lshl_b64 s[28:29], s[26:27], 20
	s_add_u32 s28, s56, s28
	s_addc_u32 s29, s57, s29
	s_and_b64 s[30:31], s[2:3], exec
	s_cselect_b32 s13, s29, s53
	s_cselect_b32 s27, s28, s52
	s_ashr_i32 s25, s24, 31
	s_lshl_b64 s[30:31], s[24:25], 20
	s_add_u32 s30, s4, s30
	s_addc_u32 s31, s5, s31
	s_and_b64 s[54:55], s[2:3], exec
	s_cselect_b32 s25, s31, s35
	s_cselect_b32 s82, s30, s34
	s_add_u32 s52, s52, 0x80080
	s_addc_u32 s53, s53, 0
	s_add_u32 s83, s34, 0x100
	s_addc_u32 s84, s35, 0
	s_mov_b32 s85, -2
	ds_read_b128 v[130:133], v165
	ds_read_b128 v[134:137], v165 offset:1024
	ds_read_b128 v[158:161], v165 offset:2048
	ds_read_b128 v[170:173], v165 offset:3072
	ds_read_b128 v[174:177], v166
	ds_read_b128 v[178:181], v166 offset:1024
	ds_read_b128 v[182:185], v166 offset:2048
	ds_read_b128 v[186:189], v166 offset:3072
	s_add_u32 s34, s52, 0xfff80080
	s_addc_u32 s35, s53, -1
	s_cmp_eq_u32 s85, 28
	s_cselect_b32 s55, s13, s35
	s_cselect_b32 s54, s27, s34
	s_cselect_b32 s35, s25, s84
	s_cselect_b32 s34, s82, s83
	s_add_i32 m0, s61, 0xc000
	ds_read_b128 v[190:193], v167
	ds_read_b128 v[194:197], v167 offset:1024
	ds_read_b128 v[198:201], v167 offset:2048
	ds_read_b128 v[202:205], v167 offset:3072
	ds_read_b128 v[206:209], v167 offset:4096
	ds_read_b128 v[210:213], v167 offset:5120
	ds_read_b128 v[214:217], v167 offset:6144
	ds_read_b128 v[218:221], v167 offset:7168
	global_load_lds_dwordx4 v150, s[52:53]
	s_add_i32 m0, s61, 0xe000
	s_nop 0
	global_load_lds_dwordx4 v152, s[52:53]
	s_waitcnt vmcnt(8)
	s_waitcnt lgkmcnt(0)
	s_barrier
	s_waitcnt lgkmcnt(0)
	v_mfma_f32_16x16x32_bf16 v[126:129], v[130:133], v[190:193], 0
	v_mfma_f32_16x16x32_bf16 v[122:125], v[158:161], v[190:193], 0
	v_mfma_f32_16x16x32_bf16 v[114:117], v[130:133], v[198:201], 0
	v_mfma_f32_16x16x32_bf16 v[106:109], v[158:161], v[198:201], 0
	v_mfma_f32_16x16x32_bf16 v[98:101], v[130:133], v[206:209], 0
	v_mfma_f32_16x16x32_bf16 v[90:93], v[158:161], v[206:209], 0
	v_mfma_f32_16x16x32_bf16 v[82:85], v[130:133], v[214:217], 0
	v_mfma_f32_16x16x32_bf16 v[74:77], v[158:161], v[214:217], 0
	v_mfma_f32_16x16x32_bf16 v[126:129], v[134:137], v[194:197], v[126:129]
	v_mfma_f32_16x16x32_bf16 v[122:125], v[170:173], v[194:197], v[122:125]
	v_mfma_f32_16x16x32_bf16 v[114:117], v[134:137], v[202:205], v[114:117]
	v_mfma_f32_16x16x32_bf16 v[106:109], v[170:173], v[202:205], v[106:109]
	v_mfma_f32_16x16x32_bf16 v[98:101], v[134:137], v[210:213], v[98:101]
	v_mfma_f32_16x16x32_bf16 v[90:93], v[170:173], v[210:213], v[90:93]
	v_mfma_f32_16x16x32_bf16 v[82:85], v[134:137], v[218:221], v[82:85]
	v_mfma_f32_16x16x32_bf16 v[74:77], v[170:173], v[218:221], v[74:77]
	v_mfma_f32_16x16x32_bf16 v[118:121], v[174:177], v[190:193], 0
	v_mfma_f32_16x16x32_bf16 v[110:113], v[182:185], v[190:193], 0
	v_mfma_f32_16x16x32_bf16 v[102:105], v[174:177], v[198:201], 0
	v_mfma_f32_16x16x32_bf16 v[94:97], v[182:185], v[198:201], 0
	v_mfma_f32_16x16x32_bf16 v[86:89], v[174:177], v[206:209], 0
	v_mfma_f32_16x16x32_bf16 v[78:81], v[182:185], v[206:209], 0
	v_mfma_f32_16x16x32_bf16 v[70:73], v[174:177], v[214:217], 0
	v_mfma_f32_16x16x32_bf16 v[66:69], v[182:185], v[214:217], 0
	v_mfma_f32_16x16x32_bf16 v[118:121], v[178:181], v[194:197], v[118:121]
	v_mfma_f32_16x16x32_bf16 v[110:113], v[186:189], v[194:197], v[110:113]
	v_mfma_f32_16x16x32_bf16 v[102:105], v[178:181], v[202:205], v[102:105]
	v_mfma_f32_16x16x32_bf16 v[94:97], v[186:189], v[202:205], v[94:97]
	v_mfma_f32_16x16x32_bf16 v[86:89], v[178:181], v[210:213], v[86:89]
	v_mfma_f32_16x16x32_bf16 v[78:81], v[186:189], v[210:213], v[78:81]
	v_mfma_f32_16x16x32_bf16 v[70:73], v[178:181], v[218:221], v[70:73]
	v_mfma_f32_16x16x32_bf16 v[66:69], v[186:189], v[218:221], v[66:69]
	s_barrier
	s_add_i32 s88, s72, s58
	s_mov_b32 m0, s88
	ds_read_b128 v[190:193], v167 offset:16384
	ds_read_b128 v[194:197], v167 offset:17408
	ds_read_b128 v[198:201], v167 offset:18432
	ds_read_b128 v[202:205], v167 offset:19456
	ds_read_b128 v[206:209], v167 offset:20480
	ds_read_b128 v[210:213], v167 offset:21504
	ds_read_b128 v[214:217], v167 offset:22528
	ds_read_b128 v[218:221], v167 offset:23552
	global_load_lds_dwordx4 v140, s[34:35]
	s_add_i32 m0, s88, 0x2000
	s_add_u32 s88, s34, 0x80000
	s_addc_u32 s89, s35, 0
	s_add_i32 s90, s73, s58
	global_load_lds_dwordx4 v144, s[34:35]
	s_mov_b32 m0, s90
	s_nop 0
	global_load_lds_dwordx4 v140, s[88:89]
	s_add_i32 m0, s90, 0x2000
	s_nop 0
	global_load_lds_dwordx4 v144, s[88:89]
	s_mov_b32 m0, s61
	s_nop 0
	global_load_lds_dwordx4 v138, s[54:55]
	s_mov_b32 m0, s62
	s_nop 0
	global_load_lds_dwordx4 v142, s[54:55]
	s_waitcnt vmcnt(8)
	s_waitcnt lgkmcnt(0)
	s_barrier
; #define PG8_STAGE(bufoff, gbase, voff) do { _Pragma("unroll") for (int _i = 0; _i < 2; ++_i) \
;         __builtin_amdgcn_global_load_lds((const unsigned*)((const char*)(gbase) + (voff)[_i]), (PG8_LAS unsigned*)(lds + (bufoff) + ldsw + _i * 8192), 16, 0, 0); } while (0)
; #define PG8_LDA(dst, b, h) do { _Pragma("unroll") for (int m = 0; m < 4; ++m) _Pragma("unroll") for (int k = 0; k < 2; ++k) dst[m][k] = *(const PG8_LAS bf16x8*)(lds + PG8_SA(b, h) + aoff + m * 2048 + k * 1024); } while (0)
; #define PG8_LDB(dst, b, h) do { _Pragma("unroll") for (int n = 0; n < 2; ++n) _Pragma("unroll") for (int k = 0; k < 2; ++k) dst[n][k] = *(const PG8_LAS bf16x8*)(lds + PG8_SB(b, h) + boff + n * 2048 + k * 1024); } while (0)
; #define PG8_MMA(ai, bj, At, Bt) do { __builtin_amdgcn_s_setprio(1); _Pragma("unroll") for (int m = 0; m < 4; ++m) _Pragma("unroll") for (int n = 0; n < 2; ++n) _Pragma("unroll") for (int k = 0; k < 2; ++k) \
;         acc[ai][bj][m][n] = __builtin_amdgcn_mfma_f32_16x16x32_bf16(Bt[n][k], At[m][k], acc[ai][bj][m][n], 0, 0, 0); __builtin_amdgcn_s_setprio(0); } while (0)
; #define PG8_WAIT_V(n) asm volatile("s_waitcnt vmcnt(" #n ")" ::: "memory")
; #define PG8_WAIT_L(n) asm volatile("s_waitcnt lgkmcnt(" #n ")" ::: "memory")
; #define PG8_BAR __builtin_amdgcn_s_barrier()
; #define PG8_SCHED __builtin_amdgcn_sched_barrier(0)
; #define PG8_STAGE(bufoff, gbase, voff) do { _Pragma("unroll") for (int _i = 0; _i < 2; ++_i) \
;         __builtin_amdgcn_global_load_lds((const unsigned*)((const char*)(gbase) + (voff)[_i]), (PG8_LAS unsigned*)(lds + (bufoff) + ldsw + _i * 8192), 16, 0, 0); } while (0)
; #define PG8_WAIT_V(n) asm volatile("s_waitcnt vmcnt(" #n ")" ::: "memory")
; #define PG8_WAIT_L(n) asm volatile("s_waitcnt lgkmcnt(" #n ")" ::: "memory")
; #define PG8_BAR __builtin_amdgcn_s_barrier()
; template <class Epi, class Sched, bool ALIGN_EPI = false>
; __device__ __forceinline__ void gemm_phase(PG8_LAS unsigned char* lds, const Gemm g, const Sched& S, const Epi& E) {
;     ...
;             PG8_WAIT_V(8); PG8_WAIT_L(0); PG8_BAR; PG8_MMA(1, 0, At, B0); PG8_MMA(1, 1, At, B1); PG8_BAR; PG8_SCHED;
;             PG8_LDB(B0, 1, 0); PG8_LDB(B1, 1, 1); PG8_SCHED; PG8_LDA(At, 1, 0); PG8_STAGE(PG8_SA(0, 1), a2 + hstepA, voffA);
;             PG8_WAIT_V(8); PG8_WAIT_L(0); PG8_BAR; PG8_MMA(0, 0, At, B0); PG8_MMA(0, 1, At, B1); PG8_BAR; PG8_SCHED;
	s_waitcnt lgkmcnt(0)
	v_mfma_f32_16x16x32_bf16 v[62:65], v[130:133], v[190:193], 0
	v_mfma_f32_16x16x32_bf16 v[58:61], v[158:161], v[190:193], 0
	v_mfma_f32_16x16x32_bf16 v[54:57], v[130:133], v[198:201], 0
	v_mfma_f32_16x16x32_bf16 v[46:49], v[158:161], v[198:201], 0
	v_mfma_f32_16x16x32_bf16 v[38:41], v[130:133], v[206:209], 0
	v_mfma_f32_16x16x32_bf16 v[30:33], v[158:161], v[206:209], 0
	v_mfma_f32_16x16x32_bf16 v[22:25], v[130:133], v[214:217], 0
	v_mfma_f32_16x16x32_bf16 v[14:17], v[158:161], v[214:217], 0
	v_mfma_f32_16x16x32_bf16 v[62:65], v[134:137], v[194:197], v[62:65]
	v_mfma_f32_16x16x32_bf16 v[58:61], v[170:173], v[194:197], v[58:61]
	v_mfma_f32_16x16x32_bf16 v[54:57], v[134:137], v[202:205], v[54:57]
	v_mfma_f32_16x16x32_bf16 v[46:49], v[170:173], v[202:205], v[46:49]
	v_mfma_f32_16x16x32_bf16 v[38:41], v[134:137], v[210:213], v[38:41]
	v_mfma_f32_16x16x32_bf16 v[30:33], v[170:173], v[210:213], v[30:33]
	v_mfma_f32_16x16x32_bf16 v[22:25], v[134:137], v[218:221], v[22:25]
	v_mfma_f32_16x16x32_bf16 v[14:17], v[170:173], v[218:221], v[14:17]
	v_mfma_f32_16x16x32_bf16 v[50:53], v[174:177], v[190:193], 0
	v_mfma_f32_16x16x32_bf16 v[42:45], v[182:185], v[190:193], 0
	v_mfma_f32_16x16x32_bf16 v[34:37], v[174:177], v[198:201], 0
	v_mfma_f32_16x16x32_bf16 v[26:29], v[182:185], v[198:201], 0
	v_mfma_f32_16x16x32_bf16 v[18:21], v[174:177], v[206:209], 0
	v_mfma_f32_16x16x32_bf16 v[10:13], v[182:185], v[206:209], 0
	v_mfma_f32_16x16x32_bf16 v[6:9], v[174:177], v[214:217], 0
	v_mfma_f32_16x16x32_bf16 v[2:5], v[182:185], v[214:217], 0
	v_mfma_f32_16x16x32_bf16 v[50:53], v[178:181], v[194:197], v[50:53]
	v_mfma_f32_16x16x32_bf16 v[42:45], v[186:189], v[194:197], v[42:45]
	v_mfma_f32_16x16x32_bf16 v[34:37], v[178:181], v[202:205], v[34:37]
	v_mfma_f32_16x16x32_bf16 v[26:29], v[186:189], v[202:205], v[26:29]
	v_mfma_f32_16x16x32_bf16 v[18:21], v[178:181], v[210:213], v[18:21]
	v_mfma_f32_16x16x32_bf16 v[10:13], v[186:189], v[210:213], v[10:13]
	v_mfma_f32_16x16x32_bf16 v[6:9], v[178:181], v[218:221], v[6:9]
	v_mfma_f32_16x16x32_bf16 v[2:5], v[186:189], v[218:221], v[2:5]
	s_barrier
	s_add_i32 s88, 0, 0x18000
	v_add_u32_e32 v146, s88, v164
	s_add_i32 s89, 0, 0x1c000
	ds_read_b128 v[130:133], v146
	ds_read_b128 v[134:137], v146 offset:1024
	ds_read_b128 v[158:161], v146 offset:2048
	ds_read_b128 v[170:173], v146 offset:3072
	v_add_u32_e32 v146, s89, v164
	ds_read_b128 v[174:177], v146
	ds_read_b128 v[178:181], v146 offset:1024
	ds_read_b128 v[182:185], v146 offset:2048
	ds_read_b128 v[186:189], v146 offset:3072
	s_add_u32 s54, s54, 0x80000
	s_addc_u32 s55, s55, 0
	s_mov_b32 m0, s63
	ds_read_b128 v[190:193], v167 offset:32768
	ds_read_b128 v[194:197], v167 offset:33792
	ds_read_b128 v[198:201], v167 offset:34816
	ds_read_b128 v[202:205], v167 offset:35840
	ds_read_b128 v[206:209], v167 offset:36864
	ds_read_b128 v[210:213], v167 offset:37888
	ds_read_b128 v[214:217], v167 offset:38912
	ds_read_b128 v[218:221], v167 offset:39936
	global_load_lds_dwordx4 v138, s[54:55]
	s_mov_b32 m0, s64
	s_nop 0
	global_load_lds_dwordx4 v142, s[54:55]
	s_waitcnt vmcnt(8)
	s_waitcnt lgkmcnt(0)
	s_barrier
	s_waitcnt lgkmcnt(0)
	v_mfma_f32_16x16x32_bf16 v[126:129], v[130:133], v[190:193], v[126:129]
	v_mfma_f32_16x16x32_bf16 v[122:125], v[158:161], v[190:193], v[122:125]
	v_mfma_f32_16x16x32_bf16 v[114:117], v[130:133], v[198:201], v[114:117]
	v_mfma_f32_16x16x32_bf16 v[106:109], v[158:161], v[198:201], v[106:109]
	v_mfma_f32_16x16x32_bf16 v[98:101], v[130:133], v[206:209], v[98:101]
	v_mfma_f32_16x16x32_bf16 v[90:93], v[158:161], v[206:209], v[90:93]
	v_mfma_f32_16x16x32_bf16 v[82:85], v[130:133], v[214:217], v[82:85]
	v_mfma_f32_16x16x32_bf16 v[74:77], v[158:161], v[214:217], v[74:77]
	v_mfma_f32_16x16x32_bf16 v[126:129], v[134:137], v[194:197], v[126:129]
	v_mfma_f32_16x16x32_bf16 v[122:125], v[170:173], v[194:197], v[122:125]
	v_mfma_f32_16x16x32_bf16 v[114:117], v[134:137], v[202:205], v[114:117]
	v_mfma_f32_16x16x32_bf16 v[106:109], v[170:173], v[202:205], v[106:109]
	v_mfma_f32_16x16x32_bf16 v[98:101], v[134:137], v[210:213], v[98:101]
	v_mfma_f32_16x16x32_bf16 v[90:93], v[170:173], v[210:213], v[90:93]
	v_mfma_f32_16x16x32_bf16 v[82:85], v[134:137], v[218:221], v[82:85]
	v_mfma_f32_16x16x32_bf16 v[74:77], v[170:173], v[218:221], v[74:77]
	v_mfma_f32_16x16x32_bf16 v[118:121], v[174:177], v[190:193], v[118:121]
	v_mfma_f32_16x16x32_bf16 v[110:113], v[182:185], v[190:193], v[110:113]
	v_mfma_f32_16x16x32_bf16 v[102:105], v[174:177], v[198:201], v[102:105]
	v_mfma_f32_16x16x32_bf16 v[94:97], v[182:185], v[198:201], v[94:97]
	v_mfma_f32_16x16x32_bf16 v[86:89], v[174:177], v[206:209], v[86:89]
	v_mfma_f32_16x16x32_bf16 v[78:81], v[182:185], v[206:209], v[78:81]
	v_mfma_f32_16x16x32_bf16 v[70:73], v[174:177], v[214:217], v[70:73]
	v_mfma_f32_16x16x32_bf16 v[66:69], v[182:185], v[214:217], v[66:69]
	v_mfma_f32_16x16x32_bf16 v[118:121], v[178:181], v[194:197], v[118:121]
	v_mfma_f32_16x16x32_bf16 v[110:113], v[186:189], v[194:197], v[110:113]
	v_mfma_f32_16x16x32_bf16 v[102:105], v[178:181], v[202:205], v[102:105]
	v_mfma_f32_16x16x32_bf16 v[94:97], v[186:189], v[202:205], v[94:97]
	v_mfma_f32_16x16x32_bf16 v[86:89], v[178:181], v[210:213], v[86:89]
	v_mfma_f32_16x16x32_bf16 v[78:81], v[186:189], v[210:213], v[78:81]
	v_mfma_f32_16x16x32_bf16 v[70:73], v[178:181], v[218:221], v[70:73]
	v_mfma_f32_16x16x32_bf16 v[66:69], v[186:189], v[218:221], v[66:69]
	s_barrier
; #define PG8_STAGE(bufoff, gbase, voff) do { _Pragma("unroll") for (int _i = 0; _i < 2; ++_i) \
;         __builtin_amdgcn_global_load_lds((const unsigned*)((const char*)(gbase) + (voff)[_i]), (PG8_LAS unsigned*)(lds + (bufoff) + ldsw + _i * 8192), 16, 0, 0); } while (0)
; #define PG8_LDA(dst, b, h) do { _Pragma("unroll") for (int m = 0; m < 4; ++m) _Pragma("unroll") for (int k = 0; k < 2; ++k) dst[m][k] = *(const PG8_LAS bf16x8*)(lds + PG8_SA(b, h) + aoff + m * 2048 + k * 1024); } while (0)
; #define PG8_LDB(dst, b, h) do { _Pragma("unroll") for (int n = 0; n < 2; ++n) _Pragma("unroll") for (int k = 0; k < 2; ++k) dst[n][k] = *(const PG8_LAS bf16x8*)(lds + PG8_SB(b, h) + boff + n * 2048 + k * 1024); } while (0)
; #define PG8_MMA(ai, bj, At, Bt) do { __builtin_amdgcn_s_setprio(1); _Pragma("unroll") for (int m = 0; m < 4; ++m) _Pragma("unroll") for (int n = 0; n < 2; ++n) _Pragma("unroll") for (int k = 0; k < 2; ++k) \
;         acc[ai][bj][m][n] = __builtin_amdgcn_mfma_f32_16x16x32_bf16(Bt[n][k], At[m][k], acc[ai][bj][m][n], 0, 0, 0); __builtin_amdgcn_s_setprio(0); } while (0)
; #define PG8_WAIT_V(n) asm volatile("s_waitcnt vmcnt(" #n ")" ::: "memory")
; #define PG8_WAIT_L(n) asm volatile("s_waitcnt lgkmcnt(" #n ")" ::: "memory")
; #define PG8_BAR __builtin_amdgcn_s_barrier()
; #define PG8_SCHED __builtin_amdgcn_sched_barrier(0)
; #define PG8_STAGE(bufoff, gbase, voff) do { _Pragma("unroll") for (int _i = 0; _i < 2; ++_i) \
;         __builtin_amdgcn_global_load_lds((const unsigned*)((const char*)(gbase) + (voff)[_i]), (PG8_LAS unsigned*)(lds + (bufoff) + ldsw + _i * 8192), 16, 0, 0); } while (0)
; #define PG8_WAIT_V(n) asm volatile("s_waitcnt vmcnt(" #n ")" ::: "memory")
; template <class Epi, class Sched, bool ALIGN_EPI = false>
; __device__ __forceinline__ void gemm_phase(PG8_LAS unsigned char* lds, const Gemm g, const Sched& S, const Epi& E) {
;     ...
;             PG8_LDB(B0, 0, 0); PG8_LDB(B1, 0, 1); PG8_SCHED; PG8_LDA(At, 0, 0); PG8_STAGE(PG8_SA(1, 1), a1 + hstepA, voffA);
;             PG8_WAIT_V(8); PG8_WAIT_L(0); PG8_BAR; PG8_MMA(0, 0, At, B0); PG8_MMA(0, 1, At, B1); PG8_BAR; PG8_SCHED;
;     ...
;             PG8_LDA(At, 1, 1); PG8_STAGE(PG8_SB(1, 0), b3, voffB); PG8_STAGE(PG8_SB(1, 1), b3 + hstepB, voffB); PG8_STAGE(PG8_SA(1, 0), a3, voffA);
;             PG8_WAIT_V(8); PG8_WAIT_L(0); PG8_BAR; PG8_MMA(1, 0, At, B0); PG8_MMA(1, 1, At, B1); PG8_BAR; PG8_SCHED;
	s_add_i32 s101, s88, s58
	s_add_u32 s98, s34, s10
	s_addc_u32 s99, s35, s11
	s_mov_b32 m0, s101
	ds_read_b128 v[190:193], v167 offset:49152
	ds_read_b128 v[194:197], v167 offset:50176
	ds_read_b128 v[198:201], v167 offset:51200
	ds_read_b128 v[202:205], v167 offset:52224
	ds_read_b128 v[206:209], v167 offset:53248
	ds_read_b128 v[210:213], v167 offset:54272
	ds_read_b128 v[214:217], v167 offset:55296
	ds_read_b128 v[218:221], v167 offset:56320
	global_load_lds_dwordx4 v140, s[98:99]
	s_add_i32 m0, s101, 0x2000
	s_add_u32 s34, s34, 0x80080
	s_addc_u32 s35, s35, 0
	s_add_i32 s101, s89, s58
	global_load_lds_dwordx4 v144, s[98:99]
	s_add_u32 s98, s54, s10
	s_addc_u32 s99, s55, s11
	s_sub_u32 s98, s98, 0x80000
	s_subb_u32 s99, s99, 0
	s_mov_b32 m0, s101
	s_nop 0
	global_load_lds_dwordx4 v140, s[34:35]
	s_add_i32 m0, s101, 0x2000
	s_nop 0
	global_load_lds_dwordx4 v144, s[34:35]
	s_mov_b32 m0, s70
	s_nop 0
	global_load_lds_dwordx4 v138, s[98:99]
	s_mov_b32 m0, s71
	s_nop 0
	global_load_lds_dwordx4 v142, s[98:99]
	s_waitcnt vmcnt(8)
	s_waitcnt lgkmcnt(0)
	s_barrier
	s_waitcnt lgkmcnt(0)
	v_mfma_f32_16x16x32_bf16 v[62:65], v[130:133], v[190:193], v[62:65]
	v_mfma_f32_16x16x32_bf16 v[58:61], v[158:161], v[190:193], v[58:61]
	v_mfma_f32_16x16x32_bf16 v[54:57], v[130:133], v[198:201], v[54:57]
	v_mfma_f32_16x16x32_bf16 v[46:49], v[158:161], v[198:201], v[46:49]
	v_mfma_f32_16x16x32_bf16 v[38:41], v[130:133], v[206:209], v[38:41]
	v_mfma_f32_16x16x32_bf16 v[30:33], v[158:161], v[206:209], v[30:33]
	v_mfma_f32_16x16x32_bf16 v[22:25], v[130:133], v[214:217], v[22:25]
	v_mfma_f32_16x16x32_bf16 v[14:17], v[158:161], v[214:217], v[14:17]
	v_mfma_f32_16x16x32_bf16 v[62:65], v[134:137], v[194:197], v[62:65]
	v_mfma_f32_16x16x32_bf16 v[58:61], v[170:173], v[194:197], v[58:61]
	v_mfma_f32_16x16x32_bf16 v[54:57], v[134:137], v[202:205], v[54:57]
	v_mfma_f32_16x16x32_bf16 v[46:49], v[170:173], v[202:205], v[46:49]
	v_mfma_f32_16x16x32_bf16 v[38:41], v[134:137], v[210:213], v[38:41]
	v_mfma_f32_16x16x32_bf16 v[30:33], v[170:173], v[210:213], v[30:33]
	v_mfma_f32_16x16x32_bf16 v[22:25], v[134:137], v[218:221], v[22:25]
	v_mfma_f32_16x16x32_bf16 v[14:17], v[170:173], v[218:221], v[14:17]
	v_mfma_f32_16x16x32_bf16 v[50:53], v[174:177], v[190:193], v[50:53]
	v_mfma_f32_16x16x32_bf16 v[42:45], v[182:185], v[190:193], v[42:45]
	v_mfma_f32_16x16x32_bf16 v[34:37], v[174:177], v[198:201], v[34:37]
	v_mfma_f32_16x16x32_bf16 v[26:29], v[182:185], v[198:201], v[26:29]
	v_mfma_f32_16x16x32_bf16 v[18:21], v[174:177], v[206:209], v[18:21]
	v_mfma_f32_16x16x32_bf16 v[10:13], v[182:185], v[206:209], v[10:13]
	v_mfma_f32_16x16x32_bf16 v[6:9], v[174:177], v[214:217], v[6:9]
	v_mfma_f32_16x16x32_bf16 v[2:5], v[182:185], v[214:217], v[2:5]
	v_mfma_f32_16x16x32_bf16 v[50:53], v[178:181], v[194:197], v[50:53]
	v_mfma_f32_16x16x32_bf16 v[42:45], v[186:189], v[194:197], v[42:45]
	v_mfma_f32_16x16x32_bf16 v[34:37], v[178:181], v[202:205], v[34:37]
	v_mfma_f32_16x16x32_bf16 v[26:29], v[186:189], v[202:205], v[26:29]
	v_mfma_f32_16x16x32_bf16 v[18:21], v[178:181], v[210:213], v[18:21]
	v_mfma_f32_16x16x32_bf16 v[10:13], v[186:189], v[210:213], v[10:13]
	v_mfma_f32_16x16x32_bf16 v[6:9], v[178:181], v[218:221], v[6:9]
	v_mfma_f32_16x16x32_bf16 v[2:5], v[186:189], v[218:221], v[2:5]
	s_barrier
	s_add_i32 s85, s85, 2
	s_add_u32 s52, s52, 0x100
	s_addc_u32 s53, s53, 0
	s_add_u32 s83, s83, 0x100
	s_addc_u32 s84, s84, 0
	s_cmp_gt_u32 s85, 29
.LBB0_734:
	ds_read_b128 v[130:133], v165
	ds_read_b128 v[134:137], v165 offset:1024
	ds_read_b128 v[158:161], v165 offset:2048
	ds_read_b128 v[170:173], v165 offset:3072
	ds_read_b128 v[174:177], v166
	ds_read_b128 v[178:181], v166 offset:1024
	ds_read_b128 v[182:185], v166 offset:2048
	ds_read_b128 v[186:189], v166 offset:3072
	s_add_u32 s34, s52, 0xfff80080
	s_addc_u32 s35, s53, -1
	s_cmp_eq_u32 s85, 28
	s_cselect_b32 s55, s13, s35
	s_cselect_b32 s54, s27, s34
	s_cselect_b32 s35, s25, s84
	s_cselect_b32 s34, s82, s83
	s_add_i32 m0, s61, 0xc000
	ds_read_b128 v[190:193], v167
	ds_read_b128 v[194:197], v167 offset:1024
	ds_read_b128 v[198:201], v167 offset:2048
	ds_read_b128 v[202:205], v167 offset:3072
	ds_read_b128 v[206:209], v167 offset:4096
	ds_read_b128 v[210:213], v167 offset:5120
	ds_read_b128 v[214:217], v167 offset:6144
	ds_read_b128 v[218:221], v167 offset:7168
	global_load_lds_dwordx4 v150, s[52:53]
	s_add_i32 m0, s61, 0xe000
	s_nop 0
	global_load_lds_dwordx4 v152, s[52:53]
	s_waitcnt vmcnt(8)
	s_waitcnt lgkmcnt(0)
	s_barrier
; #define PG8_STAGE(bufoff, gbase, voff) do { _Pragma("unroll") for (int _i = 0; _i < 2; ++_i) \
;         __builtin_amdgcn_global_load_lds((const unsigned*)((const char*)(gbase) + (voff)[_i]), (PG8_LAS unsigned*)(lds + (bufoff) + ldsw + _i * 8192), 16, 0, 0); } while (0)
; #define PG8_LDA(dst, b, h) do { _Pragma("unroll") for (int m = 0; m < 4; ++m) _Pragma("unroll") for (int k = 0; k < 2; ++k) dst[m][k] = *(const PG8_LAS bf16x8*)(lds + PG8_SA(b, h) + aoff + m * 2048 + k * 1024); } while (0)
; #define PG8_MMA(ai, bj, At, Bt) do { __builtin_amdgcn_s_setprio(1); _Pragma("unroll") for (int m = 0; m < 4; ++m) _Pragma("unroll") for (int n = 0; n < 2; ++n) _Pragma("unroll") for (int k = 0; k < 2; ++k) \
;         acc[ai][bj][m][n] = __builtin_amdgcn_mfma_f32_16x16x32_bf16(Bt[n][k], At[m][k], acc[ai][bj][m][n], 0, 0, 0); __builtin_amdgcn_s_setprio(0); } while (0)
; #define PG8_WAIT_V(n) asm volatile("s_waitcnt vmcnt(" #n ")" ::: "memory")
; #define PG8_WAIT_L(n) asm volatile("s_waitcnt lgkmcnt(" #n ")" ::: "memory")
; #define PG8_BAR __builtin_amdgcn_s_barrier()
; #define PG8_SCHED __builtin_amdgcn_sched_barrier(0)
; #define PG8_STAGE(bufoff, gbase, voff) do { _Pragma("unroll") for (int _i = 0; _i < 2; ++_i) \
;         __builtin_amdgcn_global_load_lds((const unsigned*)((const char*)(gbase) + (voff)[_i]), (PG8_LAS unsigned*)(lds + (bufoff) + ldsw + _i * 8192), 16, 0, 0); } while (0)
; #define PG8_LDA(dst, b, h) do { _Pragma("unroll") for (int m = 0; m < 4; ++m) dst[m] = cat8(*(const PG8_LAS bf16x8*)(lds + PG8_SA(b, h) + aoff + m * 2048), *(const PG8_LAS bf16x8*)(lds + PG8_SA(b, h) + (aoff ^ 16) + m * 2048)); } while (0)
; #define PG8_WAIT_V(n) asm volatile("s_waitcnt vmcnt(" #n ")" ::: "memory")
; #define PG8_WAIT_L(n) asm volatile("s_waitcnt lgkmcnt(" #n ")" ::: "memory")
; template <class Epi, class Sched, bool ALIGN_EPI = false>
; __device__ __forceinline__ void gemm_phase(PG8_LAS unsigned char* lds, const Gemm g, const Sched& S, const Epi& E) {
;     ...
;             PG8_WAIT_V(8); PG8_WAIT_L(0); PG8_BAR; PG8_MMA(0, 0, At, B0); PG8_MMA(0, 1, At, B1); PG8_BAR; PG8_SCHED;
;             PG8_LDA(At, 0, 1); PG8_STAGE(PG8_SB(0, 0), b2, voffB); PG8_STAGE(PG8_SB(0, 1), b2 + hstepB, voffB); PG8_STAGE(PG8_SA(0, 0), a2, voffA);
;             PG8_WAIT_V(8); PG8_WAIT_L(0); PG8_BAR; PG8_MMA(1, 0, At, B0); PG8_MMA(1, 1, At, B1); PG8_BAR; PG8_SCHED;
	s_waitcnt lgkmcnt(0)
	v_mfma_f32_16x16x32_bf16 v[126:129], v[130:133], v[190:193], v[126:129]
	v_mfma_f32_16x16x32_bf16 v[122:125], v[158:161], v[190:193], v[122:125]
	v_mfma_f32_16x16x32_bf16 v[114:117], v[130:133], v[198:201], v[114:117]
	v_mfma_f32_16x16x32_bf16 v[106:109], v[158:161], v[198:201], v[106:109]
	v_mfma_f32_16x16x32_bf16 v[98:101], v[130:133], v[206:209], v[98:101]
	v_mfma_f32_16x16x32_bf16 v[90:93], v[158:161], v[206:209], v[90:93]
	v_mfma_f32_16x16x32_bf16 v[82:85], v[130:133], v[214:217], v[82:85]
	v_mfma_f32_16x16x32_bf16 v[74:77], v[158:161], v[214:217], v[74:77]
	v_mfma_f32_16x16x32_bf16 v[126:129], v[134:137], v[194:197], v[126:129]
	v_mfma_f32_16x16x32_bf16 v[122:125], v[170:173], v[194:197], v[122:125]
	v_mfma_f32_16x16x32_bf16 v[114:117], v[134:137], v[202:205], v[114:117]
	v_mfma_f32_16x16x32_bf16 v[106:109], v[170:173], v[202:205], v[106:109]
	v_mfma_f32_16x16x32_bf16 v[98:101], v[134:137], v[210:213], v[98:101]
	v_mfma_f32_16x16x32_bf16 v[90:93], v[170:173], v[210:213], v[90:93]
	v_mfma_f32_16x16x32_bf16 v[82:85], v[134:137], v[218:221], v[82:85]
	v_mfma_f32_16x16x32_bf16 v[74:77], v[170:173], v[218:221], v[74:77]
	v_mfma_f32_16x16x32_bf16 v[118:121], v[174:177], v[190:193], v[118:121]
	v_mfma_f32_16x16x32_bf16 v[110:113], v[182:185], v[190:193], v[110:113]
	v_mfma_f32_16x16x32_bf16 v[102:105], v[174:177], v[198:201], v[102:105]
	v_mfma_f32_16x16x32_bf16 v[94:97], v[182:185], v[198:201], v[94:97]
	v_mfma_f32_16x16x32_bf16 v[86:89], v[174:177], v[206:209], v[86:89]
	v_mfma_f32_16x16x32_bf16 v[78:81], v[182:185], v[206:209], v[78:81]
	v_mfma_f32_16x16x32_bf16 v[70:73], v[174:177], v[214:217], v[70:73]
	v_mfma_f32_16x16x32_bf16 v[66:69], v[182:185], v[214:217], v[66:69]
	v_mfma_f32_16x16x32_bf16 v[118:121], v[178:181], v[194:197], v[118:121]
	v_mfma_f32_16x16x32_bf16 v[110:113], v[186:189], v[194:197], v[110:113]
	v_mfma_f32_16x16x32_bf16 v[102:105], v[178:181], v[202:205], v[102:105]
	v_mfma_f32_16x16x32_bf16 v[94:97], v[186:189], v[202:205], v[94:97]
	v_mfma_f32_16x16x32_bf16 v[86:89], v[178:181], v[210:213], v[86:89]
	v_mfma_f32_16x16x32_bf16 v[78:81], v[186:189], v[210:213], v[78:81]
	v_mfma_f32_16x16x32_bf16 v[70:73], v[178:181], v[218:221], v[70:73]
	v_mfma_f32_16x16x32_bf16 v[66:69], v[186:189], v[218:221], v[66:69]
	s_barrier
	s_add_i32 s88, s72, s58
	s_mov_b32 m0, s88
	ds_read_b128 v[190:193], v167 offset:16384
	ds_read_b128 v[194:197], v167 offset:17408
	ds_read_b128 v[198:201], v167 offset:18432
	ds_read_b128 v[202:205], v167 offset:19456
	ds_read_b128 v[206:209], v167 offset:20480
	ds_read_b128 v[210:213], v167 offset:21504
	ds_read_b128 v[214:217], v167 offset:22528
	ds_read_b128 v[218:221], v167 offset:23552
	global_load_lds_dwordx4 v140, s[34:35]
	s_add_i32 m0, s88, 0x2000
	s_add_u32 s88, s34, 0x80000
	s_addc_u32 s89, s35, 0
	s_add_i32 s90, s73, s58
	global_load_lds_dwordx4 v144, s[34:35]
	s_mov_b32 m0, s90
	s_nop 0
	global_load_lds_dwordx4 v140, s[88:89]
	s_add_i32 m0, s90, 0x2000
	s_nop 0
	global_load_lds_dwordx4 v144, s[88:89]
	s_mov_b32 m0, s61
	s_nop 0
	global_load_lds_dwordx4 v138, s[54:55]
	s_mov_b32 m0, s62
	s_nop 0
	global_load_lds_dwordx4 v142, s[54:55]
	s_waitcnt vmcnt(8)
	s_waitcnt lgkmcnt(0)
	s_barrier
	s_waitcnt lgkmcnt(0)
	v_mfma_f32_16x16x32_bf16 v[62:65], v[130:133], v[190:193], v[62:65]
	v_mfma_f32_16x16x32_bf16 v[58:61], v[158:161], v[190:193], v[58:61]
	v_mfma_f32_16x16x32_bf16 v[54:57], v[130:133], v[198:201], v[54:57]
	v_mfma_f32_16x16x32_bf16 v[46:49], v[158:161], v[198:201], v[46:49]
	v_mfma_f32_16x16x32_bf16 v[38:41], v[130:133], v[206:209], v[38:41]
	v_mfma_f32_16x16x32_bf16 v[30:33], v[158:161], v[206:209], v[30:33]
	v_mfma_f32_16x16x32_bf16 v[22:25], v[130:133], v[214:217], v[22:25]
	v_mfma_f32_16x16x32_bf16 v[14:17], v[158:161], v[214:217], v[14:17]
	v_mfma_f32_16x16x32_bf16 v[62:65], v[134:137], v[194:197], v[62:65]
	v_mfma_f32_16x16x32_bf16 v[58:61], v[170:173], v[194:197], v[58:61]
	v_mfma_f32_16x16x32_bf16 v[54:57], v[134:137], v[202:205], v[54:57]
	v_mfma_f32_16x16x32_bf16 v[46:49], v[170:173], v[202:205], v[46:49]
	v_mfma_f32_16x16x32_bf16 v[38:41], v[134:137], v[210:213], v[38:41]
	v_mfma_f32_16x16x32_bf16 v[30:33], v[170:173], v[210:213], v[30:33]
	v_mfma_f32_16x16x32_bf16 v[22:25], v[134:137], v[218:221], v[22:25]
	v_mfma_f32_16x16x32_bf16 v[14:17], v[170:173], v[218:221], v[14:17]
	v_mfma_f32_16x16x32_bf16 v[50:53], v[174:177], v[190:193], v[50:53]
	v_mfma_f32_16x16x32_bf16 v[42:45], v[182:185], v[190:193], v[42:45]
	v_mfma_f32_16x16x32_bf16 v[34:37], v[174:177], v[198:201], v[34:37]
	v_mfma_f32_16x16x32_bf16 v[26:29], v[182:185], v[198:201], v[26:29]
	v_mfma_f32_16x16x32_bf16 v[18:21], v[174:177], v[206:209], v[18:21]
	v_mfma_f32_16x16x32_bf16 v[10:13], v[182:185], v[206:209], v[10:13]
	v_mfma_f32_16x16x32_bf16 v[6:9], v[174:177], v[214:217], v[6:9]
	v_mfma_f32_16x16x32_bf16 v[2:5], v[182:185], v[214:217], v[2:5]
	v_mfma_f32_16x16x32_bf16 v[50:53], v[178:181], v[194:197], v[50:53]
	v_mfma_f32_16x16x32_bf16 v[42:45], v[186:189], v[194:197], v[42:45]
	v_mfma_f32_16x16x32_bf16 v[34:37], v[178:181], v[202:205], v[34:37]
	v_mfma_f32_16x16x32_bf16 v[26:29], v[186:189], v[202:205], v[26:29]
	v_mfma_f32_16x16x32_bf16 v[18:21], v[178:181], v[210:213], v[18:21]
	v_mfma_f32_16x16x32_bf16 v[10:13], v[186:189], v[210:213], v[10:13]
	v_mfma_f32_16x16x32_bf16 v[6:9], v[178:181], v[218:221], v[6:9]
	v_mfma_f32_16x16x32_bf16 v[2:5], v[186:189], v[218:221], v[2:5]
	s_barrier
; #define PG8_STAGE(bufoff, gbase, voff) do { _Pragma("unroll") for (int _i = 0; _i < 2; ++_i) \
;         __builtin_amdgcn_global_load_lds((const unsigned*)((const char*)(gbase) + (voff)[_i]), (PG8_LAS unsigned*)(lds + (bufoff) + ldsw + _i * 8192), 16, 0, 0); } while (0)
; #define PG8_LDA(dst, b, h) do { _Pragma("unroll") for (int m = 0; m < 4; ++m) _Pragma("unroll") for (int k = 0; k < 2; ++k) dst[m][k] = *(const PG8_LAS bf16x8*)(lds + PG8_SA(b, h) + aoff + m * 2048 + k * 1024); } while (0)
; #define PG8_LDB(dst, b, h) do { _Pragma("unroll") for (int n = 0; n < 2; ++n) _Pragma("unroll") for (int k = 0; k < 2; ++k) dst[n][k] = *(const PG8_LAS bf16x8*)(lds + PG8_SB(b, h) + boff + n * 2048 + k * 1024); } while (0)
; #define PG8_MMA(ai, bj, At, Bt) do { __builtin_amdgcn_s_setprio(1); _Pragma("unroll") for (int m = 0; m < 4; ++m) _Pragma("unroll") for (int n = 0; n < 2; ++n) _Pragma("unroll") for (int k = 0; k < 2; ++k) \
;         acc[ai][bj][m][n] = __builtin_amdgcn_mfma_f32_16x16x32_bf16(Bt[n][k], At[m][k], acc[ai][bj][m][n], 0, 0, 0); __builtin_amdgcn_s_setprio(0); } while (0)
; #define PG8_WAIT_V(n) asm volatile("s_waitcnt vmcnt(" #n ")" ::: "memory")
; #define PG8_WAIT_L(n) asm volatile("s_waitcnt lgkmcnt(" #n ")" ::: "memory")
; #define PG8_BAR __builtin_amdgcn_s_barrier()
; #define PG8_SCHED __builtin_amdgcn_sched_barrier(0)
; #define PG8_STAGE(bufoff, gbase, voff) do { _Pragma("unroll") for (int _i = 0; _i < 2; ++_i) \
;         __builtin_amdgcn_global_load_lds((const unsigned*)((const char*)(gbase) + (voff)[_i]), (PG8_LAS unsigned*)(lds + (bufoff) + ldsw + _i * 8192), 16, 0, 0); } while (0)
; #define PG8_BAR __builtin_amdgcn_s_barrier()
; template <class Epi, class Sched, bool ALIGN_EPI = false>
; __device__ __forceinline__ void gemm_phase(PG8_LAS unsigned char* lds, const Gemm g, const Sched& S, const Epi& E) {
;     ...
;             PG8_LDB(B0, 1, 0); PG8_LDB(B1, 1, 1); PG8_SCHED; PG8_LDA(At, 1, 0); PG8_STAGE(PG8_SA(0, 1), a2 + hstepA, voffA);
;             PG8_WAIT_V(8); PG8_WAIT_L(0); PG8_BAR; PG8_MMA(0, 0, At, B0); PG8_MMA(0, 1, At, B1); PG8_BAR; PG8_SCHED;
;             PG8_LDA(At, 1, 1); PG8_STAGE(PG8_SB(1, 0), b3, voffB); PG8_STAGE(PG8_SB(1, 1), b3 + hstepB, voffB); PG8_STAGE(PG8_SA(1, 0), a3, voffA);
;             PG8_WAIT_V(8); PG8_WAIT_L(0); PG8_BAR; PG8_MMA(1, 0, At, B0); PG8_MMA(1, 1, At, B1); PG8_BAR; PG8_SCHED;
;         }
	s_add_i32 s88, 0, 0x18000
	v_add_u32_e32 v146, s88, v164
	s_add_i32 s89, 0, 0x1c000
	ds_read_b128 v[130:133], v146
	ds_read_b128 v[134:137], v146 offset:1024
	ds_read_b128 v[158:161], v146 offset:2048
	ds_read_b128 v[170:173], v146 offset:3072
	v_add_u32_e32 v146, s89, v164
	ds_read_b128 v[174:177], v146
	ds_read_b128 v[178:181], v146 offset:1024
	ds_read_b128 v[182:185], v146 offset:2048
	ds_read_b128 v[186:189], v146 offset:3072
	s_add_u32 s54, s54, 0x80000
	s_addc_u32 s55, s55, 0
	s_mov_b32 m0, s63
	ds_read_b128 v[190:193], v167 offset:32768
	ds_read_b128 v[194:197], v167 offset:33792
	ds_read_b128 v[198:201], v167 offset:34816
	ds_read_b128 v[202:205], v167 offset:35840
	ds_read_b128 v[206:209], v167 offset:36864
	ds_read_b128 v[210:213], v167 offset:37888
	ds_read_b128 v[214:217], v167 offset:38912
	ds_read_b128 v[218:221], v167 offset:39936
	global_load_lds_dwordx4 v138, s[54:55]
	s_mov_b32 m0, s64
	s_nop 0
	global_load_lds_dwordx4 v142, s[54:55]
	s_waitcnt vmcnt(8)
	s_waitcnt lgkmcnt(0)
	s_barrier
	s_waitcnt lgkmcnt(0)
	v_mfma_f32_16x16x32_bf16 v[126:129], v[130:133], v[190:193], v[126:129]
	v_mfma_f32_16x16x32_bf16 v[122:125], v[158:161], v[190:193], v[122:125]
	v_mfma_f32_16x16x32_bf16 v[114:117], v[130:133], v[198:201], v[114:117]
	v_mfma_f32_16x16x32_bf16 v[106:109], v[158:161], v[198:201], v[106:109]
	v_mfma_f32_16x16x32_bf16 v[98:101], v[130:133], v[206:209], v[98:101]
	v_mfma_f32_16x16x32_bf16 v[90:93], v[158:161], v[206:209], v[90:93]
	v_mfma_f32_16x16x32_bf16 v[82:85], v[130:133], v[214:217], v[82:85]
	v_mfma_f32_16x16x32_bf16 v[74:77], v[158:161], v[214:217], v[74:77]
	v_mfma_f32_16x16x32_bf16 v[126:129], v[134:137], v[194:197], v[126:129]
	v_mfma_f32_16x16x32_bf16 v[122:125], v[170:173], v[194:197], v[122:125]
	v_mfma_f32_16x16x32_bf16 v[114:117], v[134:137], v[202:205], v[114:117]
	v_mfma_f32_16x16x32_bf16 v[106:109], v[170:173], v[202:205], v[106:109]
	v_mfma_f32_16x16x32_bf16 v[98:101], v[134:137], v[210:213], v[98:101]
	v_mfma_f32_16x16x32_bf16 v[90:93], v[170:173], v[210:213], v[90:93]
	v_mfma_f32_16x16x32_bf16 v[82:85], v[134:137], v[218:221], v[82:85]
	v_mfma_f32_16x16x32_bf16 v[74:77], v[170:173], v[218:221], v[74:77]
	v_mfma_f32_16x16x32_bf16 v[118:121], v[174:177], v[190:193], v[118:121]
	v_mfma_f32_16x16x32_bf16 v[110:113], v[182:185], v[190:193], v[110:113]
	v_mfma_f32_16x16x32_bf16 v[102:105], v[174:177], v[198:201], v[102:105]
	v_mfma_f32_16x16x32_bf16 v[94:97], v[182:185], v[198:201], v[94:97]
	v_mfma_f32_16x16x32_bf16 v[86:89], v[174:177], v[206:209], v[86:89]
	v_mfma_f32_16x16x32_bf16 v[78:81], v[182:185], v[206:209], v[78:81]
	v_mfma_f32_16x16x32_bf16 v[70:73], v[174:177], v[214:217], v[70:73]
	v_mfma_f32_16x16x32_bf16 v[66:69], v[182:185], v[214:217], v[66:69]
	v_mfma_f32_16x16x32_bf16 v[118:121], v[178:181], v[194:197], v[118:121]
	v_mfma_f32_16x16x32_bf16 v[110:113], v[186:189], v[194:197], v[110:113]
	v_mfma_f32_16x16x32_bf16 v[102:105], v[178:181], v[202:205], v[102:105]
	v_mfma_f32_16x16x32_bf16 v[94:97], v[186:189], v[202:205], v[94:97]
	v_mfma_f32_16x16x32_bf16 v[86:89], v[178:181], v[210:213], v[86:89]
	v_mfma_f32_16x16x32_bf16 v[78:81], v[186:189], v[210:213], v[78:81]
	v_mfma_f32_16x16x32_bf16 v[70:73], v[178:181], v[218:221], v[70:73]
	v_mfma_f32_16x16x32_bf16 v[66:69], v[186:189], v[218:221], v[66:69]
	s_barrier
	s_add_i32 s101, s88, s58
	s_add_u32 s98, s34, s10
	s_addc_u32 s99, s35, s11
	s_mov_b32 m0, s101
	ds_read_b128 v[190:193], v167 offset:49152
	ds_read_b128 v[194:197], v167 offset:50176
	ds_read_b128 v[198:201], v167 offset:51200
	ds_read_b128 v[202:205], v167 offset:52224
	ds_read_b128 v[206:209], v167 offset:53248
	ds_read_b128 v[210:213], v167 offset:54272
	ds_read_b128 v[214:217], v167 offset:55296
	ds_read_b128 v[218:221], v167 offset:56320
	global_load_lds_dwordx4 v140, s[98:99]
	s_add_i32 m0, s101, 0x2000
	s_add_u32 s34, s34, 0x80080
	s_addc_u32 s35, s35, 0
	s_add_i32 s101, s89, s58
	global_load_lds_dwordx4 v144, s[98:99]
	s_add_u32 s98, s54, s10
	s_addc_u32 s99, s55, s11
	s_sub_u32 s98, s98, 0x80000
	s_subb_u32 s99, s99, 0
	s_mov_b32 m0, s101
	s_nop 0
	global_load_lds_dwordx4 v140, s[34:35]
	s_add_i32 m0, s101, 0x2000
	s_nop 0
	global_load_lds_dwordx4 v144, s[34:35]
	s_mov_b32 m0, s70
	s_nop 0
	global_load_lds_dwordx4 v138, s[98:99]
	s_mov_b32 m0, s71
	s_nop 0
	global_load_lds_dwordx4 v142, s[98:99]
	s_waitcnt vmcnt(8)
	s_waitcnt lgkmcnt(0)
	s_barrier
	s_waitcnt lgkmcnt(0)
	v_mfma_f32_16x16x32_bf16 v[62:65], v[130:133], v[190:193], v[62:65]
	v_mfma_f32_16x16x32_bf16 v[58:61], v[158:161], v[190:193], v[58:61]
	v_mfma_f32_16x16x32_bf16 v[54:57], v[130:133], v[198:201], v[54:57]
	v_mfma_f32_16x16x32_bf16 v[46:49], v[158:161], v[198:201], v[46:49]
	v_mfma_f32_16x16x32_bf16 v[38:41], v[130:133], v[206:209], v[38:41]
	v_mfma_f32_16x16x32_bf16 v[30:33], v[158:161], v[206:209], v[30:33]
	v_mfma_f32_16x16x32_bf16 v[22:25], v[130:133], v[214:217], v[22:25]
	v_mfma_f32_16x16x32_bf16 v[14:17], v[158:161], v[214:217], v[14:17]
	v_mfma_f32_16x16x32_bf16 v[62:65], v[134:137], v[194:197], v[62:65]
	v_mfma_f32_16x16x32_bf16 v[58:61], v[170:173], v[194:197], v[58:61]
	v_mfma_f32_16x16x32_bf16 v[54:57], v[134:137], v[202:205], v[54:57]
	v_mfma_f32_16x16x32_bf16 v[46:49], v[170:173], v[202:205], v[46:49]
	v_mfma_f32_16x16x32_bf16 v[38:41], v[134:137], v[210:213], v[38:41]
	v_mfma_f32_16x16x32_bf16 v[30:33], v[170:173], v[210:213], v[30:33]
	v_mfma_f32_16x16x32_bf16 v[22:25], v[134:137], v[218:221], v[22:25]
	v_mfma_f32_16x16x32_bf16 v[14:17], v[170:173], v[218:221], v[14:17]
	v_mfma_f32_16x16x32_bf16 v[50:53], v[174:177], v[190:193], v[50:53]
	v_mfma_f32_16x16x32_bf16 v[42:45], v[182:185], v[190:193], v[42:45]
	v_mfma_f32_16x16x32_bf16 v[34:37], v[174:177], v[198:201], v[34:37]
	v_mfma_f32_16x16x32_bf16 v[26:29], v[182:185], v[198:201], v[26:29]
	v_mfma_f32_16x16x32_bf16 v[18:21], v[174:177], v[206:209], v[18:21]
	v_mfma_f32_16x16x32_bf16 v[10:13], v[182:185], v[206:209], v[10:13]
	v_mfma_f32_16x16x32_bf16 v[6:9], v[174:177], v[214:217], v[6:9]
	v_mfma_f32_16x16x32_bf16 v[2:5], v[182:185], v[214:217], v[2:5]
	v_mfma_f32_16x16x32_bf16 v[50:53], v[178:181], v[194:197], v[50:53]
	v_mfma_f32_16x16x32_bf16 v[42:45], v[186:189], v[194:197], v[42:45]
	v_mfma_f32_16x16x32_bf16 v[34:37], v[178:181], v[202:205], v[34:37]
	v_mfma_f32_16x16x32_bf16 v[26:29], v[186:189], v[202:205], v[26:29]
	v_mfma_f32_16x16x32_bf16 v[18:21], v[178:181], v[210:213], v[18:21]
	v_mfma_f32_16x16x32_bf16 v[10:13], v[186:189], v[210:213], v[10:13]
	v_mfma_f32_16x16x32_bf16 v[6:9], v[178:181], v[218:221], v[6:9]
	v_mfma_f32_16x16x32_bf16 v[2:5], v[186:189], v[218:221], v[2:5]
	s_barrier
	s_add_i32 s85, s85, 2
	s_add_u32 s52, s52, 0x100
	s_addc_u32 s53, s53, 0
	s_add_u32 s83, s83, 0x100
	s_addc_u32 s84, s84, 0
	s_cmp_gt_u32 s85, 29
	s_cbranch_scc0 .LBB0_734
	s_and_b64 vcc, exec, s[14:15]
	s_cbranch_vccz .LBB0_737
	s_barrier

; #define PG8_STAGE(bufoff, gbase, voff) do { _Pragma("unroll") for (int _i = 0; _i < 2; ++_i) \
;         __builtin_amdgcn_global_load_lds((const unsigned*)((const char*)(gbase) + (voff)[_i]), (PG8_LAS unsigned*)(lds + (bufoff) + ldsw + _i * 8192), 16, 0, 0); } while (0)
; #define PG8_LDA(dst, b, h) do { _Pragma("unroll") for (int m = 0; m < 4; ++m) _Pragma("unroll") for (int k = 0; k < 2; ++k) dst[m][k] = *(const PG8_LAS bf16x8*)(lds + PG8_SA(b, h) + aoff + m * 2048 + k * 1024); } while (0)
; #define PG8_LDB(dst, b, h) do { _Pragma("unroll") for (int n = 0; n < 2; ++n) _Pragma("unroll") for (int k = 0; k < 2; ++k) dst[n][k] = *(const PG8_LAS bf16x8*)(lds + PG8_SB(b, h) + boff + n * 2048 + k * 1024); } while (0)
; #define PG8_WAIT_V(n) asm volatile("s_waitcnt vmcnt(" #n ")" ::: "memory")
; #define PG8_WAIT_L(n) asm volatile("s_waitcnt lgkmcnt(" #n ")" ::: "memory")
; template <class Epi, class Sched, bool ALIGN_EPI = false>
; __device__ __forceinline__ void gemm_phase8(PG8_LAS unsigned char* lds, const Gemm g, const Sched& S, const Epi& E) {
;     ...
;         const bool has_next = S.next(ui + 1, nxt);
;         const size_t nko = (has_next && nxt.kp > 0) ? (size_t)nxt.kp * g.kpiece : 0;
;         const char* nA = has_next ? (const char*)g.A + (size_t)nxt.pm * tstepA + (size_t)nxt.pn * astep + nko : cA; const char* nB = has_next ? (const char*)g.Bt + (size_t)nxt.pn * tstepB + nko : cB;
;         const int nt = (cur.kp < 0 ? g.K : g.kpiece) / 128;
;         for (int t = 0; t < nt; t += 2) {
;             const bool last = (t == nt - 2);
;             const char* a1 = cA + (size_t)(t + 1) * kstep;
;             const char* a2 = last ? nA : cA + (size_t)(t + 2) * kstep; const char* b2 = last ? nB : cB + (size_t)(t + 2) * kstep;
;             const char* a3 = a2 + kstep; const char* b3 = b2 + kstep;
;             if (last && has_next) S.a_ready(nxt);
;             PG8_LDB(B0, 0, 0); PG8_LDB(B1, 0, 1); PG8_SCHED; PG8_LDA(At, 0, 0); PG8_STAGE(PG8_SA(1, 1), a1 + hstepA, voffA);
;             PG8_WAIT_V(8); PG8_WAIT_L(0); PG8_BAR; PG8_MMA(0, 0, At, B0); PG8_MMA(0, 1, At, B1); PG8_BAR; PG8_SCHED;
;             PG8_LDA(At, 0, 1); PG8_STAGE(PG8_SB(0, 0), b2, voffB); PG8_STAGE(PG8_SB(0, 1), b2 + hstepB, voffB); PG8_STAGE(PG8_SA(0, 0), a2, voffA);
;             PG8_WAIT_V(8); PG8_WAIT_L(0); PG8_BAR; PG8_MMA(1, 0, At, B0); PG8_MMA(1, 1, At, B1); PG8_BAR; PG8_SCHED;
.LBB0_1186:
	s_cmp_gt_i32 s0, 0
	s_cselect_b64 s[24:25], -1, 0
	s_and_b64 s[24:25], s[22:23], s[24:25]
	s_lshl_b64 s[26:27], s[0:1], 9
	s_and_b64 s[24:25], s[24:25], exec
	s_cselect_b32 s54, s27, 0
	s_cselect_b32 s55, s26, 0
	s_ashr_i32 s19, s18, 31
	s_lshl_b64 s[24:25], s[18:19], 19
	s_add_u32 s19, s33, s24
	s_addc_u32 s21, s60, s25
	s_add_u32 s24, s19, s55
	s_addc_u32 s25, s21, s54
	s_and_b64 s[26:27], s[22:23], exec
	s_cselect_b32 s19, s25, s57
	s_cselect_b32 s31, s24, s56
	s_ashr_i32 s21, s20, 31
	s_lshl_b64 s[26:27], s[20:21], 19
	s_add_u32 s21, s2, s26
	s_addc_u32 s27, s3, s27
	s_add_u32 s26, s21, s55
	s_addc_u32 s27, s27, s54
	s_and_b64 s[54:55], s[22:23], exec
	s_cselect_b32 s21, s27, s35
	s_cselect_b32 s75, s26, s34
	s_cmp_gt_i32 s30, -1
	s_cselect_b64 s[54:55], -1, 0
	s_cmp_lt_i32 s30, 0
	s_cselect_b32 s76, 16, 4
	s_add_i32 s77, s76, -2
	s_add_u32 s56, s56, 0x40080
	s_addc_u32 s57, s57, 0
	s_add_u32 s78, s34, 0x100
	s_mov_b32 s58, 0
	s_addc_u32 s79, s35, 0
	ds_read_b128 v[18:21], v187
	ds_read_b128 v[26:29], v187 offset:2048
	ds_read_b128 v[22:25], v188
	ds_read_b128 v[30:33], v188 offset:2048
	ds_read_b128 v[2:5], v189
	ds_read_b128 v[10:13], v189 offset:2048
	ds_read_b128 v[6:9], v190
	ds_read_b128 v[14:17], v190 offset:2048
	s_add_i32 s80, s58, 2
	s_add_u32 s34, s56, 0xfffc0080
	s_addc_u32 s35, s57, -1
	s_cmp_eq_u32 s77, s58
	s_cselect_b32 s58, s31, s34
	s_cselect_b32 s59, s19, s35
	s_cselect_b32 s35, s21, s79
	s_cselect_b32 s34, s75, s78
	s_add_i32 m0, s29, 0xc000
	ds_read_b128 v[174:177], v191
	ds_read_b128 v[194:197], v191 offset:2048
	ds_read_b128 v[178:181], v192
	ds_read_b128 v[198:201], v192 offset:2048
	ds_read_b128 v[202:205], v191 offset:4096
	ds_read_b128 v[210:213], v191 offset:6144
	ds_read_b128 v[206:209], v192 offset:4096
	ds_read_b128 v[214:217], v192 offset:6144
	global_load_lds_dwordx4 v170, s[56:57]
	s_add_i32 m0, s29, 0xe000
	s_nop 0
	global_load_lds_dwordx4 v172, s[56:57]
	s_waitcnt vmcnt(8)
	s_waitcnt lgkmcnt(0)
	s_barrier
	s_setprio 1
	s_waitcnt lgkmcnt(0)
	v_mfma_scale_f32_16x16x128_f8f6f4 v[158:161], v[18:25], v[174:181], 0, v1, v182 op_sel_hi:[0,0,0]
	v_mfma_scale_f32_16x16x128_f8f6f4 v[154:157], v[26:33], v[174:181], 0, v1, v182 op_sel_hi:[0,0,0]
	v_mfma_scale_f32_16x16x128_f8f6f4 v[150:153], v[18:25], v[194:201], 0, v1, v182 op_sel_hi:[0,0,0]
	v_mfma_scale_f32_16x16x128_f8f6f4 v[138:141], v[26:33], v[194:201], 0, v1, v182 op_sel_hi:[0,0,0]
	v_mfma_scale_f32_16x16x128_f8f6f4 v[130:133], v[18:25], v[202:209], 0, v1, v182 op_sel_hi:[0,0,0]
	v_mfma_scale_f32_16x16x128_f8f6f4 v[122:125], v[26:33], v[202:209], 0, v1, v182 op_sel_hi:[0,0,0]
	v_mfma_scale_f32_16x16x128_f8f6f4 v[118:121], v[18:25], v[210:217], 0, v1, v182 op_sel_hi:[0,0,0]
	v_mfma_scale_f32_16x16x128_f8f6f4 v[106:109], v[26:33], v[210:217], 0, v1, v182 op_sel_hi:[0,0,0]
	s_setprio 0
	s_setprio 1
	v_mfma_scale_f32_16x16x128_f8f6f4 v[146:149], v[2:9], v[174:181], 0, v1, v182 op_sel_hi:[0,0,0]
	v_mfma_scale_f32_16x16x128_f8f6f4 v[142:145], v[10:17], v[174:181], 0, v1, v182 op_sel_hi:[0,0,0]
	v_mfma_scale_f32_16x16x128_f8f6f4 v[134:137], v[2:9], v[194:201], 0, v1, v182 op_sel_hi:[0,0,0]
	v_mfma_scale_f32_16x16x128_f8f6f4 v[126:129], v[10:17], v[194:201], 0, v1, v182 op_sel_hi:[0,0,0]
	v_mfma_scale_f32_16x16x128_f8f6f4 v[114:117], v[2:9], v[202:209], 0, v1, v182 op_sel_hi:[0,0,0]
	v_mfma_scale_f32_16x16x128_f8f6f4 v[110:113], v[10:17], v[202:209], 0, v1, v182 op_sel_hi:[0,0,0]
	v_mfma_scale_f32_16x16x128_f8f6f4 v[102:105], v[2:9], v[210:217], 0, v1, v182 op_sel_hi:[0,0,0]
	v_mfma_scale_f32_16x16x128_f8f6f4 v[98:101], v[10:17], v[210:217], 0, v1, v182 op_sel_hi:[0,0,0]
	s_setprio 0
	s_barrier
	s_add_i32 s81, s71, s61
	s_mov_b32 m0, s81
	ds_read_b128 v[194:197], v191 offset:16384
	ds_read_b128 v[202:205], v191 offset:18432
	ds_read_b128 v[198:201], v192 offset:16384
	ds_read_b128 v[206:209], v192 offset:18432
	ds_read_b128 v[210:213], v191 offset:20480
	ds_read_b128 v[218:221], v191 offset:22528
	ds_read_b128 v[214:217], v192 offset:20480
	ds_read_b128 v[222:225], v192 offset:22528
	global_load_lds_dwordx4 v164, s[34:35]
	s_add_i32 m0, s81, 0x2000
	s_add_u32 s82, s34, 0x40000
	s_addc_u32 s83, s35, 0
	s_add_i32 s81, s72, s61
	global_load_lds_dwordx4 v168, s[34:35]
	s_mov_b32 m0, s81
	s_nop 0
	global_load_lds_dwordx4 v164, s[82:83]
	s_add_i32 m0, s81, 0x2000
	s_nop 0
	global_load_lds_dwordx4 v168, s[82:83]
	s_mov_b32 m0, s29
	s_nop 0
	global_load_lds_dwordx4 v162, s[58:59]
	s_mov_b32 m0, s53
	s_nop 0
	global_load_lds_dwordx4 v166, s[58:59]
	s_waitcnt vmcnt(8)
	s_waitcnt lgkmcnt(0)
	s_barrier
	s_setprio 1
	s_waitcnt lgkmcnt(0)
	v_mfma_scale_f32_16x16x128_f8f6f4 v[94:97], v[18:25], v[194:201], 0, v1, v182 op_sel_hi:[0,0,0]
	v_mfma_scale_f32_16x16x128_f8f6f4 v[90:93], v[26:33], v[194:201], 0, v1, v182 op_sel_hi:[0,0,0]
	v_mfma_scale_f32_16x16x128_f8f6f4 v[82:85], v[18:25], v[202:209], 0, v1, v182 op_sel_hi:[0,0,0]
	v_mfma_scale_f32_16x16x128_f8f6f4 v[74:77], v[26:33], v[202:209], 0, v1, v182 op_sel_hi:[0,0,0]
	v_mfma_scale_f32_16x16x128_f8f6f4 v[66:69], v[18:25], v[210:217], 0, v1, v182 op_sel_hi:[0,0,0]
	v_mfma_scale_f32_16x16x128_f8f6f4 v[58:61], v[26:33], v[210:217], 0, v1, v182 op_sel_hi:[0,0,0]
	v_mfma_scale_f32_16x16x128_f8f6f4 v[50:53], v[18:25], v[218:225], 0, v1, v182 op_sel_hi:[0,0,0]
	v_mfma_scale_f32_16x16x128_f8f6f4 v[42:45], v[26:33], v[218:225], 0, v1, v182 op_sel_hi:[0,0,0]
	s_setprio 0
	s_setprio 1
	v_mfma_scale_f32_16x16x128_f8f6f4 v[86:89], v[2:9], v[194:201], 0, v1, v182 op_sel_hi:[0,0,0]
	v_mfma_scale_f32_16x16x128_f8f6f4 v[78:81], v[10:17], v[194:201], 0, v1, v182 op_sel_hi:[0,0,0]
	v_mfma_scale_f32_16x16x128_f8f6f4 v[70:73], v[2:9], v[202:209], 0, v1, v182 op_sel_hi:[0,0,0]
	v_mfma_scale_f32_16x16x128_f8f6f4 v[62:65], v[10:17], v[202:209], 0, v1, v182 op_sel_hi:[0,0,0]
	v_mfma_scale_f32_16x16x128_f8f6f4 v[54:57], v[2:9], v[210:217], 0, v1, v182 op_sel_hi:[0,0,0]
	v_mfma_scale_f32_16x16x128_f8f6f4 v[46:49], v[10:17], v[210:217], 0, v1, v182 op_sel_hi:[0,0,0]
	v_mfma_scale_f32_16x16x128_f8f6f4 v[38:41], v[2:9], v[218:225], 0, v1, v182 op_sel_hi:[0,0,0]
	v_mfma_scale_f32_16x16x128_f8f6f4 v[34:37], v[10:17], v[218:225], 0, v1, v182 op_sel_hi:[0,0,0]
	s_setprio 0
	s_barrier
; #define PG8_STAGE(bufoff, gbase, voff) do { _Pragma("unroll") for (int _i = 0; _i < 2; ++_i) \
;         __builtin_amdgcn_global_load_lds((const unsigned*)((const char*)(gbase) + (voff)[_i]), (PG8_LAS unsigned*)(lds + (bufoff) + ldsw + _i * 8192), 16, 0, 0); } while (0)
; #define PG8_LDA(dst, b, h) do { _Pragma("unroll") for (int m = 0; m < 4; ++m) _Pragma("unroll") for (int k = 0; k < 2; ++k) dst[m][k] = *(const PG8_LAS bf16x8*)(lds + PG8_SA(b, h) + aoff + m * 2048 + k * 1024); } while (0)
; #define PG8_LDB(dst, b, h) do { _Pragma("unroll") for (int n = 0; n < 2; ++n) _Pragma("unroll") for (int k = 0; k < 2; ++k) dst[n][k] = *(const PG8_LAS bf16x8*)(lds + PG8_SB(b, h) + boff + n * 2048 + k * 1024); } while (0)
; #define PG8_MMA(ai, bj, At, Bt) do { __builtin_amdgcn_s_setprio(1); _Pragma("unroll") for (int m = 0; m < 4; ++m) _Pragma("unroll") for (int n = 0; n < 2; ++n) _Pragma("unroll") for (int k = 0; k < 2; ++k) \
;         acc[ai][bj][m][n] = __builtin_amdgcn_mfma_f32_16x16x32_bf16(Bt[n][k], At[m][k], acc[ai][bj][m][n], 0, 0, 0); __builtin_amdgcn_s_setprio(0); } while (0)
; #define PG8_WAIT_V(n) asm volatile("s_waitcnt vmcnt(" #n ")" ::: "memory")
; #define PG8_WAIT_L(n) asm volatile("s_waitcnt lgkmcnt(" #n ")" ::: "memory")
; #define PG8_BAR __builtin_amdgcn_s_barrier()
; #define PG8_SCHED __builtin_amdgcn_sched_barrier(0)
; #define PG8_STAGE(bufoff, gbase, voff) do { _Pragma("unroll") for (int _i = 0; _i < 2; ++_i) \
;         __builtin_amdgcn_global_load_lds((const unsigned*)((const char*)(gbase) + (voff)[_i]), (PG8_LAS unsigned*)(lds + (bufoff) + ldsw + _i * 8192), 16, 0, 0); } while (0)
; #define PG8_WAIT_V(n) asm volatile("s_waitcnt vmcnt(" #n ")" ::: "memory")
; template <class Epi, class Sched, bool ALIGN_EPI = false>
; __device__ __forceinline__ void gemm_phase8(PG8_LAS unsigned char* lds, const Gemm g, const Sched& S, const Epi& E) {
;     ...
;             PG8_LDB(B0, 1, 0); PG8_LDB(B1, 1, 1); PG8_SCHED; PG8_LDA(At, 1, 0); PG8_STAGE(PG8_SA(0, 1), a2 + hstepA, voffA);
;             PG8_WAIT_V(8); PG8_WAIT_L(0); PG8_BAR; PG8_MMA(0, 0, At, B0); PG8_MMA(0, 1, At, B1); PG8_BAR; PG8_SCHED;
;             PG8_LDA(At, 1, 1); PG8_STAGE(PG8_SB(1, 0), b3, voffB); PG8_STAGE(PG8_SB(1, 1), b3 + hstepB, voffB); PG8_STAGE(PG8_SA(1, 0), a3, voffA);
;             PG8_WAIT_V(8); PG8_WAIT_L(0); PG8_BAR; PG8_MMA(1, 0, At, B0); PG8_MMA(1, 1, At, B1); PG8_BAR; PG8_SCHED;
	s_add_i32 s81, 0, 0x18000
	s_add_i32 s82, 0, 0x1c000
	v_add_u32_e32 v6, s81, v184
	v_add_u32_e32 v14, s81, v185
	v_add_u32_e32 v22, s82, v184
	v_add_u32_e32 v30, s82, v185
	ds_read_b128 v[2:5], v6
	ds_read_b128 v[10:13], v6 offset:2048
	ds_read_b128 v[6:9], v14
	ds_read_b128 v[14:17], v14 offset:2048
	ds_read_b128 v[18:21], v22
	ds_read_b128 v[26:29], v22 offset:2048
	ds_read_b128 v[22:25], v30
	ds_read_b128 v[30:33], v30 offset:2048
	s_add_u32 s58, s58, 0x40000
	s_addc_u32 s59, s59, 0
	s_mov_b32 m0, s62
	ds_read_b128 v[194:197], v191 offset:32768
	ds_read_b128 v[202:205], v191 offset:34816
	ds_read_b128 v[198:201], v192 offset:32768
	ds_read_b128 v[206:209], v192 offset:34816
	ds_read_b128 v[210:213], v191 offset:36864
	ds_read_b128 v[218:221], v191 offset:38912
	ds_read_b128 v[214:217], v192 offset:36864
	ds_read_b128 v[222:225], v192 offset:38912
	global_load_lds_dwordx4 v162, s[58:59]
	s_mov_b32 m0, s63
	s_nop 0
	global_load_lds_dwordx4 v166, s[58:59]
	s_waitcnt vmcnt(8)
	s_waitcnt lgkmcnt(0)
	s_barrier
	s_setprio 1
	s_waitcnt lgkmcnt(0)
	v_mfma_scale_f32_16x16x128_f8f6f4 v[158:161], v[2:9], v[194:201], v[158:161], v1, v182 op_sel_hi:[0,0,0]
	v_mfma_scale_f32_16x16x128_f8f6f4 v[154:157], v[10:17], v[194:201], v[154:157], v1, v182 op_sel_hi:[0,0,0]
	v_mfma_scale_f32_16x16x128_f8f6f4 v[150:153], v[2:9], v[202:209], v[150:153], v1, v182 op_sel_hi:[0,0,0]
	v_mfma_scale_f32_16x16x128_f8f6f4 v[138:141], v[10:17], v[202:209], v[138:141], v1, v182 op_sel_hi:[0,0,0]
	v_mfma_scale_f32_16x16x128_f8f6f4 v[130:133], v[2:9], v[210:217], v[130:133], v1, v182 op_sel_hi:[0,0,0]
	v_mfma_scale_f32_16x16x128_f8f6f4 v[122:125], v[10:17], v[210:217], v[122:125], v1, v182 op_sel_hi:[0,0,0]
	v_mfma_scale_f32_16x16x128_f8f6f4 v[118:121], v[2:9], v[218:225], v[118:121], v1, v182 op_sel_hi:[0,0,0]
	v_mfma_scale_f32_16x16x128_f8f6f4 v[106:109], v[10:17], v[218:225], v[106:109], v1, v182 op_sel_hi:[0,0,0]
	s_setprio 0
	s_setprio 1
	v_mfma_scale_f32_16x16x128_f8f6f4 v[146:149], v[18:25], v[194:201], v[146:149], v1, v182 op_sel_hi:[0,0,0]
	v_mfma_scale_f32_16x16x128_f8f6f4 v[142:145], v[26:33], v[194:201], v[142:145], v1, v182 op_sel_hi:[0,0,0]
	v_mfma_scale_f32_16x16x128_f8f6f4 v[134:137], v[18:25], v[202:209], v[134:137], v1, v182 op_sel_hi:[0,0,0]
	v_mfma_scale_f32_16x16x128_f8f6f4 v[126:129], v[26:33], v[202:209], v[126:129], v1, v182 op_sel_hi:[0,0,0]
	v_mfma_scale_f32_16x16x128_f8f6f4 v[114:117], v[18:25], v[210:217], v[114:117], v1, v182 op_sel_hi:[0,0,0]
	v_mfma_scale_f32_16x16x128_f8f6f4 v[110:113], v[26:33], v[210:217], v[110:113], v1, v182 op_sel_hi:[0,0,0]
	v_mfma_scale_f32_16x16x128_f8f6f4 v[102:105], v[18:25], v[218:225], v[102:105], v1, v182 op_sel_hi:[0,0,0]
	v_mfma_scale_f32_16x16x128_f8f6f4 v[98:101], v[26:33], v[218:225], v[98:101], v1, v182 op_sel_hi:[0,0,0]
	s_setprio 0
	s_barrier
	s_add_i32 s101, s81, s61
	s_add_u32 s98, s34, s10
	s_addc_u32 s99, s35, s11
	s_mov_b32 m0, s101
	ds_read_b128 v[194:197], v191 offset:49152
	ds_read_b128 v[202:205], v191 offset:51200
	ds_read_b128 v[198:201], v192 offset:49152
	ds_read_b128 v[206:209], v192 offset:51200
	ds_read_b128 v[210:213], v191 offset:53248
	ds_read_b128 v[218:221], v191 offset:55296
	ds_read_b128 v[214:217], v192 offset:53248
	ds_read_b128 v[222:225], v192 offset:55296
	global_load_lds_dwordx4 v164, s[98:99]
	s_add_i32 m0, s101, 0x2000
	s_add_u32 s34, s34, 0x40080
	s_addc_u32 s35, s35, 0
	s_add_i32 s101, s82, s61
	global_load_lds_dwordx4 v168, s[98:99]
	s_add_u32 s98, s58, s10
	s_addc_u32 s99, s59, s11
	s_sub_u32 s98, s98, 0x40000
	s_subb_u32 s99, s99, 0
	s_mov_b32 m0, s101
	s_nop 0
	global_load_lds_dwordx4 v164, s[34:35]
	s_add_i32 m0, s101, 0x2000
	s_nop 0
	global_load_lds_dwordx4 v168, s[34:35]
	s_mov_b32 m0, s69
	s_nop 0
	global_load_lds_dwordx4 v162, s[98:99]
	s_mov_b32 m0, s70
	s_nop 0
	global_load_lds_dwordx4 v166, s[98:99]
	s_waitcnt vmcnt(8)
	s_waitcnt lgkmcnt(0)
	s_barrier
	s_setprio 1
	s_waitcnt lgkmcnt(0)
	v_mfma_scale_f32_16x16x128_f8f6f4 v[94:97], v[2:9], v[194:201], v[94:97], v1, v182 op_sel_hi:[0,0,0]
	v_mfma_scale_f32_16x16x128_f8f6f4 v[90:93], v[10:17], v[194:201], v[90:93], v1, v182 op_sel_hi:[0,0,0]
	v_mfma_scale_f32_16x16x128_f8f6f4 v[82:85], v[2:9], v[202:209], v[82:85], v1, v182 op_sel_hi:[0,0,0]
	v_mfma_scale_f32_16x16x128_f8f6f4 v[74:77], v[10:17], v[202:209], v[74:77], v1, v182 op_sel_hi:[0,0,0]
	v_mfma_scale_f32_16x16x128_f8f6f4 v[66:69], v[2:9], v[210:217], v[66:69], v1, v182 op_sel_hi:[0,0,0]
	v_mfma_scale_f32_16x16x128_f8f6f4 v[58:61], v[10:17], v[210:217], v[58:61], v1, v182 op_sel_hi:[0,0,0]
	v_mfma_scale_f32_16x16x128_f8f6f4 v[50:53], v[2:9], v[218:225], v[50:53], v1, v182 op_sel_hi:[0,0,0]
	v_mfma_scale_f32_16x16x128_f8f6f4 v[42:45], v[10:17], v[218:225], v[42:45], v1, v182 op_sel_hi:[0,0,0]
	s_setprio 0
	s_setprio 1
	v_mfma_scale_f32_16x16x128_f8f6f4 v[86:89], v[18:25], v[194:201], v[86:89], v1, v182 op_sel_hi:[0,0,0]
	v_mfma_scale_f32_16x16x128_f8f6f4 v[78:81], v[26:33], v[194:201], v[78:81], v1, v182 op_sel_hi:[0,0,0]
	v_mfma_scale_f32_16x16x128_f8f6f4 v[70:73], v[18:25], v[202:209], v[70:73], v1, v182 op_sel_hi:[0,0,0]
	v_mfma_scale_f32_16x16x128_f8f6f4 v[62:65], v[26:33], v[202:209], v[62:65], v1, v182 op_sel_hi:[0,0,0]
	v_mfma_scale_f32_16x16x128_f8f6f4 v[54:57], v[18:25], v[210:217], v[54:57], v1, v182 op_sel_hi:[0,0,0]
	v_mfma_scale_f32_16x16x128_f8f6f4 v[46:49], v[26:33], v[210:217], v[46:49], v1, v182 op_sel_hi:[0,0,0]
	v_mfma_scale_f32_16x16x128_f8f6f4 v[38:41], v[18:25], v[218:225], v[38:41], v1, v182 op_sel_hi:[0,0,0]
	v_mfma_scale_f32_16x16x128_f8f6f4 v[34:37], v[26:33], v[218:225], v[34:37], v1, v182 op_sel_hi:[0,0,0]
	s_setprio 0
	s_barrier
	s_add_u32 s56, s56, 0x100
	s_addc_u32 s57, s57, 0
	s_add_u32 s78, s78, 0x100
	s_addc_u32 s79, s79, 0
	s_cmp_ge_u32 s80, s76
	s_mov_b32 s58, s80
; #define PG8_STAGE(bufoff, gbase, voff) do { _Pragma("unroll") for (int _i = 0; _i < 2; ++_i) \
;         __builtin_amdgcn_global_load_lds((const unsigned*)((const char*)(gbase) + (voff)[_i]), (PG8_LAS unsigned*)(lds + (bufoff) + ldsw + _i * 8192), 16, 0, 0); } while (0)
; #define PG8_LDA(dst, b, h) do { _Pragma("unroll") for (int m = 0; m < 4; ++m) _Pragma("unroll") for (int k = 0; k < 2; ++k) dst[m][k] = *(const PG8_LAS bf16x8*)(lds + PG8_SA(b, h) + aoff + m * 2048 + k * 1024); } while (0)
; #define PG8_LDB(dst, b, h) do { _Pragma("unroll") for (int n = 0; n < 2; ++n) _Pragma("unroll") for (int k = 0; k < 2; ++k) dst[n][k] = *(const PG8_LAS bf16x8*)(lds + PG8_SB(b, h) + boff + n * 2048 + k * 1024); } while (0)
; #define PG8_MMA(ai, bj, At, Bt) do { __builtin_amdgcn_s_setprio(1); _Pragma("unroll") for (int m = 0; m < 4; ++m) _Pragma("unroll") for (int n = 0; n < 2; ++n) _Pragma("unroll") for (int k = 0; k < 2; ++k) \
;         acc[ai][bj][m][n] = __builtin_amdgcn_mfma_f32_16x16x32_bf16(Bt[n][k], At[m][k], acc[ai][bj][m][n], 0, 0, 0); __builtin_amdgcn_s_setprio(0); } while (0)
; #define PG8_WAIT_V(n) asm volatile("s_waitcnt vmcnt(" #n ")" ::: "memory")
; #define PG8_WAIT_L(n) asm volatile("s_waitcnt lgkmcnt(" #n ")" ::: "memory")
; #define PG8_BAR __builtin_amdgcn_s_barrier()
; #define PG8_SCHED __builtin_amdgcn_sched_barrier(0)
; #define PG8_STAGE(bufoff, gbase, voff) do { _Pragma("unroll") for (int _i = 0; _i < 2; ++_i) \
;         __builtin_amdgcn_global_load_lds((const unsigned*)((const char*)(gbase) + (voff)[_i]), (PG8_LAS unsigned*)(lds + (bufoff) + ldsw + _i * 8192), 16, 0, 0); } while (0)
; #define PG8_WAIT_V(n) asm volatile("s_waitcnt vmcnt(" #n ")" ::: "memory")
; template <class Epi, class Sched, bool ALIGN_EPI = false>
; __device__ __forceinline__ void gemm_phase8(PG8_LAS unsigned char* lds, const Gemm g, const Sched& S, const Epi& E) {
;     ...
;             PG8_LDB(B0, 0, 0); PG8_LDB(B1, 0, 1); PG8_SCHED; PG8_LDA(At, 0, 0); PG8_STAGE(PG8_SA(1, 1), a1 + hstepA, voffA);
;             PG8_WAIT_V(8); PG8_WAIT_L(0); PG8_BAR; PG8_MMA(0, 0, At, B0); PG8_MMA(0, 1, At, B1); PG8_BAR; PG8_SCHED;
;             PG8_LDA(At, 0, 1); PG8_STAGE(PG8_SB(0, 0), b2, voffB); PG8_STAGE(PG8_SB(0, 1), b2 + hstepB, voffB); PG8_STAGE(PG8_SA(0, 0), a2, voffA);
;             PG8_WAIT_V(8); PG8_WAIT_L(0); PG8_BAR; PG8_MMA(1, 0, At, B0); PG8_MMA(1, 1, At, B1); PG8_BAR; PG8_SCHED;
.LBB0_1187:
	ds_read_b128 v[18:21], v187
	ds_read_b128 v[26:29], v187 offset:2048
	ds_read_b128 v[22:25], v188
	ds_read_b128 v[30:33], v188 offset:2048
	ds_read_b128 v[2:5], v189
	ds_read_b128 v[10:13], v189 offset:2048
	ds_read_b128 v[6:9], v190
	ds_read_b128 v[14:17], v190 offset:2048
	s_add_i32 s80, s58, 2
	s_add_u32 s34, s56, 0xfffc0080
	s_addc_u32 s35, s57, -1
	s_cmp_eq_u32 s77, s58
	s_cselect_b32 s58, s31, s34
	s_cselect_b32 s59, s19, s35
	s_cselect_b32 s35, s21, s79
	s_cselect_b32 s34, s75, s78
	s_add_i32 m0, s29, 0xc000
	ds_read_b128 v[174:177], v191
	ds_read_b128 v[194:197], v191 offset:2048
	ds_read_b128 v[178:181], v192
	ds_read_b128 v[198:201], v192 offset:2048
	ds_read_b128 v[202:205], v191 offset:4096
	ds_read_b128 v[210:213], v191 offset:6144
	ds_read_b128 v[206:209], v192 offset:4096
	ds_read_b128 v[214:217], v192 offset:6144
	global_load_lds_dwordx4 v170, s[56:57]
	s_add_i32 m0, s29, 0xe000
	s_nop 0
	global_load_lds_dwordx4 v172, s[56:57]
	s_waitcnt vmcnt(8)
	s_waitcnt lgkmcnt(0)
	s_barrier
	s_setprio 1
	s_waitcnt lgkmcnt(0)
	v_mfma_scale_f32_16x16x128_f8f6f4 v[158:161], v[18:25], v[174:181], v[158:161], v1, v182 op_sel_hi:[0,0,0]
	v_mfma_scale_f32_16x16x128_f8f6f4 v[154:157], v[26:33], v[174:181], v[154:157], v1, v182 op_sel_hi:[0,0,0]
	v_mfma_scale_f32_16x16x128_f8f6f4 v[150:153], v[18:25], v[194:201], v[150:153], v1, v182 op_sel_hi:[0,0,0]
	v_mfma_scale_f32_16x16x128_f8f6f4 v[138:141], v[26:33], v[194:201], v[138:141], v1, v182 op_sel_hi:[0,0,0]
	v_mfma_scale_f32_16x16x128_f8f6f4 v[130:133], v[18:25], v[202:209], v[130:133], v1, v182 op_sel_hi:[0,0,0]
	v_mfma_scale_f32_16x16x128_f8f6f4 v[122:125], v[26:33], v[202:209], v[122:125], v1, v182 op_sel_hi:[0,0,0]
	v_mfma_scale_f32_16x16x128_f8f6f4 v[118:121], v[18:25], v[210:217], v[118:121], v1, v182 op_sel_hi:[0,0,0]
	v_mfma_scale_f32_16x16x128_f8f6f4 v[106:109], v[26:33], v[210:217], v[106:109], v1, v182 op_sel_hi:[0,0,0]
	s_setprio 0
	s_setprio 1
	v_mfma_scale_f32_16x16x128_f8f6f4 v[146:149], v[2:9], v[174:181], v[146:149], v1, v182 op_sel_hi:[0,0,0]
	v_mfma_scale_f32_16x16x128_f8f6f4 v[142:145], v[10:17], v[174:181], v[142:145], v1, v182 op_sel_hi:[0,0,0]
	v_mfma_scale_f32_16x16x128_f8f6f4 v[134:137], v[2:9], v[194:201], v[134:137], v1, v182 op_sel_hi:[0,0,0]
	v_mfma_scale_f32_16x16x128_f8f6f4 v[126:129], v[10:17], v[194:201], v[126:129], v1, v182 op_sel_hi:[0,0,0]
	v_mfma_scale_f32_16x16x128_f8f6f4 v[114:117], v[2:9], v[202:209], v[114:117], v1, v182 op_sel_hi:[0,0,0]
	v_mfma_scale_f32_16x16x128_f8f6f4 v[110:113], v[10:17], v[202:209], v[110:113], v1, v182 op_sel_hi:[0,0,0]
	v_mfma_scale_f32_16x16x128_f8f6f4 v[102:105], v[2:9], v[210:217], v[102:105], v1, v182 op_sel_hi:[0,0,0]
	v_mfma_scale_f32_16x16x128_f8f6f4 v[98:101], v[10:17], v[210:217], v[98:101], v1, v182 op_sel_hi:[0,0,0]
	s_setprio 0
	s_barrier
	s_add_i32 s81, s71, s61
	s_mov_b32 m0, s81
	ds_read_b128 v[194:197], v191 offset:16384
	ds_read_b128 v[202:205], v191 offset:18432
	ds_read_b128 v[198:201], v192 offset:16384
	ds_read_b128 v[206:209], v192 offset:18432
	ds_read_b128 v[210:213], v191 offset:20480
	ds_read_b128 v[218:221], v191 offset:22528
	ds_read_b128 v[214:217], v192 offset:20480
	ds_read_b128 v[222:225], v192 offset:22528
	global_load_lds_dwordx4 v164, s[34:35]
	s_add_i32 m0, s81, 0x2000
	s_add_u32 s82, s34, 0x40000
	s_addc_u32 s83, s35, 0
	s_add_i32 s81, s72, s61
	global_load_lds_dwordx4 v168, s[34:35]
	s_mov_b32 m0, s81
	s_nop 0
	global_load_lds_dwordx4 v164, s[82:83]
	s_add_i32 m0, s81, 0x2000
	s_nop 0
	global_load_lds_dwordx4 v168, s[82:83]
	s_mov_b32 m0, s29
	s_nop 0
	global_load_lds_dwordx4 v162, s[58:59]
	s_mov_b32 m0, s53
	s_nop 0
	global_load_lds_dwordx4 v166, s[58:59]
	s_waitcnt vmcnt(8)
	s_waitcnt lgkmcnt(0)
	s_barrier
	s_setprio 1
	s_waitcnt lgkmcnt(0)
	v_mfma_scale_f32_16x16x128_f8f6f4 v[94:97], v[18:25], v[194:201], v[94:97], v1, v182 op_sel_hi:[0,0,0]
	v_mfma_scale_f32_16x16x128_f8f6f4 v[90:93], v[26:33], v[194:201], v[90:93], v1, v182 op_sel_hi:[0,0,0]
	v_mfma_scale_f32_16x16x128_f8f6f4 v[82:85], v[18:25], v[202:209], v[82:85], v1, v182 op_sel_hi:[0,0,0]
	v_mfma_scale_f32_16x16x128_f8f6f4 v[74:77], v[26:33], v[202:209], v[74:77], v1, v182 op_sel_hi:[0,0,0]
	v_mfma_scale_f32_16x16x128_f8f6f4 v[66:69], v[18:25], v[210:217], v[66:69], v1, v182 op_sel_hi:[0,0,0]
	v_mfma_scale_f32_16x16x128_f8f6f4 v[58:61], v[26:33], v[210:217], v[58:61], v1, v182 op_sel_hi:[0,0,0]
	v_mfma_scale_f32_16x16x128_f8f6f4 v[50:53], v[18:25], v[218:225], v[50:53], v1, v182 op_sel_hi:[0,0,0]
	v_mfma_scale_f32_16x16x128_f8f6f4 v[42:45], v[26:33], v[218:225], v[42:45], v1, v182 op_sel_hi:[0,0,0]
	s_setprio 0
	s_setprio 1
	v_mfma_scale_f32_16x16x128_f8f6f4 v[86:89], v[2:9], v[194:201], v[86:89], v1, v182 op_sel_hi:[0,0,0]
	v_mfma_scale_f32_16x16x128_f8f6f4 v[78:81], v[10:17], v[194:201], v[78:81], v1, v182 op_sel_hi:[0,0,0]
	v_mfma_scale_f32_16x16x128_f8f6f4 v[70:73], v[2:9], v[202:209], v[70:73], v1, v182 op_sel_hi:[0,0,0]
	v_mfma_scale_f32_16x16x128_f8f6f4 v[62:65], v[10:17], v[202:209], v[62:65], v1, v182 op_sel_hi:[0,0,0]
	v_mfma_scale_f32_16x16x128_f8f6f4 v[54:57], v[2:9], v[210:217], v[54:57], v1, v182 op_sel_hi:[0,0,0]
	v_mfma_scale_f32_16x16x128_f8f6f4 v[46:49], v[10:17], v[210:217], v[46:49], v1, v182 op_sel_hi:[0,0,0]
	v_mfma_scale_f32_16x16x128_f8f6f4 v[38:41], v[2:9], v[218:225], v[38:41], v1, v182 op_sel_hi:[0,0,0]
	v_mfma_scale_f32_16x16x128_f8f6f4 v[34:37], v[10:17], v[218:225], v[34:37], v1, v182 op_sel_hi:[0,0,0]
	s_setprio 0
	s_barrier
; #define PG8_STAGE(bufoff, gbase, voff) do { _Pragma("unroll") for (int _i = 0; _i < 2; ++_i) \
;         __builtin_amdgcn_global_load_lds((const unsigned*)((const char*)(gbase) + (voff)[_i]), (PG8_LAS unsigned*)(lds + (bufoff) + ldsw + _i * 8192), 16, 0, 0); } while (0)
; #define PG8_LDA(dst, b, h) do { _Pragma("unroll") for (int m = 0; m < 4; ++m) _Pragma("unroll") for (int k = 0; k < 2; ++k) dst[m][k] = *(const PG8_LAS bf16x8*)(lds + PG8_SA(b, h) + aoff + m * 2048 + k * 1024); } while (0)
; #define PG8_LDB(dst, b, h) do { _Pragma("unroll") for (int n = 0; n < 2; ++n) _Pragma("unroll") for (int k = 0; k < 2; ++k) dst[n][k] = *(const PG8_LAS bf16x8*)(lds + PG8_SB(b, h) + boff + n * 2048 + k * 1024); } while (0)
; #define PG8_MMA(ai, bj, At, Bt) do { __builtin_amdgcn_s_setprio(1); _Pragma("unroll") for (int m = 0; m < 4; ++m) _Pragma("unroll") for (int n = 0; n < 2; ++n) _Pragma("unroll") for (int k = 0; k < 2; ++k) \
;         acc[ai][bj][m][n] = __builtin_amdgcn_mfma_f32_16x16x32_bf16(Bt[n][k], At[m][k], acc[ai][bj][m][n], 0, 0, 0); __builtin_amdgcn_s_setprio(0); } while (0)
; #define PG8_WAIT_V(n) asm volatile("s_waitcnt vmcnt(" #n ")" ::: "memory")
; #define PG8_WAIT_L(n) asm volatile("s_waitcnt lgkmcnt(" #n ")" ::: "memory")
; #define PG8_BAR __builtin_amdgcn_s_barrier()
; #define PG8_SCHED __builtin_amdgcn_sched_barrier(0)
; #define PG8_STAGE(bufoff, gbase, voff) do { _Pragma("unroll") for (int _i = 0; _i < 2; ++_i) \
;         __builtin_amdgcn_global_load_lds((const unsigned*)((const char*)(gbase) + (voff)[_i]), (PG8_LAS unsigned*)(lds + (bufoff) + ldsw + _i * 8192), 16, 0, 0); } while (0)
; #define PG8_BAR __builtin_amdgcn_s_barrier()
; template <class Epi, class Sched, bool ALIGN_EPI = false>
; __device__ __forceinline__ void gemm_phase8(PG8_LAS unsigned char* lds, const Gemm g, const Sched& S, const Epi& E) {
;     ...
;             PG8_LDB(B0, 1, 0); PG8_LDB(B1, 1, 1); PG8_SCHED; PG8_LDA(At, 1, 0); PG8_STAGE(PG8_SA(0, 1), a2 + hstepA, voffA);
;             PG8_WAIT_V(8); PG8_WAIT_L(0); PG8_BAR; PG8_MMA(0, 0, At, B0); PG8_MMA(0, 1, At, B1); PG8_BAR; PG8_SCHED;
;             PG8_LDA(At, 1, 1); PG8_STAGE(PG8_SB(1, 0), b3, voffB); PG8_STAGE(PG8_SB(1, 1), b3 + hstepB, voffB); PG8_STAGE(PG8_SA(1, 0), a3, voffA);
;             PG8_WAIT_V(8); PG8_WAIT_L(0); PG8_BAR; PG8_MMA(1, 0, At, B0); PG8_MMA(1, 1, At, B1); PG8_BAR; PG8_SCHED;
;         }
	s_add_i32 s81, 0, 0x18000
	s_add_i32 s82, 0, 0x1c000
	v_add_u32_e32 v6, s81, v184
	v_add_u32_e32 v14, s81, v185
	v_add_u32_e32 v22, s82, v184
	v_add_u32_e32 v30, s82, v185
	ds_read_b128 v[2:5], v6
	ds_read_b128 v[10:13], v6 offset:2048
	ds_read_b128 v[6:9], v14
	ds_read_b128 v[14:17], v14 offset:2048
	ds_read_b128 v[18:21], v22
	ds_read_b128 v[26:29], v22 offset:2048
	ds_read_b128 v[22:25], v30
	ds_read_b128 v[30:33], v30 offset:2048
	s_add_u32 s58, s58, 0x40000
	s_addc_u32 s59, s59, 0
	s_mov_b32 m0, s62
	ds_read_b128 v[194:197], v191 offset:32768
	ds_read_b128 v[202:205], v191 offset:34816
	ds_read_b128 v[198:201], v192 offset:32768
	ds_read_b128 v[206:209], v192 offset:34816
	ds_read_b128 v[210:213], v191 offset:36864
	ds_read_b128 v[218:221], v191 offset:38912
	ds_read_b128 v[214:217], v192 offset:36864
	ds_read_b128 v[222:225], v192 offset:38912
	global_load_lds_dwordx4 v162, s[58:59]
	s_mov_b32 m0, s63
	s_nop 0
	global_load_lds_dwordx4 v166, s[58:59]
	s_waitcnt vmcnt(8)
	s_waitcnt lgkmcnt(0)
	s_barrier
	s_setprio 1
	s_waitcnt lgkmcnt(0)
	v_mfma_scale_f32_16x16x128_f8f6f4 v[158:161], v[2:9], v[194:201], v[158:161], v1, v182 op_sel_hi:[0,0,0]
	v_mfma_scale_f32_16x16x128_f8f6f4 v[154:157], v[10:17], v[194:201], v[154:157], v1, v182 op_sel_hi:[0,0,0]
	v_mfma_scale_f32_16x16x128_f8f6f4 v[150:153], v[2:9], v[202:209], v[150:153], v1, v182 op_sel_hi:[0,0,0]
	v_mfma_scale_f32_16x16x128_f8f6f4 v[138:141], v[10:17], v[202:209], v[138:141], v1, v182 op_sel_hi:[0,0,0]
	v_mfma_scale_f32_16x16x128_f8f6f4 v[130:133], v[2:9], v[210:217], v[130:133], v1, v182 op_sel_hi:[0,0,0]
	v_mfma_scale_f32_16x16x128_f8f6f4 v[122:125], v[10:17], v[210:217], v[122:125], v1, v182 op_sel_hi:[0,0,0]
	v_mfma_scale_f32_16x16x128_f8f6f4 v[118:121], v[2:9], v[218:225], v[118:121], v1, v182 op_sel_hi:[0,0,0]
	v_mfma_scale_f32_16x16x128_f8f6f4 v[106:109], v[10:17], v[218:225], v[106:109], v1, v182 op_sel_hi:[0,0,0]
	s_setprio 0
	s_setprio 1
	v_mfma_scale_f32_16x16x128_f8f6f4 v[146:149], v[18:25], v[194:201], v[146:149], v1, v182 op_sel_hi:[0,0,0]
	v_mfma_scale_f32_16x16x128_f8f6f4 v[142:145], v[26:33], v[194:201], v[142:145], v1, v182 op_sel_hi:[0,0,0]
	v_mfma_scale_f32_16x16x128_f8f6f4 v[134:137], v[18:25], v[202:209], v[134:137], v1, v182 op_sel_hi:[0,0,0]
	v_mfma_scale_f32_16x16x128_f8f6f4 v[126:129], v[26:33], v[202:209], v[126:129], v1, v182 op_sel_hi:[0,0,0]
	v_mfma_scale_f32_16x16x128_f8f6f4 v[114:117], v[18:25], v[210:217], v[114:117], v1, v182 op_sel_hi:[0,0,0]
	v_mfma_scale_f32_16x16x128_f8f6f4 v[110:113], v[26:33], v[210:217], v[110:113], v1, v182 op_sel_hi:[0,0,0]
	v_mfma_scale_f32_16x16x128_f8f6f4 v[102:105], v[18:25], v[218:225], v[102:105], v1, v182 op_sel_hi:[0,0,0]
	v_mfma_scale_f32_16x16x128_f8f6f4 v[98:101], v[26:33], v[218:225], v[98:101], v1, v182 op_sel_hi:[0,0,0]
	s_setprio 0
	s_barrier
	s_add_i32 s101, s81, s61
	s_add_u32 s98, s34, s10
	s_addc_u32 s99, s35, s11
	s_mov_b32 m0, s101
	ds_read_b128 v[194:197], v191 offset:49152
	ds_read_b128 v[202:205], v191 offset:51200
	ds_read_b128 v[198:201], v192 offset:49152
	ds_read_b128 v[206:209], v192 offset:51200
	ds_read_b128 v[210:213], v191 offset:53248
	ds_read_b128 v[218:221], v191 offset:55296
	ds_read_b128 v[214:217], v192 offset:53248
	ds_read_b128 v[222:225], v192 offset:55296
	global_load_lds_dwordx4 v164, s[98:99]
	s_add_i32 m0, s101, 0x2000
	s_add_u32 s34, s34, 0x40080
	s_addc_u32 s35, s35, 0
	s_add_i32 s101, s82, s61
	global_load_lds_dwordx4 v168, s[98:99]
	s_add_u32 s98, s58, s10
	s_addc_u32 s99, s59, s11
	s_sub_u32 s98, s98, 0x40000
	s_subb_u32 s99, s99, 0
	s_mov_b32 m0, s101
	s_nop 0
	global_load_lds_dwordx4 v164, s[34:35]
	s_add_i32 m0, s101, 0x2000
	s_nop 0
	global_load_lds_dwordx4 v168, s[34:35]
	s_mov_b32 m0, s69
	s_nop 0
	global_load_lds_dwordx4 v162, s[98:99]
	s_mov_b32 m0, s70
	s_nop 0
	global_load_lds_dwordx4 v166, s[98:99]
	s_waitcnt vmcnt(8)
	s_waitcnt lgkmcnt(0)
	s_barrier
	s_setprio 1
	s_waitcnt lgkmcnt(0)
	v_mfma_scale_f32_16x16x128_f8f6f4 v[94:97], v[2:9], v[194:201], v[94:97], v1, v182 op_sel_hi:[0,0,0]
	v_mfma_scale_f32_16x16x128_f8f6f4 v[90:93], v[10:17], v[194:201], v[90:93], v1, v182 op_sel_hi:[0,0,0]
	v_mfma_scale_f32_16x16x128_f8f6f4 v[82:85], v[2:9], v[202:209], v[82:85], v1, v182 op_sel_hi:[0,0,0]
	v_mfma_scale_f32_16x16x128_f8f6f4 v[74:77], v[10:17], v[202:209], v[74:77], v1, v182 op_sel_hi:[0,0,0]
	v_mfma_scale_f32_16x16x128_f8f6f4 v[66:69], v[2:9], v[210:217], v[66:69], v1, v182 op_sel_hi:[0,0,0]
	v_mfma_scale_f32_16x16x128_f8f6f4 v[58:61], v[10:17], v[210:217], v[58:61], v1, v182 op_sel_hi:[0,0,0]
	v_mfma_scale_f32_16x16x128_f8f6f4 v[50:53], v[2:9], v[218:225], v[50:53], v1, v182 op_sel_hi:[0,0,0]
	v_mfma_scale_f32_16x16x128_f8f6f4 v[42:45], v[10:17], v[218:225], v[42:45], v1, v182 op_sel_hi:[0,0,0]
	s_setprio 0
	s_setprio 1
	v_mfma_scale_f32_16x16x128_f8f6f4 v[86:89], v[18:25], v[194:201], v[86:89], v1, v182 op_sel_hi:[0,0,0]
	v_mfma_scale_f32_16x16x128_f8f6f4 v[78:81], v[26:33], v[194:201], v[78:81], v1, v182 op_sel_hi:[0,0,0]
	v_mfma_scale_f32_16x16x128_f8f6f4 v[70:73], v[18:25], v[202:209], v[70:73], v1, v182 op_sel_hi:[0,0,0]
	v_mfma_scale_f32_16x16x128_f8f6f4 v[62:65], v[26:33], v[202:209], v[62:65], v1, v182 op_sel_hi:[0,0,0]
	v_mfma_scale_f32_16x16x128_f8f6f4 v[54:57], v[18:25], v[210:217], v[54:57], v1, v182 op_sel_hi:[0,0,0]
	v_mfma_scale_f32_16x16x128_f8f6f4 v[46:49], v[26:33], v[210:217], v[46:49], v1, v182 op_sel_hi:[0,0,0]
	v_mfma_scale_f32_16x16x128_f8f6f4 v[38:41], v[18:25], v[218:225], v[38:41], v1, v182 op_sel_hi:[0,0,0]
	v_mfma_scale_f32_16x16x128_f8f6f4 v[34:37], v[26:33], v[218:225], v[34:37], v1, v182 op_sel_hi:[0,0,0]
	s_setprio 0
	s_barrier
	s_add_u32 s56, s56, 0x100
	s_addc_u32 s57, s57, 0
	s_add_u32 s78, s78, 0x100
	s_addc_u32 s79, s79, 0
	s_cmp_ge_u32 s80, s76
	s_mov_b32 s58, s80
	s_cbranch_scc0 .LBB0_1187
	s_and_b64 vcc, exec, s[12:13]
	s_cbranch_vccz .LBB0_1190
	s_barrier

; #define PG8_STAGE(bufoff, gbase, voff) do { _Pragma("unroll") for (int _i = 0; _i < 2; ++_i) \
;         __builtin_amdgcn_global_load_lds((const unsigned*)((const char*)(gbase) + (voff)[_i]), (PG8_LAS unsigned*)(lds + (bufoff) + ldsw + _i * 8192), 16, 0, 0); } while (0)
; #define PG8_LDA(dst, b, h) do { _Pragma("unroll") for (int m = 0; m < 4; ++m) _Pragma("unroll") for (int k = 0; k < 2; ++k) dst[m][k] = *(const PG8_LAS bf16x8*)(lds + PG8_SA(b, h) + aoff + m * 2048 + k * 1024); } while (0)
; #define PG8_LDB(dst, b, h) do { _Pragma("unroll") for (int n = 0; n < 2; ++n) _Pragma("unroll") for (int k = 0; k < 2; ++k) dst[n][k] = *(const PG8_LAS bf16x8*)(lds + PG8_SB(b, h) + boff + n * 2048 + k * 1024); } while (0)
; #define PG8_WAIT_V(n) asm volatile("s_waitcnt vmcnt(" #n ")" ::: "memory")
; #define PG8_WAIT_L(n) asm volatile("s_waitcnt lgkmcnt(" #n ")" ::: "memory")
; template <class Epi, class Sched, bool ALIGN_EPI = false>
; __device__ __forceinline__ void gemm_phase8(PG8_LAS unsigned char* lds, const Gemm g, const Sched& S, const Epi& E) {
;     ...
;         const bool has_next = S.next(ui + 1, nxt);
;         const size_t nko = (has_next && nxt.kp > 0) ? (size_t)nxt.kp * g.kpiece : 0;
;         const char* nA = has_next ? (const char*)g.A + (size_t)nxt.pm * tstepA + (size_t)nxt.pn * astep + nko : cA; const char* nB = has_next ? (const char*)g.Bt + (size_t)nxt.pn * tstepB + nko : cB;
;         const int nt = (cur.kp < 0 ? g.K : g.kpiece) / 128;
;         for (int t = 0; t < nt; t += 2) {
;             const bool last = (t == nt - 2);
;             const char* a1 = cA + (size_t)(t + 1) * kstep;
;             const char* a2 = last ? nA : cA + (size_t)(t + 2) * kstep; const char* b2 = last ? nB : cB + (size_t)(t + 2) * kstep;
;             const char* a3 = a2 + kstep; const char* b3 = b2 + kstep;
;             if (last && has_next) S.a_ready(nxt);
;             PG8_LDB(B0, 0, 0); PG8_LDB(B1, 0, 1); PG8_SCHED; PG8_LDA(At, 0, 0); PG8_STAGE(PG8_SA(1, 1), a1 + hstepA, voffA);
;             PG8_WAIT_V(8); PG8_WAIT_L(0); PG8_BAR; PG8_MMA(0, 0, At, B0); PG8_MMA(0, 1, At, B1); PG8_BAR; PG8_SCHED;
;             PG8_LDA(At, 0, 1); PG8_STAGE(PG8_SB(0, 0), b2, voffB); PG8_STAGE(PG8_SB(0, 1), b2 + hstepB, voffB); PG8_STAGE(PG8_SA(0, 0), a2, voffA);
;             PG8_WAIT_V(8); PG8_WAIT_L(0); PG8_BAR; PG8_MMA(1, 0, At, B0); PG8_MMA(1, 1, At, B1); PG8_BAR; PG8_SCHED;
.LBB0_1421:
	s_ashr_i32 s13, s12, 31
	s_lshl_b64 s[14:15], s[12:13], 19
	s_add_u32 s14, s26, s14
	s_addc_u32 s15, s27, s15
	s_and_b64 s[16:17], s[2:3], exec
	s_cselect_b32 s13, s15, s21
	s_cselect_b32 s45, s14, s20
	s_ashr_i32 s11, s10, 31
	s_lshl_b64 s[16:17], s[10:11], 19
	s_add_u32 s16, s28, s16
	s_addc_u32 s17, s29, s17
	s_and_b64 s[24:25], s[2:3], exec
	s_cselect_b32 s11, s17, s23
	s_cselect_b32 s52, s16, s22
	s_add_u32 s20, s20, 0x40080
	s_addc_u32 s21, s21, 0
	s_add_u32 s53, s22, 0x100
	s_addc_u32 s54, s23, 0
	s_mov_b32 s55, -2
	ds_read_b128 v[18:21], v191
	ds_read_b128 v[26:29], v191 offset:2048
	ds_read_b128 v[22:25], v192
	ds_read_b128 v[30:33], v192 offset:2048
	ds_read_b128 v[2:5], v193
	ds_read_b128 v[10:13], v193 offset:2048
	ds_read_b128 v[6:9], v194
	ds_read_b128 v[14:17], v194 offset:2048
	s_add_u32 s22, s20, 0xfffc0080
	s_addc_u32 s23, s21, -1
	s_cmp_eq_u32 s55, 12
	s_cselect_b32 s25, s13, s23
	s_cselect_b32 s24, s45, s22
	s_cselect_b32 s23, s11, s54
	s_cselect_b32 s22, s52, s53
	s_add_i32 m0, s19, 0xc000
	ds_read_b128 v[178:181], v195
	ds_read_b128 v[198:201], v195 offset:2048
	ds_read_b128 v[182:185], v196
	ds_read_b128 v[202:205], v196 offset:2048
	ds_read_b128 v[206:209], v195 offset:4096
	ds_read_b128 v[214:217], v195 offset:6144
	ds_read_b128 v[210:213], v196 offset:4096
	ds_read_b128 v[218:221], v196 offset:6144
	global_load_lds_dwordx4 v170, s[20:21]
	s_add_i32 m0, s19, 0xe000
	s_nop 0
	global_load_lds_dwordx4 v172, s[20:21]
	s_waitcnt vmcnt(8)
	s_waitcnt lgkmcnt(0)
	s_barrier
	s_setprio 1
	s_waitcnt lgkmcnt(0)
	v_mfma_scale_f32_16x16x128_f8f6f4 v[158:161], v[18:25], v[178:185], 0, v1, v186 op_sel_hi:[0,0,0]
	v_mfma_scale_f32_16x16x128_f8f6f4 v[150:153], v[26:33], v[178:185], 0, v1, v186 op_sel_hi:[0,0,0]
	v_mfma_scale_f32_16x16x128_f8f6f4 v[142:145], v[18:25], v[198:205], 0, v1, v186 op_sel_hi:[0,0,0]
	v_mfma_scale_f32_16x16x128_f8f6f4 v[134:137], v[26:33], v[198:205], 0, v1, v186 op_sel_hi:[0,0,0]
	v_mfma_scale_f32_16x16x128_f8f6f4 v[126:129], v[18:25], v[206:213], 0, v1, v186 op_sel_hi:[0,0,0]
	v_mfma_scale_f32_16x16x128_f8f6f4 v[118:121], v[26:33], v[206:213], 0, v1, v186 op_sel_hi:[0,0,0]
	v_mfma_scale_f32_16x16x128_f8f6f4 v[110:113], v[18:25], v[214:221], 0, v1, v186 op_sel_hi:[0,0,0]
	v_mfma_scale_f32_16x16x128_f8f6f4 v[102:105], v[26:33], v[214:221], 0, v1, v186 op_sel_hi:[0,0,0]
	s_setprio 0
	s_setprio 1
	v_mfma_scale_f32_16x16x128_f8f6f4 v[154:157], v[2:9], v[178:185], 0, v1, v186 op_sel_hi:[0,0,0]
	v_mfma_scale_f32_16x16x128_f8f6f4 v[146:149], v[10:17], v[178:185], 0, v1, v186 op_sel_hi:[0,0,0]
	v_mfma_scale_f32_16x16x128_f8f6f4 v[138:141], v[2:9], v[198:205], 0, v1, v186 op_sel_hi:[0,0,0]
	v_mfma_scale_f32_16x16x128_f8f6f4 v[130:133], v[10:17], v[198:205], 0, v1, v186 op_sel_hi:[0,0,0]
	v_mfma_scale_f32_16x16x128_f8f6f4 v[122:125], v[2:9], v[206:213], 0, v1, v186 op_sel_hi:[0,0,0]
	v_mfma_scale_f32_16x16x128_f8f6f4 v[114:117], v[10:17], v[206:213], 0, v1, v186 op_sel_hi:[0,0,0]
	v_mfma_scale_f32_16x16x128_f8f6f4 v[106:109], v[2:9], v[214:221], 0, v1, v186 op_sel_hi:[0,0,0]
	v_mfma_scale_f32_16x16x128_f8f6f4 v[98:101], v[10:17], v[214:221], 0, v1, v186 op_sel_hi:[0,0,0]
	s_setprio 0
	s_barrier
	s_add_i32 s56, s41, s30
	s_mov_b32 m0, s56
	ds_read_b128 v[198:201], v195 offset:16384
	ds_read_b128 v[206:209], v195 offset:18432
	ds_read_b128 v[202:205], v196 offset:16384
	ds_read_b128 v[210:213], v196 offset:18432
	ds_read_b128 v[214:217], v195 offset:20480
	ds_read_b128 v[222:225], v195 offset:22528
	ds_read_b128 v[218:221], v196 offset:20480
	ds_read_b128 v[226:229], v196 offset:22528
	global_load_lds_dwordx4 v164, s[22:23]
	s_add_i32 m0, s56, 0x2000
	s_add_u32 s56, s22, 0x40000
	s_addc_u32 s57, s23, 0
	s_add_i32 s58, s42, s30
	global_load_lds_dwordx4 v168, s[22:23]
	s_mov_b32 m0, s58
	s_nop 0
	global_load_lds_dwordx4 v164, s[56:57]
	s_add_i32 m0, s58, 0x2000
	s_nop 0
	global_load_lds_dwordx4 v168, s[56:57]
	s_mov_b32 m0, s19
	s_nop 0
	global_load_lds_dwordx4 v162, s[24:25]
	s_mov_b32 m0, s34
	s_nop 0
	global_load_lds_dwordx4 v166, s[24:25]
	s_waitcnt vmcnt(8)
	s_waitcnt lgkmcnt(0)
	s_barrier
	s_setprio 1
	s_waitcnt lgkmcnt(0)
	v_mfma_scale_f32_16x16x128_f8f6f4 v[94:97], v[18:25], v[198:205], 0, v1, v186 op_sel_hi:[0,0,0]
	v_mfma_scale_f32_16x16x128_f8f6f4 v[86:89], v[26:33], v[198:205], 0, v1, v186 op_sel_hi:[0,0,0]
	v_mfma_scale_f32_16x16x128_f8f6f4 v[78:81], v[18:25], v[206:213], 0, v1, v186 op_sel_hi:[0,0,0]
	v_mfma_scale_f32_16x16x128_f8f6f4 v[70:73], v[26:33], v[206:213], 0, v1, v186 op_sel_hi:[0,0,0]
	v_mfma_scale_f32_16x16x128_f8f6f4 v[62:65], v[18:25], v[214:221], 0, v1, v186 op_sel_hi:[0,0,0]
	v_mfma_scale_f32_16x16x128_f8f6f4 v[54:57], v[26:33], v[214:221], 0, v1, v186 op_sel_hi:[0,0,0]
	v_mfma_scale_f32_16x16x128_f8f6f4 v[46:49], v[18:25], v[222:229], 0, v1, v186 op_sel_hi:[0,0,0]
	v_mfma_scale_f32_16x16x128_f8f6f4 v[38:41], v[26:33], v[222:229], 0, v1, v186 op_sel_hi:[0,0,0]
	s_setprio 0
	s_setprio 1
	v_mfma_scale_f32_16x16x128_f8f6f4 v[90:93], v[2:9], v[198:205], 0, v1, v186 op_sel_hi:[0,0,0]
	v_mfma_scale_f32_16x16x128_f8f6f4 v[82:85], v[10:17], v[198:205], 0, v1, v186 op_sel_hi:[0,0,0]
	v_mfma_scale_f32_16x16x128_f8f6f4 v[74:77], v[2:9], v[206:213], 0, v1, v186 op_sel_hi:[0,0,0]
	v_mfma_scale_f32_16x16x128_f8f6f4 v[66:69], v[10:17], v[206:213], 0, v1, v186 op_sel_hi:[0,0,0]
	v_mfma_scale_f32_16x16x128_f8f6f4 v[58:61], v[2:9], v[214:221], 0, v1, v186 op_sel_hi:[0,0,0]
	v_mfma_scale_f32_16x16x128_f8f6f4 v[50:53], v[10:17], v[214:221], 0, v1, v186 op_sel_hi:[0,0,0]
	v_mfma_scale_f32_16x16x128_f8f6f4 v[42:45], v[2:9], v[222:229], 0, v1, v186 op_sel_hi:[0,0,0]
	v_mfma_scale_f32_16x16x128_f8f6f4 v[34:37], v[10:17], v[222:229], 0, v1, v186 op_sel_hi:[0,0,0]
	s_setprio 0
	s_barrier
; #define PG8_STAGE(bufoff, gbase, voff) do { _Pragma("unroll") for (int _i = 0; _i < 2; ++_i) \
;         __builtin_amdgcn_global_load_lds((const unsigned*)((const char*)(gbase) + (voff)[_i]), (PG8_LAS unsigned*)(lds + (bufoff) + ldsw + _i * 8192), 16, 0, 0); } while (0)
; #define PG8_LDA(dst, b, h) do { _Pragma("unroll") for (int m = 0; m < 4; ++m) _Pragma("unroll") for (int k = 0; k < 2; ++k) dst[m][k] = *(const PG8_LAS bf16x8*)(lds + PG8_SA(b, h) + aoff + m * 2048 + k * 1024); } while (0)
; #define PG8_LDB(dst, b, h) do { _Pragma("unroll") for (int n = 0; n < 2; ++n) _Pragma("unroll") for (int k = 0; k < 2; ++k) dst[n][k] = *(const PG8_LAS bf16x8*)(lds + PG8_SB(b, h) + boff + n * 2048 + k * 1024); } while (0)
; #define PG8_MMA(ai, bj, At, Bt) do { __builtin_amdgcn_s_setprio(1); _Pragma("unroll") for (int m = 0; m < 4; ++m) _Pragma("unroll") for (int n = 0; n < 2; ++n) _Pragma("unroll") for (int k = 0; k < 2; ++k) \
;         acc[ai][bj][m][n] = __builtin_amdgcn_mfma_f32_16x16x32_bf16(Bt[n][k], At[m][k], acc[ai][bj][m][n], 0, 0, 0); __builtin_amdgcn_s_setprio(0); } while (0)
; #define PG8_WAIT_V(n) asm volatile("s_waitcnt vmcnt(" #n ")" ::: "memory")
; #define PG8_WAIT_L(n) asm volatile("s_waitcnt lgkmcnt(" #n ")" ::: "memory")
; #define PG8_BAR __builtin_amdgcn_s_barrier()
; #define PG8_SCHED __builtin_amdgcn_sched_barrier(0)
; #define PG8_STAGE(bufoff, gbase, voff) do { _Pragma("unroll") for (int _i = 0; _i < 2; ++_i) \
;         __builtin_amdgcn_global_load_lds((const unsigned*)((const char*)(gbase) + (voff)[_i]), (PG8_LAS unsigned*)(lds + (bufoff) + ldsw + _i * 8192), 16, 0, 0); } while (0)
; #define PG8_BAR __builtin_amdgcn_s_barrier()
; template <class Epi, class Sched, bool ALIGN_EPI = false>
; __device__ __forceinline__ void gemm_phase8(PG8_LAS unsigned char* lds, const Gemm g, const Sched& S, const Epi& E) {
;     ...
;             PG8_LDB(B0, 1, 0); PG8_LDB(B1, 1, 1); PG8_SCHED; PG8_LDA(At, 1, 0); PG8_STAGE(PG8_SA(0, 1), a2 + hstepA, voffA);
;             PG8_WAIT_V(8); PG8_WAIT_L(0); PG8_BAR; PG8_MMA(0, 0, At, B0); PG8_MMA(0, 1, At, B1); PG8_BAR; PG8_SCHED;
;             PG8_LDA(At, 1, 1); PG8_STAGE(PG8_SB(1, 0), b3, voffB); PG8_STAGE(PG8_SB(1, 1), b3 + hstepB, voffB); PG8_STAGE(PG8_SA(1, 0), a3, voffA);
;             PG8_WAIT_V(8); PG8_WAIT_L(0); PG8_BAR; PG8_MMA(1, 0, At, B0); PG8_MMA(1, 1, At, B1); PG8_BAR; PG8_SCHED;
;         }
	s_add_i32 s56, 0, 0x18000
	s_add_i32 s57, 0, 0x1c000
	v_add_u32_e32 v6, s56, v187
	v_add_u32_e32 v14, s56, v188
	v_add_u32_e32 v22, s57, v187
	v_add_u32_e32 v30, s57, v188
	ds_read_b128 v[2:5], v6
	ds_read_b128 v[10:13], v6 offset:2048
	ds_read_b128 v[6:9], v14
	ds_read_b128 v[14:17], v14 offset:2048
	ds_read_b128 v[18:21], v22
	ds_read_b128 v[26:29], v22 offset:2048
	ds_read_b128 v[22:25], v30
	ds_read_b128 v[30:33], v30 offset:2048
	s_add_u32 s24, s24, 0x40000
	s_addc_u32 s25, s25, 0
	s_mov_b32 m0, s35
	ds_read_b128 v[198:201], v195 offset:32768
	ds_read_b128 v[206:209], v195 offset:34816
	ds_read_b128 v[202:205], v196 offset:32768
	ds_read_b128 v[210:213], v196 offset:34816
	ds_read_b128 v[214:217], v195 offset:36864
	ds_read_b128 v[222:225], v195 offset:38912
	ds_read_b128 v[218:221], v196 offset:36864
	ds_read_b128 v[226:229], v196 offset:38912
	global_load_lds_dwordx4 v162, s[24:25]
	s_mov_b32 m0, s36
	s_nop 0
	global_load_lds_dwordx4 v166, s[24:25]
	s_waitcnt vmcnt(8)
	s_waitcnt lgkmcnt(0)
	s_barrier
	s_setprio 1
	s_waitcnt lgkmcnt(0)
	v_mfma_scale_f32_16x16x128_f8f6f4 v[158:161], v[2:9], v[198:205], v[158:161], v1, v186 op_sel_hi:[0,0,0]
	v_mfma_scale_f32_16x16x128_f8f6f4 v[150:153], v[10:17], v[198:205], v[150:153], v1, v186 op_sel_hi:[0,0,0]
	v_mfma_scale_f32_16x16x128_f8f6f4 v[142:145], v[2:9], v[206:213], v[142:145], v1, v186 op_sel_hi:[0,0,0]
	v_mfma_scale_f32_16x16x128_f8f6f4 v[134:137], v[10:17], v[206:213], v[134:137], v1, v186 op_sel_hi:[0,0,0]
	v_mfma_scale_f32_16x16x128_f8f6f4 v[126:129], v[2:9], v[214:221], v[126:129], v1, v186 op_sel_hi:[0,0,0]
	v_mfma_scale_f32_16x16x128_f8f6f4 v[118:121], v[10:17], v[214:221], v[118:121], v1, v186 op_sel_hi:[0,0,0]
	v_mfma_scale_f32_16x16x128_f8f6f4 v[110:113], v[2:9], v[222:229], v[110:113], v1, v186 op_sel_hi:[0,0,0]
	v_mfma_scale_f32_16x16x128_f8f6f4 v[102:105], v[10:17], v[222:229], v[102:105], v1, v186 op_sel_hi:[0,0,0]
	s_setprio 0
	s_setprio 1
	v_mfma_scale_f32_16x16x128_f8f6f4 v[154:157], v[18:25], v[198:205], v[154:157], v1, v186 op_sel_hi:[0,0,0]
	v_mfma_scale_f32_16x16x128_f8f6f4 v[146:149], v[26:33], v[198:205], v[146:149], v1, v186 op_sel_hi:[0,0,0]
	v_mfma_scale_f32_16x16x128_f8f6f4 v[138:141], v[18:25], v[206:213], v[138:141], v1, v186 op_sel_hi:[0,0,0]
	v_mfma_scale_f32_16x16x128_f8f6f4 v[130:133], v[26:33], v[206:213], v[130:133], v1, v186 op_sel_hi:[0,0,0]
	v_mfma_scale_f32_16x16x128_f8f6f4 v[122:125], v[18:25], v[214:221], v[122:125], v1, v186 op_sel_hi:[0,0,0]
	v_mfma_scale_f32_16x16x128_f8f6f4 v[114:117], v[26:33], v[214:221], v[114:117], v1, v186 op_sel_hi:[0,0,0]
	v_mfma_scale_f32_16x16x128_f8f6f4 v[106:109], v[18:25], v[222:229], v[106:109], v1, v186 op_sel_hi:[0,0,0]
	v_mfma_scale_f32_16x16x128_f8f6f4 v[98:101], v[26:33], v[222:229], v[98:101], v1, v186 op_sel_hi:[0,0,0]
	s_setprio 0
	s_barrier
	s_add_i32 s101, s56, s30
	s_add_u32 s98, s22, s6
	s_addc_u32 s99, s23, s7
	s_mov_b32 m0, s101
	ds_read_b128 v[198:201], v195 offset:49152
	ds_read_b128 v[206:209], v195 offset:51200
	ds_read_b128 v[202:205], v196 offset:49152
	ds_read_b128 v[210:213], v196 offset:51200
	ds_read_b128 v[214:217], v195 offset:53248
	ds_read_b128 v[222:225], v195 offset:55296
	ds_read_b128 v[218:221], v196 offset:53248
	ds_read_b128 v[226:229], v196 offset:55296
	global_load_lds_dwordx4 v164, s[98:99]
	s_add_i32 m0, s101, 0x2000
	s_add_u32 s22, s22, 0x40080
	s_addc_u32 s23, s23, 0
	s_add_i32 s101, s57, s30
	global_load_lds_dwordx4 v168, s[98:99]
	s_add_u32 s98, s24, s6
	s_addc_u32 s99, s25, s7
	s_sub_u32 s98, s98, 0x40000
	s_subb_u32 s99, s99, 0
	s_mov_b32 m0, s101
	s_nop 0
	global_load_lds_dwordx4 v164, s[22:23]
	s_add_i32 m0, s101, 0x2000
	s_nop 0
	global_load_lds_dwordx4 v168, s[22:23]
	s_mov_b32 m0, s39
	s_nop 0
	global_load_lds_dwordx4 v162, s[98:99]
	s_mov_b32 m0, s40
	s_nop 0
	global_load_lds_dwordx4 v166, s[98:99]
	s_waitcnt vmcnt(8)
	s_waitcnt lgkmcnt(0)
	s_barrier
	s_setprio 1
	s_waitcnt lgkmcnt(0)
	v_mfma_scale_f32_16x16x128_f8f6f4 v[94:97], v[2:9], v[198:205], v[94:97], v1, v186 op_sel_hi:[0,0,0]
	v_mfma_scale_f32_16x16x128_f8f6f4 v[86:89], v[10:17], v[198:205], v[86:89], v1, v186 op_sel_hi:[0,0,0]
	v_mfma_scale_f32_16x16x128_f8f6f4 v[78:81], v[2:9], v[206:213], v[78:81], v1, v186 op_sel_hi:[0,0,0]
	v_mfma_scale_f32_16x16x128_f8f6f4 v[70:73], v[10:17], v[206:213], v[70:73], v1, v186 op_sel_hi:[0,0,0]
	v_mfma_scale_f32_16x16x128_f8f6f4 v[62:65], v[2:9], v[214:221], v[62:65], v1, v186 op_sel_hi:[0,0,0]
	v_mfma_scale_f32_16x16x128_f8f6f4 v[54:57], v[10:17], v[214:221], v[54:57], v1, v186 op_sel_hi:[0,0,0]
	v_mfma_scale_f32_16x16x128_f8f6f4 v[46:49], v[2:9], v[222:229], v[46:49], v1, v186 op_sel_hi:[0,0,0]
	v_mfma_scale_f32_16x16x128_f8f6f4 v[38:41], v[10:17], v[222:229], v[38:41], v1, v186 op_sel_hi:[0,0,0]
	s_setprio 0
	s_setprio 1
	v_mfma_scale_f32_16x16x128_f8f6f4 v[90:93], v[18:25], v[198:205], v[90:93], v1, v186 op_sel_hi:[0,0,0]
	v_mfma_scale_f32_16x16x128_f8f6f4 v[82:85], v[26:33], v[198:205], v[82:85], v1, v186 op_sel_hi:[0,0,0]
	v_mfma_scale_f32_16x16x128_f8f6f4 v[74:77], v[18:25], v[206:213], v[74:77], v1, v186 op_sel_hi:[0,0,0]
	v_mfma_scale_f32_16x16x128_f8f6f4 v[66:69], v[26:33], v[206:213], v[66:69], v1, v186 op_sel_hi:[0,0,0]
	v_mfma_scale_f32_16x16x128_f8f6f4 v[58:61], v[18:25], v[214:221], v[58:61], v1, v186 op_sel_hi:[0,0,0]
	v_mfma_scale_f32_16x16x128_f8f6f4 v[50:53], v[26:33], v[214:221], v[50:53], v1, v186 op_sel_hi:[0,0,0]
	v_mfma_scale_f32_16x16x128_f8f6f4 v[42:45], v[18:25], v[222:229], v[42:45], v1, v186 op_sel_hi:[0,0,0]
	v_mfma_scale_f32_16x16x128_f8f6f4 v[34:37], v[26:33], v[222:229], v[34:37], v1, v186 op_sel_hi:[0,0,0]
	s_setprio 0
	s_barrier
	s_add_i32 s55, s55, 2
	s_add_u32 s20, s20, 0x100
	s_addc_u32 s21, s21, 0
	s_add_u32 s53, s53, 0x100
	s_addc_u32 s54, s54, 0
	s_cmp_gt_u32 s55, 13
; #define PG8_STAGE(bufoff, gbase, voff) do { _Pragma("unroll") for (int _i = 0; _i < 2; ++_i) \
;         __builtin_amdgcn_global_load_lds((const unsigned*)((const char*)(gbase) + (voff)[_i]), (PG8_LAS unsigned*)(lds + (bufoff) + ldsw + _i * 8192), 16, 0, 0); } while (0)
; #define PG8_LDA(dst, b, h) do { _Pragma("unroll") for (int m = 0; m < 4; ++m) _Pragma("unroll") for (int k = 0; k < 2; ++k) dst[m][k] = *(const PG8_LAS bf16x8*)(lds + PG8_SA(b, h) + aoff + m * 2048 + k * 1024); } while (0)
; #define PG8_LDB(dst, b, h) do { _Pragma("unroll") for (int n = 0; n < 2; ++n) _Pragma("unroll") for (int k = 0; k < 2; ++k) dst[n][k] = *(const PG8_LAS bf16x8*)(lds + PG8_SB(b, h) + boff + n * 2048 + k * 1024); } while (0)
; #define PG8_MMA(ai, bj, At, Bt) do { __builtin_amdgcn_s_setprio(1); _Pragma("unroll") for (int m = 0; m < 4; ++m) _Pragma("unroll") for (int n = 0; n < 2; ++n) _Pragma("unroll") for (int k = 0; k < 2; ++k) \
;         acc[ai][bj][m][n] = __builtin_amdgcn_mfma_f32_16x16x32_bf16(Bt[n][k], At[m][k], acc[ai][bj][m][n], 0, 0, 0); __builtin_amdgcn_s_setprio(0); } while (0)
; #define PG8_WAIT_V(n) asm volatile("s_waitcnt vmcnt(" #n ")" ::: "memory")
; #define PG8_WAIT_L(n) asm volatile("s_waitcnt lgkmcnt(" #n ")" ::: "memory")
; template <class Epi, class Sched, bool ALIGN_EPI = false>
; __device__ __forceinline__ void gemm_phase8(PG8_LAS unsigned char* lds, const Gemm g, const Sched& S, const Epi& E) {
;     ...
;         for (int t = 0; t < nt; t += 2) {
;             const bool last = (t == nt - 2);
;             const char* a1 = cA + (size_t)(t + 1) * kstep;
;             const char* a2 = last ? nA : cA + (size_t)(t + 2) * kstep; const char* b2 = last ? nB : cB + (size_t)(t + 2) * kstep;
;             const char* a3 = a2 + kstep; const char* b3 = b2 + kstep;
;             if (last && has_next) S.a_ready(nxt);
;             PG8_LDB(B0, 0, 0); PG8_LDB(B1, 0, 1); PG8_SCHED; PG8_LDA(At, 0, 0); PG8_STAGE(PG8_SA(1, 1), a1 + hstepA, voffA);
;             PG8_WAIT_V(8); PG8_WAIT_L(0); PG8_BAR; PG8_MMA(0, 0, At, B0); PG8_MMA(0, 1, At, B1); PG8_BAR; PG8_SCHED;
;             PG8_LDA(At, 0, 1); PG8_STAGE(PG8_SB(0, 0), b2, voffB); PG8_STAGE(PG8_SB(0, 1), b2 + hstepB, voffB); PG8_STAGE(PG8_SA(0, 0), a2, voffA);
;             PG8_WAIT_V(8); PG8_WAIT_L(0); PG8_BAR; PG8_MMA(1, 0, At, B0); PG8_MMA(1, 1, At, B1); PG8_BAR; PG8_SCHED;
.LBB0_1422:
	ds_read_b128 v[18:21], v191
	ds_read_b128 v[26:29], v191 offset:2048
	ds_read_b128 v[22:25], v192
	ds_read_b128 v[30:33], v192 offset:2048
	ds_read_b128 v[2:5], v193
	ds_read_b128 v[10:13], v193 offset:2048
	ds_read_b128 v[6:9], v194
	ds_read_b128 v[14:17], v194 offset:2048
	s_add_u32 s22, s20, 0xfffc0080
	s_addc_u32 s23, s21, -1
	s_cmp_eq_u32 s55, 12
	s_cselect_b32 s25, s13, s23
	s_cselect_b32 s24, s45, s22
	s_cselect_b32 s23, s11, s54
	s_cselect_b32 s22, s52, s53
	s_add_i32 m0, s19, 0xc000
	ds_read_b128 v[178:181], v195
	ds_read_b128 v[198:201], v195 offset:2048
	ds_read_b128 v[182:185], v196
	ds_read_b128 v[202:205], v196 offset:2048
	ds_read_b128 v[206:209], v195 offset:4096
	ds_read_b128 v[214:217], v195 offset:6144
	ds_read_b128 v[210:213], v196 offset:4096
	ds_read_b128 v[218:221], v196 offset:6144
	global_load_lds_dwordx4 v170, s[20:21]
	s_add_i32 m0, s19, 0xe000
	s_nop 0
	global_load_lds_dwordx4 v172, s[20:21]
	s_waitcnt vmcnt(8)
	s_waitcnt lgkmcnt(0)
	s_barrier
	s_setprio 1
	s_waitcnt lgkmcnt(0)
	v_mfma_scale_f32_16x16x128_f8f6f4 v[158:161], v[18:25], v[178:185], v[158:161], v1, v186 op_sel_hi:[0,0,0]
	v_mfma_scale_f32_16x16x128_f8f6f4 v[150:153], v[26:33], v[178:185], v[150:153], v1, v186 op_sel_hi:[0,0,0]
	v_mfma_scale_f32_16x16x128_f8f6f4 v[142:145], v[18:25], v[198:205], v[142:145], v1, v186 op_sel_hi:[0,0,0]
	v_mfma_scale_f32_16x16x128_f8f6f4 v[134:137], v[26:33], v[198:205], v[134:137], v1, v186 op_sel_hi:[0,0,0]
	v_mfma_scale_f32_16x16x128_f8f6f4 v[126:129], v[18:25], v[206:213], v[126:129], v1, v186 op_sel_hi:[0,0,0]
	v_mfma_scale_f32_16x16x128_f8f6f4 v[118:121], v[26:33], v[206:213], v[118:121], v1, v186 op_sel_hi:[0,0,0]
	v_mfma_scale_f32_16x16x128_f8f6f4 v[110:113], v[18:25], v[214:221], v[110:113], v1, v186 op_sel_hi:[0,0,0]
	v_mfma_scale_f32_16x16x128_f8f6f4 v[102:105], v[26:33], v[214:221], v[102:105], v1, v186 op_sel_hi:[0,0,0]
	s_setprio 0
	s_setprio 1
	v_mfma_scale_f32_16x16x128_f8f6f4 v[154:157], v[2:9], v[178:185], v[154:157], v1, v186 op_sel_hi:[0,0,0]
	v_mfma_scale_f32_16x16x128_f8f6f4 v[146:149], v[10:17], v[178:185], v[146:149], v1, v186 op_sel_hi:[0,0,0]
	v_mfma_scale_f32_16x16x128_f8f6f4 v[138:141], v[2:9], v[198:205], v[138:141], v1, v186 op_sel_hi:[0,0,0]
	v_mfma_scale_f32_16x16x128_f8f6f4 v[130:133], v[10:17], v[198:205], v[130:133], v1, v186 op_sel_hi:[0,0,0]
	v_mfma_scale_f32_16x16x128_f8f6f4 v[122:125], v[2:9], v[206:213], v[122:125], v1, v186 op_sel_hi:[0,0,0]
	v_mfma_scale_f32_16x16x128_f8f6f4 v[114:117], v[10:17], v[206:213], v[114:117], v1, v186 op_sel_hi:[0,0,0]
	v_mfma_scale_f32_16x16x128_f8f6f4 v[106:109], v[2:9], v[214:221], v[106:109], v1, v186 op_sel_hi:[0,0,0]
	v_mfma_scale_f32_16x16x128_f8f6f4 v[98:101], v[10:17], v[214:221], v[98:101], v1, v186 op_sel_hi:[0,0,0]
	s_setprio 0
	s_barrier
	s_add_i32 s56, s41, s30
	s_mov_b32 m0, s56
	ds_read_b128 v[198:201], v195 offset:16384
	ds_read_b128 v[206:209], v195 offset:18432
	ds_read_b128 v[202:205], v196 offset:16384
	ds_read_b128 v[210:213], v196 offset:18432
	ds_read_b128 v[214:217], v195 offset:20480
	ds_read_b128 v[222:225], v195 offset:22528
	ds_read_b128 v[218:221], v196 offset:20480
	ds_read_b128 v[226:229], v196 offset:22528
	global_load_lds_dwordx4 v164, s[22:23]
	s_add_i32 m0, s56, 0x2000
	s_add_u32 s56, s22, 0x40000
	s_addc_u32 s57, s23, 0
	s_add_i32 s58, s42, s30
	global_load_lds_dwordx4 v168, s[22:23]
	s_mov_b32 m0, s58
	s_nop 0
	global_load_lds_dwordx4 v164, s[56:57]
	s_add_i32 m0, s58, 0x2000
	s_nop 0
	global_load_lds_dwordx4 v168, s[56:57]
	s_mov_b32 m0, s19
	s_nop 0
	global_load_lds_dwordx4 v162, s[24:25]
	s_mov_b32 m0, s34
	s_nop 0
	global_load_lds_dwordx4 v166, s[24:25]
	s_waitcnt vmcnt(8)
	s_waitcnt lgkmcnt(0)
	s_barrier
	s_setprio 1
	s_waitcnt lgkmcnt(0)
	v_mfma_scale_f32_16x16x128_f8f6f4 v[94:97], v[18:25], v[198:205], v[94:97], v1, v186 op_sel_hi:[0,0,0]
	v_mfma_scale_f32_16x16x128_f8f6f4 v[86:89], v[26:33], v[198:205], v[86:89], v1, v186 op_sel_hi:[0,0,0]
	v_mfma_scale_f32_16x16x128_f8f6f4 v[78:81], v[18:25], v[206:213], v[78:81], v1, v186 op_sel_hi:[0,0,0]
	v_mfma_scale_f32_16x16x128_f8f6f4 v[70:73], v[26:33], v[206:213], v[70:73], v1, v186 op_sel_hi:[0,0,0]
	v_mfma_scale_f32_16x16x128_f8f6f4 v[62:65], v[18:25], v[214:221], v[62:65], v1, v186 op_sel_hi:[0,0,0]
	v_mfma_scale_f32_16x16x128_f8f6f4 v[54:57], v[26:33], v[214:221], v[54:57], v1, v186 op_sel_hi:[0,0,0]
	v_mfma_scale_f32_16x16x128_f8f6f4 v[46:49], v[18:25], v[222:229], v[46:49], v1, v186 op_sel_hi:[0,0,0]
	v_mfma_scale_f32_16x16x128_f8f6f4 v[38:41], v[26:33], v[222:229], v[38:41], v1, v186 op_sel_hi:[0,0,0]
	s_setprio 0
	s_setprio 1
	v_mfma_scale_f32_16x16x128_f8f6f4 v[90:93], v[2:9], v[198:205], v[90:93], v1, v186 op_sel_hi:[0,0,0]
	v_mfma_scale_f32_16x16x128_f8f6f4 v[82:85], v[10:17], v[198:205], v[82:85], v1, v186 op_sel_hi:[0,0,0]
	v_mfma_scale_f32_16x16x128_f8f6f4 v[74:77], v[2:9], v[206:213], v[74:77], v1, v186 op_sel_hi:[0,0,0]
	v_mfma_scale_f32_16x16x128_f8f6f4 v[66:69], v[10:17], v[206:213], v[66:69], v1, v186 op_sel_hi:[0,0,0]
	v_mfma_scale_f32_16x16x128_f8f6f4 v[58:61], v[2:9], v[214:221], v[58:61], v1, v186 op_sel_hi:[0,0,0]
	v_mfma_scale_f32_16x16x128_f8f6f4 v[50:53], v[10:17], v[214:221], v[50:53], v1, v186 op_sel_hi:[0,0,0]
	v_mfma_scale_f32_16x16x128_f8f6f4 v[42:45], v[2:9], v[222:229], v[42:45], v1, v186 op_sel_hi:[0,0,0]
	v_mfma_scale_f32_16x16x128_f8f6f4 v[34:37], v[10:17], v[222:229], v[34:37], v1, v186 op_sel_hi:[0,0,0]
	s_setprio 0
	s_barrier
; #define PG8_STAGE(bufoff, gbase, voff) do { _Pragma("unroll") for (int _i = 0; _i < 2; ++_i) \
;         __builtin_amdgcn_global_load_lds((const unsigned*)((const char*)(gbase) + (voff)[_i]), (PG8_LAS unsigned*)(lds + (bufoff) + ldsw + _i * 8192), 16, 0, 0); } while (0)
; #define PG8_LDA(dst, b, h) do { _Pragma("unroll") for (int m = 0; m < 4; ++m) _Pragma("unroll") for (int k = 0; k < 2; ++k) dst[m][k] = *(const PG8_LAS bf16x8*)(lds + PG8_SA(b, h) + aoff + m * 2048 + k * 1024); } while (0)
; #define PG8_LDB(dst, b, h) do { _Pragma("unroll") for (int n = 0; n < 2; ++n) _Pragma("unroll") for (int k = 0; k < 2; ++k) dst[n][k] = *(const PG8_LAS bf16x8*)(lds + PG8_SB(b, h) + boff + n * 2048 + k * 1024); } while (0)
; #define PG8_MMA(ai, bj, At, Bt) do { __builtin_amdgcn_s_setprio(1); _Pragma("unroll") for (int m = 0; m < 4; ++m) _Pragma("unroll") for (int n = 0; n < 2; ++n) _Pragma("unroll") for (int k = 0; k < 2; ++k) \
;         acc[ai][bj][m][n] = __builtin_amdgcn_mfma_f32_16x16x32_bf16(Bt[n][k], At[m][k], acc[ai][bj][m][n], 0, 0, 0); __builtin_amdgcn_s_setprio(0); } while (0)
; #define PG8_WAIT_V(n) asm volatile("s_waitcnt vmcnt(" #n ")" ::: "memory")
; #define PG8_WAIT_L(n) asm volatile("s_waitcnt lgkmcnt(" #n ")" ::: "memory")
; #define PG8_BAR __builtin_amdgcn_s_barrier()
; #define PG8_SCHED __builtin_amdgcn_sched_barrier(0)
; #define PG8_STAGE(bufoff, gbase, voff) do { _Pragma("unroll") for (int _i = 0; _i < 2; ++_i) \
;         __builtin_amdgcn_global_load_lds((const unsigned*)((const char*)(gbase) + (voff)[_i]), (PG8_LAS unsigned*)(lds + (bufoff) + ldsw + _i * 8192), 16, 0, 0); } while (0)
; template <class Epi, class Sched, bool ALIGN_EPI = false>
; __device__ __forceinline__ void gemm_phase8(PG8_LAS unsigned char* lds, const Gemm g, const Sched& S, const Epi& E) {
;     ...
;             PG8_LDB(B0, 1, 0); PG8_LDB(B1, 1, 1); PG8_SCHED; PG8_LDA(At, 1, 0); PG8_STAGE(PG8_SA(0, 1), a2 + hstepA, voffA);
;             PG8_WAIT_V(8); PG8_WAIT_L(0); PG8_BAR; PG8_MMA(0, 0, At, B0); PG8_MMA(0, 1, At, B1); PG8_BAR; PG8_SCHED;
;             PG8_LDA(At, 1, 1); PG8_STAGE(PG8_SB(1, 0), b3, voffB); PG8_STAGE(PG8_SB(1, 1), b3 + hstepB, voffB); PG8_STAGE(PG8_SA(1, 0), a3, voffA);
;             PG8_WAIT_V(8); PG8_WAIT_L(0); PG8_BAR; PG8_MMA(1, 0, At, B0); PG8_MMA(1, 1, At, B1); PG8_BAR; PG8_SCHED;
;         }
;         if constexpr (ALIGN_EPI) { if (wr == 0) PG8_BAR; }
	s_add_i32 s56, 0, 0x18000
	s_add_i32 s57, 0, 0x1c000
	v_add_u32_e32 v6, s56, v187
	v_add_u32_e32 v14, s56, v188
	v_add_u32_e32 v22, s57, v187
	v_add_u32_e32 v30, s57, v188
	ds_read_b128 v[2:5], v6
	ds_read_b128 v[10:13], v6 offset:2048
	ds_read_b128 v[6:9], v14
	ds_read_b128 v[14:17], v14 offset:2048
	ds_read_b128 v[18:21], v22
	ds_read_b128 v[26:29], v22 offset:2048
	ds_read_b128 v[22:25], v30
	ds_read_b128 v[30:33], v30 offset:2048
	s_add_u32 s24, s24, 0x40000
	s_addc_u32 s25, s25, 0
	s_mov_b32 m0, s35
	ds_read_b128 v[198:201], v195 offset:32768
	ds_read_b128 v[206:209], v195 offset:34816
	ds_read_b128 v[202:205], v196 offset:32768
	ds_read_b128 v[210:213], v196 offset:34816
	ds_read_b128 v[214:217], v195 offset:36864
	ds_read_b128 v[222:225], v195 offset:38912
	ds_read_b128 v[218:221], v196 offset:36864
	ds_read_b128 v[226:229], v196 offset:38912
	global_load_lds_dwordx4 v162, s[24:25]
	s_mov_b32 m0, s36
	s_nop 0
	global_load_lds_dwordx4 v166, s[24:25]
	s_waitcnt vmcnt(8)
	s_waitcnt lgkmcnt(0)
	s_barrier
	s_setprio 1
	s_waitcnt lgkmcnt(0)
	v_mfma_scale_f32_16x16x128_f8f6f4 v[158:161], v[2:9], v[198:205], v[158:161], v1, v186 op_sel_hi:[0,0,0]
	v_mfma_scale_f32_16x16x128_f8f6f4 v[150:153], v[10:17], v[198:205], v[150:153], v1, v186 op_sel_hi:[0,0,0]
	v_mfma_scale_f32_16x16x128_f8f6f4 v[142:145], v[2:9], v[206:213], v[142:145], v1, v186 op_sel_hi:[0,0,0]
	v_mfma_scale_f32_16x16x128_f8f6f4 v[134:137], v[10:17], v[206:213], v[134:137], v1, v186 op_sel_hi:[0,0,0]
	v_mfma_scale_f32_16x16x128_f8f6f4 v[126:129], v[2:9], v[214:221], v[126:129], v1, v186 op_sel_hi:[0,0,0]
	v_mfma_scale_f32_16x16x128_f8f6f4 v[118:121], v[10:17], v[214:221], v[118:121], v1, v186 op_sel_hi:[0,0,0]
	v_mfma_scale_f32_16x16x128_f8f6f4 v[110:113], v[2:9], v[222:229], v[110:113], v1, v186 op_sel_hi:[0,0,0]
	v_mfma_scale_f32_16x16x128_f8f6f4 v[102:105], v[10:17], v[222:229], v[102:105], v1, v186 op_sel_hi:[0,0,0]
	s_setprio 0
	s_setprio 1
	v_mfma_scale_f32_16x16x128_f8f6f4 v[154:157], v[18:25], v[198:205], v[154:157], v1, v186 op_sel_hi:[0,0,0]
	v_mfma_scale_f32_16x16x128_f8f6f4 v[146:149], v[26:33], v[198:205], v[146:149], v1, v186 op_sel_hi:[0,0,0]
	v_mfma_scale_f32_16x16x128_f8f6f4 v[138:141], v[18:25], v[206:213], v[138:141], v1, v186 op_sel_hi:[0,0,0]
	v_mfma_scale_f32_16x16x128_f8f6f4 v[130:133], v[26:33], v[206:213], v[130:133], v1, v186 op_sel_hi:[0,0,0]
	v_mfma_scale_f32_16x16x128_f8f6f4 v[122:125], v[18:25], v[214:221], v[122:125], v1, v186 op_sel_hi:[0,0,0]
	v_mfma_scale_f32_16x16x128_f8f6f4 v[114:117], v[26:33], v[214:221], v[114:117], v1, v186 op_sel_hi:[0,0,0]
	v_mfma_scale_f32_16x16x128_f8f6f4 v[106:109], v[18:25], v[222:229], v[106:109], v1, v186 op_sel_hi:[0,0,0]
	v_mfma_scale_f32_16x16x128_f8f6f4 v[98:101], v[26:33], v[222:229], v[98:101], v1, v186 op_sel_hi:[0,0,0]
	s_setprio 0
	s_barrier
	s_add_i32 s101, s56, s30
	s_add_u32 s98, s22, s6
	s_addc_u32 s99, s23, s7
	s_mov_b32 m0, s101
	ds_read_b128 v[198:201], v195 offset:49152
	ds_read_b128 v[206:209], v195 offset:51200
	ds_read_b128 v[202:205], v196 offset:49152
	ds_read_b128 v[210:213], v196 offset:51200
	ds_read_b128 v[214:217], v195 offset:53248
	ds_read_b128 v[222:225], v195 offset:55296
	ds_read_b128 v[218:221], v196 offset:53248
	ds_read_b128 v[226:229], v196 offset:55296
	global_load_lds_dwordx4 v164, s[98:99]
	s_add_i32 m0, s101, 0x2000
	s_add_u32 s22, s22, 0x40080
	s_addc_u32 s23, s23, 0
	s_add_i32 s101, s57, s30
	global_load_lds_dwordx4 v168, s[98:99]
	s_add_u32 s98, s24, s6
	s_addc_u32 s99, s25, s7
	s_sub_u32 s98, s98, 0x40000
	s_subb_u32 s99, s99, 0
	s_mov_b32 m0, s101
	s_nop 0
	global_load_lds_dwordx4 v164, s[22:23]
	s_add_i32 m0, s101, 0x2000
	s_nop 0
	global_load_lds_dwordx4 v168, s[22:23]
	s_mov_b32 m0, s39
	s_nop 0
	global_load_lds_dwordx4 v162, s[98:99]
	s_mov_b32 m0, s40
	s_nop 0
	global_load_lds_dwordx4 v166, s[98:99]
	s_waitcnt vmcnt(8)
	s_waitcnt lgkmcnt(0)
	s_barrier
	s_setprio 1
	s_waitcnt lgkmcnt(0)
	v_mfma_scale_f32_16x16x128_f8f6f4 v[94:97], v[2:9], v[198:205], v[94:97], v1, v186 op_sel_hi:[0,0,0]
	v_mfma_scale_f32_16x16x128_f8f6f4 v[86:89], v[10:17], v[198:205], v[86:89], v1, v186 op_sel_hi:[0,0,0]
	v_mfma_scale_f32_16x16x128_f8f6f4 v[78:81], v[2:9], v[206:213], v[78:81], v1, v186 op_sel_hi:[0,0,0]
	v_mfma_scale_f32_16x16x128_f8f6f4 v[70:73], v[10:17], v[206:213], v[70:73], v1, v186 op_sel_hi:[0,0,0]
	v_mfma_scale_f32_16x16x128_f8f6f4 v[62:65], v[2:9], v[214:221], v[62:65], v1, v186 op_sel_hi:[0,0,0]
	v_mfma_scale_f32_16x16x128_f8f6f4 v[54:57], v[10:17], v[214:221], v[54:57], v1, v186 op_sel_hi:[0,0,0]
	v_mfma_scale_f32_16x16x128_f8f6f4 v[46:49], v[2:9], v[222:229], v[46:49], v1, v186 op_sel_hi:[0,0,0]
	v_mfma_scale_f32_16x16x128_f8f6f4 v[38:41], v[10:17], v[222:229], v[38:41], v1, v186 op_sel_hi:[0,0,0]
	s_setprio 0
	s_setprio 1
	v_mfma_scale_f32_16x16x128_f8f6f4 v[90:93], v[18:25], v[198:205], v[90:93], v1, v186 op_sel_hi:[0,0,0]
	v_mfma_scale_f32_16x16x128_f8f6f4 v[82:85], v[26:33], v[198:205], v[82:85], v1, v186 op_sel_hi:[0,0,0]
	v_mfma_scale_f32_16x16x128_f8f6f4 v[74:77], v[18:25], v[206:213], v[74:77], v1, v186 op_sel_hi:[0,0,0]
	v_mfma_scale_f32_16x16x128_f8f6f4 v[66:69], v[26:33], v[206:213], v[66:69], v1, v186 op_sel_hi:[0,0,0]
	v_mfma_scale_f32_16x16x128_f8f6f4 v[58:61], v[18:25], v[214:221], v[58:61], v1, v186 op_sel_hi:[0,0,0]
	v_mfma_scale_f32_16x16x128_f8f6f4 v[50:53], v[26:33], v[214:221], v[50:53], v1, v186 op_sel_hi:[0,0,0]
	v_mfma_scale_f32_16x16x128_f8f6f4 v[42:45], v[18:25], v[222:229], v[42:45], v1, v186 op_sel_hi:[0,0,0]
	v_mfma_scale_f32_16x16x128_f8f6f4 v[34:37], v[26:33], v[222:229], v[34:37], v1, v186 op_sel_hi:[0,0,0]
	s_setprio 0
	s_barrier
	s_add_i32 s55, s55, 2
	s_add_u32 s20, s20, 0x100
	s_addc_u32 s21, s21, 0
	s_add_u32 s53, s53, 0x100
	s_addc_u32 s54, s54, 0
	s_cmp_gt_u32 s55, 13
	s_cbranch_scc0 .LBB0_1422
	s_and_b64 vcc, exec, s[8:9]
	s_cbranch_vccz .LBB0_1425
	s_barrier

; #define PG8_STAGE(bufoff, gbase, voff) do { _Pragma("unroll") for (int _i = 0; _i < 2; ++_i) \
;         __builtin_amdgcn_global_load_lds((const unsigned*)((const char*)(gbase) + (voff)[_i]), (PG8_LAS unsigned*)(lds + (bufoff) + ldsw + _i * 8192), 16, 0, 0); } while (0)
; #define PG8_LDA(dst, b, h) do { _Pragma("unroll") for (int m = 0; m < 4; ++m) _Pragma("unroll") for (int k = 0; k < 2; ++k) dst[m][k] = *(const PG8_LAS bf16x8*)(lds + PG8_SA(b, h) + aoff + m * 2048 + k * 1024); } while (0)
; #define PG8_LDB(dst, b, h) do { _Pragma("unroll") for (int n = 0; n < 2; ++n) _Pragma("unroll") for (int k = 0; k < 2; ++k) dst[n][k] = *(const PG8_LAS bf16x8*)(lds + PG8_SB(b, h) + boff + n * 2048 + k * 1024); } while (0)
; #define PG8_WAIT_V(n) asm volatile("s_waitcnt vmcnt(" #n ")" ::: "memory")
; #define PG8_WAIT_L(n) asm volatile("s_waitcnt lgkmcnt(" #n ")" ::: "memory")
; #define PG8_BAR __builtin_amdgcn_s_barrier()
; template <class Epi, class Sched, bool ALIGN_EPI = false>
; __device__ __forceinline__ void gemm_phase8(PG8_LAS unsigned char* lds, const Gemm g, const Sched& S, const Epi& E) {
;     ...
;         const size_t nko = (has_next && nxt.kp > 0) ? (size_t)nxt.kp * g.kpiece : 0;
;         const char* nA = has_next ? (const char*)g.A + (size_t)nxt.pm * tstepA + (size_t)nxt.pn * astep + nko : cA; const char* nB = has_next ? (const char*)g.Bt + (size_t)nxt.pn * tstepB + nko : cB;
;         const int nt = (cur.kp < 0 ? g.K : g.kpiece) / 128;
;         for (int t = 0; t < nt; t += 2) {
;             const bool last = (t == nt - 2);
;             const char* a1 = cA + (size_t)(t + 1) * kstep;
;             const char* a2 = last ? nA : cA + (size_t)(t + 2) * kstep; const char* b2 = last ? nB : cB + (size_t)(t + 2) * kstep;
;             const char* a3 = a2 + kstep; const char* b3 = b2 + kstep;
;             if (last && has_next) S.a_ready(nxt);
;             PG8_LDB(B0, 0, 0); PG8_LDB(B1, 0, 1); PG8_SCHED; PG8_LDA(At, 0, 0); PG8_STAGE(PG8_SA(1, 1), a1 + hstepA, voffA);
;             PG8_WAIT_V(8); PG8_WAIT_L(0); PG8_BAR; PG8_MMA(0, 0, At, B0); PG8_MMA(0, 1, At, B1); PG8_BAR; PG8_SCHED;
;             PG8_LDA(At, 0, 1); PG8_STAGE(PG8_SB(0, 0), b2, voffB); PG8_STAGE(PG8_SB(0, 1), b2 + hstepB, voffB); PG8_STAGE(PG8_SA(0, 0), a2, voffA);
;             PG8_WAIT_V(8); PG8_WAIT_L(0); PG8_BAR; PG8_MMA(1, 0, At, B0); PG8_MMA(1, 1, At, B1); PG8_BAR; PG8_SCHED;
.LBB0_1510:
	s_cmp_gt_i32 s30, -1
	s_cselect_b64 s[36:37], -1, 0
	s_cmp_lt_i32 s30, 0
	s_cselect_b32 s31, 44, 4
	s_add_i32 s79, s31, -2
	s_add_u32 s38, s38, 0xb0080
	s_addc_u32 s39, s39, 0
	s_add_u32 s80, s34, 0x100
	s_mov_b32 s40, 0
	s_addc_u32 s81, s35, 0
	ds_read_b128 v[18:21], v187
	ds_read_b128 v[26:29], v187 offset:2048
	ds_read_b128 v[22:25], v188
	ds_read_b128 v[30:33], v188 offset:2048
	ds_read_b128 v[2:5], v189
	ds_read_b128 v[10:13], v189 offset:2048
	ds_read_b128 v[6:9], v190
	ds_read_b128 v[14:17], v190 offset:2048
	s_add_i32 s82, s40, 2
	s_add_u32 s34, s38, 0xfff50080
	s_addc_u32 s35, s39, -1
	s_cmp_eq_u32 s79, s40
	s_cselect_b32 s40, s26, s34
	s_cselect_b32 s41, s27, s35
	s_cselect_b32 s35, s29, s81
	s_cselect_b32 s34, s28, s80
	s_add_i32 m0, s52, 0xc000
	ds_read_b128 v[174:177], v191
	ds_read_b128 v[194:197], v191 offset:2048
	ds_read_b128 v[178:181], v192
	ds_read_b128 v[198:201], v192 offset:2048
	ds_read_b128 v[202:205], v191 offset:4096
	ds_read_b128 v[210:213], v191 offset:6144
	ds_read_b128 v[206:209], v192 offset:4096
	ds_read_b128 v[214:217], v192 offset:6144
	global_load_lds_dwordx4 v170, s[38:39]
	s_add_i32 m0, s52, 0xe000
	s_nop 0
	global_load_lds_dwordx4 v172, s[38:39]
	s_waitcnt vmcnt(8)
	s_waitcnt lgkmcnt(0)
	s_barrier
	s_setprio 1
	s_waitcnt lgkmcnt(0)
	v_mfma_scale_f32_16x16x128_f8f6f4 v[158:161], v[18:25], v[174:181], 0, v1, v182 op_sel_hi:[0,0,0]
	v_mfma_scale_f32_16x16x128_f8f6f4 v[154:157], v[26:33], v[174:181], 0, v1, v182 op_sel_hi:[0,0,0]
	v_mfma_scale_f32_16x16x128_f8f6f4 v[150:153], v[18:25], v[194:201], 0, v1, v182 op_sel_hi:[0,0,0]
	v_mfma_scale_f32_16x16x128_f8f6f4 v[138:141], v[26:33], v[194:201], 0, v1, v182 op_sel_hi:[0,0,0]
	v_mfma_scale_f32_16x16x128_f8f6f4 v[130:133], v[18:25], v[202:209], 0, v1, v182 op_sel_hi:[0,0,0]
	v_mfma_scale_f32_16x16x128_f8f6f4 v[122:125], v[26:33], v[202:209], 0, v1, v182 op_sel_hi:[0,0,0]
	v_mfma_scale_f32_16x16x128_f8f6f4 v[118:121], v[18:25], v[210:217], 0, v1, v182 op_sel_hi:[0,0,0]
	v_mfma_scale_f32_16x16x128_f8f6f4 v[106:109], v[26:33], v[210:217], 0, v1, v182 op_sel_hi:[0,0,0]
	s_setprio 0
	s_setprio 1
	v_mfma_scale_f32_16x16x128_f8f6f4 v[146:149], v[2:9], v[174:181], 0, v1, v182 op_sel_hi:[0,0,0]
	v_mfma_scale_f32_16x16x128_f8f6f4 v[142:145], v[10:17], v[174:181], 0, v1, v182 op_sel_hi:[0,0,0]
	v_mfma_scale_f32_16x16x128_f8f6f4 v[134:137], v[2:9], v[194:201], 0, v1, v182 op_sel_hi:[0,0,0]
	v_mfma_scale_f32_16x16x128_f8f6f4 v[126:129], v[10:17], v[194:201], 0, v1, v182 op_sel_hi:[0,0,0]
	v_mfma_scale_f32_16x16x128_f8f6f4 v[114:117], v[2:9], v[202:209], 0, v1, v182 op_sel_hi:[0,0,0]
	v_mfma_scale_f32_16x16x128_f8f6f4 v[110:113], v[10:17], v[202:209], 0, v1, v182 op_sel_hi:[0,0,0]
	v_mfma_scale_f32_16x16x128_f8f6f4 v[102:105], v[2:9], v[210:217], 0, v1, v182 op_sel_hi:[0,0,0]
	v_mfma_scale_f32_16x16x128_f8f6f4 v[98:101], v[10:17], v[210:217], 0, v1, v182 op_sel_hi:[0,0,0]
	s_setprio 0
	s_barrier
	s_add_i32 s83, s63, s45
	s_mov_b32 m0, s83
	ds_read_b128 v[194:197], v191 offset:16384
	ds_read_b128 v[202:205], v191 offset:18432
	ds_read_b128 v[198:201], v192 offset:16384
	ds_read_b128 v[206:209], v192 offset:18432
	ds_read_b128 v[210:213], v191 offset:20480
	ds_read_b128 v[218:221], v191 offset:22528
	ds_read_b128 v[214:217], v192 offset:20480
	ds_read_b128 v[222:225], v192 offset:22528
	global_load_lds_dwordx4 v164, s[34:35]
	s_add_i32 m0, s83, 0x2000
	s_add_u32 s84, s34, 0xb0000
	s_addc_u32 s85, s35, 0
	s_add_i32 s83, s64, s45
	global_load_lds_dwordx4 v168, s[34:35]
	s_mov_b32 m0, s83
	s_nop 0
	global_load_lds_dwordx4 v164, s[84:85]
	s_add_i32 m0, s83, 0x2000
	s_nop 0
	global_load_lds_dwordx4 v168, s[84:85]
	s_mov_b32 m0, s52
	s_nop 0
	global_load_lds_dwordx4 v162, s[40:41]
	s_mov_b32 m0, s53
	s_nop 0
	global_load_lds_dwordx4 v166, s[40:41]
	s_waitcnt vmcnt(8)
	s_waitcnt lgkmcnt(0)
	s_barrier
	s_setprio 1
	s_waitcnt lgkmcnt(0)
	v_mfma_scale_f32_16x16x128_f8f6f4 v[94:97], v[18:25], v[194:201], 0, v1, v182 op_sel_hi:[0,0,0]
	v_mfma_scale_f32_16x16x128_f8f6f4 v[90:93], v[26:33], v[194:201], 0, v1, v182 op_sel_hi:[0,0,0]
	v_mfma_scale_f32_16x16x128_f8f6f4 v[82:85], v[18:25], v[202:209], 0, v1, v182 op_sel_hi:[0,0,0]
	v_mfma_scale_f32_16x16x128_f8f6f4 v[74:77], v[26:33], v[202:209], 0, v1, v182 op_sel_hi:[0,0,0]
	v_mfma_scale_f32_16x16x128_f8f6f4 v[66:69], v[18:25], v[210:217], 0, v1, v182 op_sel_hi:[0,0,0]
	v_mfma_scale_f32_16x16x128_f8f6f4 v[58:61], v[26:33], v[210:217], 0, v1, v182 op_sel_hi:[0,0,0]
	v_mfma_scale_f32_16x16x128_f8f6f4 v[50:53], v[18:25], v[218:225], 0, v1, v182 op_sel_hi:[0,0,0]
	v_mfma_scale_f32_16x16x128_f8f6f4 v[42:45], v[26:33], v[218:225], 0, v1, v182 op_sel_hi:[0,0,0]
	s_setprio 0
	s_setprio 1
	v_mfma_scale_f32_16x16x128_f8f6f4 v[86:89], v[2:9], v[194:201], 0, v1, v182 op_sel_hi:[0,0,0]
	v_mfma_scale_f32_16x16x128_f8f6f4 v[78:81], v[10:17], v[194:201], 0, v1, v182 op_sel_hi:[0,0,0]
	v_mfma_scale_f32_16x16x128_f8f6f4 v[70:73], v[2:9], v[202:209], 0, v1, v182 op_sel_hi:[0,0,0]
	v_mfma_scale_f32_16x16x128_f8f6f4 v[62:65], v[10:17], v[202:209], 0, v1, v182 op_sel_hi:[0,0,0]
	v_mfma_scale_f32_16x16x128_f8f6f4 v[54:57], v[2:9], v[210:217], 0, v1, v182 op_sel_hi:[0,0,0]
	v_mfma_scale_f32_16x16x128_f8f6f4 v[46:49], v[10:17], v[210:217], 0, v1, v182 op_sel_hi:[0,0,0]
	v_mfma_scale_f32_16x16x128_f8f6f4 v[38:41], v[2:9], v[218:225], 0, v1, v182 op_sel_hi:[0,0,0]
	v_mfma_scale_f32_16x16x128_f8f6f4 v[34:37], v[10:17], v[218:225], 0, v1, v182 op_sel_hi:[0,0,0]
	s_setprio 0
	s_barrier
; #define PG8_STAGE(bufoff, gbase, voff) do { _Pragma("unroll") for (int _i = 0; _i < 2; ++_i) \
;         __builtin_amdgcn_global_load_lds((const unsigned*)((const char*)(gbase) + (voff)[_i]), (PG8_LAS unsigned*)(lds + (bufoff) + ldsw + _i * 8192), 16, 0, 0); } while (0)
; #define PG8_LDA(dst, b, h) do { _Pragma("unroll") for (int m = 0; m < 4; ++m) _Pragma("unroll") for (int k = 0; k < 2; ++k) dst[m][k] = *(const PG8_LAS bf16x8*)(lds + PG8_SA(b, h) + aoff + m * 2048 + k * 1024); } while (0)
; #define PG8_LDB(dst, b, h) do { _Pragma("unroll") for (int n = 0; n < 2; ++n) _Pragma("unroll") for (int k = 0; k < 2; ++k) dst[n][k] = *(const PG8_LAS bf16x8*)(lds + PG8_SB(b, h) + boff + n * 2048 + k * 1024); } while (0)
; #define PG8_MMA(ai, bj, At, Bt) do { __builtin_amdgcn_s_setprio(1); _Pragma("unroll") for (int m = 0; m < 4; ++m) _Pragma("unroll") for (int n = 0; n < 2; ++n) _Pragma("unroll") for (int k = 0; k < 2; ++k) \
;         acc[ai][bj][m][n] = __builtin_amdgcn_mfma_f32_16x16x32_bf16(Bt[n][k], At[m][k], acc[ai][bj][m][n], 0, 0, 0); __builtin_amdgcn_s_setprio(0); } while (0)
; #define PG8_WAIT_V(n) asm volatile("s_waitcnt vmcnt(" #n ")" ::: "memory")
; #define PG8_WAIT_L(n) asm volatile("s_waitcnt lgkmcnt(" #n ")" ::: "memory")
; #define PG8_BAR __builtin_amdgcn_s_barrier()
; #define PG8_SCHED __builtin_amdgcn_sched_barrier(0)
; #define PG8_STAGE(bufoff, gbase, voff) do { _Pragma("unroll") for (int _i = 0; _i < 2; ++_i) \
;         __builtin_amdgcn_global_load_lds((const unsigned*)((const char*)(gbase) + (voff)[_i]), (PG8_LAS unsigned*)(lds + (bufoff) + ldsw + _i * 8192), 16, 0, 0); } while (0)
; #define PG8_BAR __builtin_amdgcn_s_barrier()
; template <class Epi, class Sched, bool ALIGN_EPI = false>
; __device__ __forceinline__ void gemm_phase8(PG8_LAS unsigned char* lds, const Gemm g, const Sched& S, const Epi& E) {
;     ...
;             PG8_LDB(B0, 1, 0); PG8_LDB(B1, 1, 1); PG8_SCHED; PG8_LDA(At, 1, 0); PG8_STAGE(PG8_SA(0, 1), a2 + hstepA, voffA);
;             PG8_WAIT_V(8); PG8_WAIT_L(0); PG8_BAR; PG8_MMA(0, 0, At, B0); PG8_MMA(0, 1, At, B1); PG8_BAR; PG8_SCHED;
;             PG8_LDA(At, 1, 1); PG8_STAGE(PG8_SB(1, 0), b3, voffB); PG8_STAGE(PG8_SB(1, 1), b3 + hstepB, voffB); PG8_STAGE(PG8_SA(1, 0), a3, voffA);
;             PG8_WAIT_V(8); PG8_WAIT_L(0); PG8_BAR; PG8_MMA(1, 0, At, B0); PG8_MMA(1, 1, At, B1); PG8_BAR; PG8_SCHED;
;         }
	s_add_i32 s83, 0, 0x18000
	s_add_i32 s84, 0, 0x1c000
	v_add_u32_e32 v6, s83, v184
	v_add_u32_e32 v14, s83, v185
	v_add_u32_e32 v22, s84, v184
	v_add_u32_e32 v30, s84, v185
	ds_read_b128 v[2:5], v6
	ds_read_b128 v[10:13], v6 offset:2048
	ds_read_b128 v[6:9], v14
	ds_read_b128 v[14:17], v14 offset:2048
	ds_read_b128 v[18:21], v22
	ds_read_b128 v[26:29], v22 offset:2048
	ds_read_b128 v[22:25], v30
	ds_read_b128 v[30:33], v30 offset:2048
	s_add_u32 s40, s40, 0xb0000
	s_addc_u32 s41, s41, 0
	s_mov_b32 m0, s54
	ds_read_b128 v[194:197], v191 offset:32768
	ds_read_b128 v[202:205], v191 offset:34816
	ds_read_b128 v[198:201], v192 offset:32768
	ds_read_b128 v[206:209], v192 offset:34816
	ds_read_b128 v[210:213], v191 offset:36864
	ds_read_b128 v[218:221], v191 offset:38912
	ds_read_b128 v[214:217], v192 offset:36864
	ds_read_b128 v[222:225], v192 offset:38912
	global_load_lds_dwordx4 v162, s[40:41]
	s_mov_b32 m0, s55
	s_nop 0
	global_load_lds_dwordx4 v166, s[40:41]
	s_waitcnt vmcnt(8)
	s_waitcnt lgkmcnt(0)
	s_barrier
	s_setprio 1
	s_waitcnt lgkmcnt(0)
	v_mfma_scale_f32_16x16x128_f8f6f4 v[158:161], v[2:9], v[194:201], v[158:161], v1, v182 op_sel_hi:[0,0,0]
	v_mfma_scale_f32_16x16x128_f8f6f4 v[154:157], v[10:17], v[194:201], v[154:157], v1, v182 op_sel_hi:[0,0,0]
	v_mfma_scale_f32_16x16x128_f8f6f4 v[150:153], v[2:9], v[202:209], v[150:153], v1, v182 op_sel_hi:[0,0,0]
	v_mfma_scale_f32_16x16x128_f8f6f4 v[138:141], v[10:17], v[202:209], v[138:141], v1, v182 op_sel_hi:[0,0,0]
	v_mfma_scale_f32_16x16x128_f8f6f4 v[130:133], v[2:9], v[210:217], v[130:133], v1, v182 op_sel_hi:[0,0,0]
	v_mfma_scale_f32_16x16x128_f8f6f4 v[122:125], v[10:17], v[210:217], v[122:125], v1, v182 op_sel_hi:[0,0,0]
	v_mfma_scale_f32_16x16x128_f8f6f4 v[118:121], v[2:9], v[218:225], v[118:121], v1, v182 op_sel_hi:[0,0,0]
	v_mfma_scale_f32_16x16x128_f8f6f4 v[106:109], v[10:17], v[218:225], v[106:109], v1, v182 op_sel_hi:[0,0,0]
	s_setprio 0
	s_setprio 1
	v_mfma_scale_f32_16x16x128_f8f6f4 v[146:149], v[18:25], v[194:201], v[146:149], v1, v182 op_sel_hi:[0,0,0]
	v_mfma_scale_f32_16x16x128_f8f6f4 v[142:145], v[26:33], v[194:201], v[142:145], v1, v182 op_sel_hi:[0,0,0]
	v_mfma_scale_f32_16x16x128_f8f6f4 v[134:137], v[18:25], v[202:209], v[134:137], v1, v182 op_sel_hi:[0,0,0]
	v_mfma_scale_f32_16x16x128_f8f6f4 v[126:129], v[26:33], v[202:209], v[126:129], v1, v182 op_sel_hi:[0,0,0]
	v_mfma_scale_f32_16x16x128_f8f6f4 v[114:117], v[18:25], v[210:217], v[114:117], v1, v182 op_sel_hi:[0,0,0]
	v_mfma_scale_f32_16x16x128_f8f6f4 v[110:113], v[26:33], v[210:217], v[110:113], v1, v182 op_sel_hi:[0,0,0]
	v_mfma_scale_f32_16x16x128_f8f6f4 v[102:105], v[18:25], v[218:225], v[102:105], v1, v182 op_sel_hi:[0,0,0]
	v_mfma_scale_f32_16x16x128_f8f6f4 v[98:101], v[26:33], v[218:225], v[98:101], v1, v182 op_sel_hi:[0,0,0]
	s_setprio 0
	s_barrier
	s_add_i32 s101, s83, s45
	s_add_u32 s98, s34, s12
	s_addc_u32 s99, s35, s13
	s_mov_b32 m0, s101
	ds_read_b128 v[194:197], v191 offset:49152
	ds_read_b128 v[202:205], v191 offset:51200
	ds_read_b128 v[198:201], v192 offset:49152
	ds_read_b128 v[206:209], v192 offset:51200
	ds_read_b128 v[210:213], v191 offset:53248
	ds_read_b128 v[218:221], v191 offset:55296
	ds_read_b128 v[214:217], v192 offset:53248
	ds_read_b128 v[222:225], v192 offset:55296
	global_load_lds_dwordx4 v164, s[98:99]
	s_add_i32 m0, s101, 0x2000
	s_add_u32 s34, s34, 0xb0080
	s_addc_u32 s35, s35, 0
	s_add_i32 s101, s84, s45
	global_load_lds_dwordx4 v168, s[98:99]
	s_add_u32 s98, s40, s12
	s_addc_u32 s99, s41, s13
	s_sub_u32 s98, s98, 0xb0000
	s_subb_u32 s99, s99, 0
	s_mov_b32 m0, s101
	s_nop 0
	global_load_lds_dwordx4 v164, s[34:35]
	s_add_i32 m0, s101, 0x2000
	s_nop 0
	global_load_lds_dwordx4 v168, s[34:35]
	s_mov_b32 m0, s61
	s_nop 0
	global_load_lds_dwordx4 v162, s[98:99]
	s_mov_b32 m0, s62
	s_nop 0
	global_load_lds_dwordx4 v166, s[98:99]
	s_waitcnt vmcnt(8)
	s_waitcnt lgkmcnt(0)
	s_barrier
	s_setprio 1
	s_waitcnt lgkmcnt(0)
	v_mfma_scale_f32_16x16x128_f8f6f4 v[94:97], v[2:9], v[194:201], v[94:97], v1, v182 op_sel_hi:[0,0,0]
	v_mfma_scale_f32_16x16x128_f8f6f4 v[90:93], v[10:17], v[194:201], v[90:93], v1, v182 op_sel_hi:[0,0,0]
	v_mfma_scale_f32_16x16x128_f8f6f4 v[82:85], v[2:9], v[202:209], v[82:85], v1, v182 op_sel_hi:[0,0,0]
	v_mfma_scale_f32_16x16x128_f8f6f4 v[74:77], v[10:17], v[202:209], v[74:77], v1, v182 op_sel_hi:[0,0,0]
	v_mfma_scale_f32_16x16x128_f8f6f4 v[66:69], v[2:9], v[210:217], v[66:69], v1, v182 op_sel_hi:[0,0,0]
	v_mfma_scale_f32_16x16x128_f8f6f4 v[58:61], v[10:17], v[210:217], v[58:61], v1, v182 op_sel_hi:[0,0,0]
	v_mfma_scale_f32_16x16x128_f8f6f4 v[50:53], v[2:9], v[218:225], v[50:53], v1, v182 op_sel_hi:[0,0,0]
	v_mfma_scale_f32_16x16x128_f8f6f4 v[42:45], v[10:17], v[218:225], v[42:45], v1, v182 op_sel_hi:[0,0,0]
	s_setprio 0
	s_setprio 1
	v_mfma_scale_f32_16x16x128_f8f6f4 v[86:89], v[18:25], v[194:201], v[86:89], v1, v182 op_sel_hi:[0,0,0]
	v_mfma_scale_f32_16x16x128_f8f6f4 v[78:81], v[26:33], v[194:201], v[78:81], v1, v182 op_sel_hi:[0,0,0]
	v_mfma_scale_f32_16x16x128_f8f6f4 v[70:73], v[18:25], v[202:209], v[70:73], v1, v182 op_sel_hi:[0,0,0]
	v_mfma_scale_f32_16x16x128_f8f6f4 v[62:65], v[26:33], v[202:209], v[62:65], v1, v182 op_sel_hi:[0,0,0]
	v_mfma_scale_f32_16x16x128_f8f6f4 v[54:57], v[18:25], v[210:217], v[54:57], v1, v182 op_sel_hi:[0,0,0]
	v_mfma_scale_f32_16x16x128_f8f6f4 v[46:49], v[26:33], v[210:217], v[46:49], v1, v182 op_sel_hi:[0,0,0]
	v_mfma_scale_f32_16x16x128_f8f6f4 v[38:41], v[18:25], v[218:225], v[38:41], v1, v182 op_sel_hi:[0,0,0]
	v_mfma_scale_f32_16x16x128_f8f6f4 v[34:37], v[26:33], v[218:225], v[34:37], v1, v182 op_sel_hi:[0,0,0]
	s_setprio 0
	s_barrier
	s_add_u32 s38, s38, 0x100
	s_addc_u32 s39, s39, 0
	s_add_u32 s80, s80, 0x100
	s_addc_u32 s81, s81, 0
	s_cmp_ge_u32 s82, s31
	s_mov_b32 s40, s82
; #define PG8_STAGE(bufoff, gbase, voff) do { _Pragma("unroll") for (int _i = 0; _i < 2; ++_i) \
;         __builtin_amdgcn_global_load_lds((const unsigned*)((const char*)(gbase) + (voff)[_i]), (PG8_LAS unsigned*)(lds + (bufoff) + ldsw + _i * 8192), 16, 0, 0); } while (0)
; #define PG8_LDA(dst, b, h) do { _Pragma("unroll") for (int m = 0; m < 4; ++m) _Pragma("unroll") for (int k = 0; k < 2; ++k) dst[m][k] = *(const PG8_LAS bf16x8*)(lds + PG8_SA(b, h) + aoff + m * 2048 + k * 1024); } while (0)
; #define PG8_LDB(dst, b, h) do { _Pragma("unroll") for (int n = 0; n < 2; ++n) _Pragma("unroll") for (int k = 0; k < 2; ++k) dst[n][k] = *(const PG8_LAS bf16x8*)(lds + PG8_SB(b, h) + boff + n * 2048 + k * 1024); } while (0)
; #define PG8_MMA(ai, bj, At, Bt) do { __builtin_amdgcn_s_setprio(1); _Pragma("unroll") for (int m = 0; m < 4; ++m) _Pragma("unroll") for (int n = 0; n < 2; ++n) _Pragma("unroll") for (int k = 0; k < 2; ++k) \
;         acc[ai][bj][m][n] = __builtin_amdgcn_mfma_f32_16x16x32_bf16(Bt[n][k], At[m][k], acc[ai][bj][m][n], 0, 0, 0); __builtin_amdgcn_s_setprio(0); } while (0)
; #define PG8_WAIT_V(n) asm volatile("s_waitcnt vmcnt(" #n ")" ::: "memory")
; #define PG8_WAIT_L(n) asm volatile("s_waitcnt lgkmcnt(" #n ")" ::: "memory")
; template <class Epi, class Sched, bool ALIGN_EPI = false>
; __device__ __forceinline__ void gemm_phase8(PG8_LAS unsigned char* lds, const Gemm g, const Sched& S, const Epi& E) {
;     ...
;         for (int t = 0; t < nt; t += 2) {
;             const bool last = (t == nt - 2);
;             const char* a1 = cA + (size_t)(t + 1) * kstep;
;             const char* a2 = last ? nA : cA + (size_t)(t + 2) * kstep; const char* b2 = last ? nB : cB + (size_t)(t + 2) * kstep;
;             const char* a3 = a2 + kstep; const char* b3 = b2 + kstep;
;             if (last && has_next) S.a_ready(nxt);
;             PG8_LDB(B0, 0, 0); PG8_LDB(B1, 0, 1); PG8_SCHED; PG8_LDA(At, 0, 0); PG8_STAGE(PG8_SA(1, 1), a1 + hstepA, voffA);
;             PG8_WAIT_V(8); PG8_WAIT_L(0); PG8_BAR; PG8_MMA(0, 0, At, B0); PG8_MMA(0, 1, At, B1); PG8_BAR; PG8_SCHED;
;             PG8_LDA(At, 0, 1); PG8_STAGE(PG8_SB(0, 0), b2, voffB); PG8_STAGE(PG8_SB(0, 1), b2 + hstepB, voffB); PG8_STAGE(PG8_SA(0, 0), a2, voffA);
;             PG8_WAIT_V(8); PG8_WAIT_L(0); PG8_BAR; PG8_MMA(1, 0, At, B0); PG8_MMA(1, 1, At, B1); PG8_BAR; PG8_SCHED;
.LBB0_1511:
	ds_read_b128 v[18:21], v187
	ds_read_b128 v[26:29], v187 offset:2048
	ds_read_b128 v[22:25], v188
	ds_read_b128 v[30:33], v188 offset:2048
	ds_read_b128 v[2:5], v189
	ds_read_b128 v[10:13], v189 offset:2048
	ds_read_b128 v[6:9], v190
	ds_read_b128 v[14:17], v190 offset:2048
	s_add_i32 s82, s40, 2
	s_add_u32 s34, s38, 0xfff50080
	s_addc_u32 s35, s39, -1
	s_cmp_eq_u32 s79, s40
	s_cselect_b32 s40, s26, s34
	s_cselect_b32 s41, s27, s35
	s_cselect_b32 s35, s29, s81
	s_cselect_b32 s34, s28, s80
	s_add_i32 m0, s52, 0xc000
	ds_read_b128 v[174:177], v191
	ds_read_b128 v[194:197], v191 offset:2048
	ds_read_b128 v[178:181], v192
	ds_read_b128 v[198:201], v192 offset:2048
	ds_read_b128 v[202:205], v191 offset:4096
	ds_read_b128 v[210:213], v191 offset:6144
	ds_read_b128 v[206:209], v192 offset:4096
	ds_read_b128 v[214:217], v192 offset:6144
	global_load_lds_dwordx4 v170, s[38:39]
	s_add_i32 m0, s52, 0xe000
	s_nop 0
	global_load_lds_dwordx4 v172, s[38:39]
	s_waitcnt vmcnt(8)
	s_waitcnt lgkmcnt(0)
	s_barrier
	s_setprio 1
	s_waitcnt lgkmcnt(0)
	v_mfma_scale_f32_16x16x128_f8f6f4 v[158:161], v[18:25], v[174:181], v[158:161], v1, v182 op_sel_hi:[0,0,0]
	v_mfma_scale_f32_16x16x128_f8f6f4 v[154:157], v[26:33], v[174:181], v[154:157], v1, v182 op_sel_hi:[0,0,0]
	v_mfma_scale_f32_16x16x128_f8f6f4 v[150:153], v[18:25], v[194:201], v[150:153], v1, v182 op_sel_hi:[0,0,0]
	v_mfma_scale_f32_16x16x128_f8f6f4 v[138:141], v[26:33], v[194:201], v[138:141], v1, v182 op_sel_hi:[0,0,0]
	v_mfma_scale_f32_16x16x128_f8f6f4 v[130:133], v[18:25], v[202:209], v[130:133], v1, v182 op_sel_hi:[0,0,0]
	v_mfma_scale_f32_16x16x128_f8f6f4 v[122:125], v[26:33], v[202:209], v[122:125], v1, v182 op_sel_hi:[0,0,0]
	v_mfma_scale_f32_16x16x128_f8f6f4 v[118:121], v[18:25], v[210:217], v[118:121], v1, v182 op_sel_hi:[0,0,0]
	v_mfma_scale_f32_16x16x128_f8f6f4 v[106:109], v[26:33], v[210:217], v[106:109], v1, v182 op_sel_hi:[0,0,0]
	s_setprio 0
	s_setprio 1
	v_mfma_scale_f32_16x16x128_f8f6f4 v[146:149], v[2:9], v[174:181], v[146:149], v1, v182 op_sel_hi:[0,0,0]
	v_mfma_scale_f32_16x16x128_f8f6f4 v[142:145], v[10:17], v[174:181], v[142:145], v1, v182 op_sel_hi:[0,0,0]
	v_mfma_scale_f32_16x16x128_f8f6f4 v[134:137], v[2:9], v[194:201], v[134:137], v1, v182 op_sel_hi:[0,0,0]
	v_mfma_scale_f32_16x16x128_f8f6f4 v[126:129], v[10:17], v[194:201], v[126:129], v1, v182 op_sel_hi:[0,0,0]
	v_mfma_scale_f32_16x16x128_f8f6f4 v[114:117], v[2:9], v[202:209], v[114:117], v1, v182 op_sel_hi:[0,0,0]
	v_mfma_scale_f32_16x16x128_f8f6f4 v[110:113], v[10:17], v[202:209], v[110:113], v1, v182 op_sel_hi:[0,0,0]
	v_mfma_scale_f32_16x16x128_f8f6f4 v[102:105], v[2:9], v[210:217], v[102:105], v1, v182 op_sel_hi:[0,0,0]
	v_mfma_scale_f32_16x16x128_f8f6f4 v[98:101], v[10:17], v[210:217], v[98:101], v1, v182 op_sel_hi:[0,0,0]
	s_setprio 0
	s_barrier
	s_add_i32 s83, s63, s45
	s_mov_b32 m0, s83
	ds_read_b128 v[194:197], v191 offset:16384
	ds_read_b128 v[202:205], v191 offset:18432
	ds_read_b128 v[198:201], v192 offset:16384
	ds_read_b128 v[206:209], v192 offset:18432
	ds_read_b128 v[210:213], v191 offset:20480
	ds_read_b128 v[218:221], v191 offset:22528
	ds_read_b128 v[214:217], v192 offset:20480
	ds_read_b128 v[222:225], v192 offset:22528
	global_load_lds_dwordx4 v164, s[34:35]
	s_add_i32 m0, s83, 0x2000
	s_add_u32 s84, s34, 0xb0000
	s_addc_u32 s85, s35, 0
	s_add_i32 s83, s64, s45
	global_load_lds_dwordx4 v168, s[34:35]
	s_mov_b32 m0, s83
	s_nop 0
	global_load_lds_dwordx4 v164, s[84:85]
	s_add_i32 m0, s83, 0x2000
	s_nop 0
	global_load_lds_dwordx4 v168, s[84:85]
	s_mov_b32 m0, s52
	s_nop 0
	global_load_lds_dwordx4 v162, s[40:41]
	s_mov_b32 m0, s53
	s_nop 0
	global_load_lds_dwordx4 v166, s[40:41]
	s_waitcnt vmcnt(8)
	s_waitcnt lgkmcnt(0)
	s_barrier
	s_setprio 1
	s_waitcnt lgkmcnt(0)
	v_mfma_scale_f32_16x16x128_f8f6f4 v[94:97], v[18:25], v[194:201], v[94:97], v1, v182 op_sel_hi:[0,0,0]
	v_mfma_scale_f32_16x16x128_f8f6f4 v[90:93], v[26:33], v[194:201], v[90:93], v1, v182 op_sel_hi:[0,0,0]
	v_mfma_scale_f32_16x16x128_f8f6f4 v[82:85], v[18:25], v[202:209], v[82:85], v1, v182 op_sel_hi:[0,0,0]
	v_mfma_scale_f32_16x16x128_f8f6f4 v[74:77], v[26:33], v[202:209], v[74:77], v1, v182 op_sel_hi:[0,0,0]
	v_mfma_scale_f32_16x16x128_f8f6f4 v[66:69], v[18:25], v[210:217], v[66:69], v1, v182 op_sel_hi:[0,0,0]
	v_mfma_scale_f32_16x16x128_f8f6f4 v[58:61], v[26:33], v[210:217], v[58:61], v1, v182 op_sel_hi:[0,0,0]
	v_mfma_scale_f32_16x16x128_f8f6f4 v[50:53], v[18:25], v[218:225], v[50:53], v1, v182 op_sel_hi:[0,0,0]
	v_mfma_scale_f32_16x16x128_f8f6f4 v[42:45], v[26:33], v[218:225], v[42:45], v1, v182 op_sel_hi:[0,0,0]
	s_setprio 0
	s_setprio 1
	v_mfma_scale_f32_16x16x128_f8f6f4 v[86:89], v[2:9], v[194:201], v[86:89], v1, v182 op_sel_hi:[0,0,0]
	v_mfma_scale_f32_16x16x128_f8f6f4 v[78:81], v[10:17], v[194:201], v[78:81], v1, v182 op_sel_hi:[0,0,0]
	v_mfma_scale_f32_16x16x128_f8f6f4 v[70:73], v[2:9], v[202:209], v[70:73], v1, v182 op_sel_hi:[0,0,0]
	v_mfma_scale_f32_16x16x128_f8f6f4 v[62:65], v[10:17], v[202:209], v[62:65], v1, v182 op_sel_hi:[0,0,0]
	v_mfma_scale_f32_16x16x128_f8f6f4 v[54:57], v[2:9], v[210:217], v[54:57], v1, v182 op_sel_hi:[0,0,0]
	v_mfma_scale_f32_16x16x128_f8f6f4 v[46:49], v[10:17], v[210:217], v[46:49], v1, v182 op_sel_hi:[0,0,0]
	v_mfma_scale_f32_16x16x128_f8f6f4 v[38:41], v[2:9], v[218:225], v[38:41], v1, v182 op_sel_hi:[0,0,0]
	v_mfma_scale_f32_16x16x128_f8f6f4 v[34:37], v[10:17], v[218:225], v[34:37], v1, v182 op_sel_hi:[0,0,0]
	s_setprio 0
	s_barrier
; #define PG8_STAGE(bufoff, gbase, voff) do { _Pragma("unroll") for (int _i = 0; _i < 2; ++_i) \
;         __builtin_amdgcn_global_load_lds((const unsigned*)((const char*)(gbase) + (voff)[_i]), (PG8_LAS unsigned*)(lds + (bufoff) + ldsw + _i * 8192), 16, 0, 0); } while (0)
; #define PG8_LDA(dst, b, h) do { _Pragma("unroll") for (int m = 0; m < 4; ++m) _Pragma("unroll") for (int k = 0; k < 2; ++k) dst[m][k] = *(const PG8_LAS bf16x8*)(lds + PG8_SA(b, h) + aoff + m * 2048 + k * 1024); } while (0)
; #define PG8_LDB(dst, b, h) do { _Pragma("unroll") for (int n = 0; n < 2; ++n) _Pragma("unroll") for (int k = 0; k < 2; ++k) dst[n][k] = *(const PG8_LAS bf16x8*)(lds + PG8_SB(b, h) + boff + n * 2048 + k * 1024); } while (0)
; #define PG8_MMA(ai, bj, At, Bt) do { __builtin_amdgcn_s_setprio(1); _Pragma("unroll") for (int m = 0; m < 4; ++m) _Pragma("unroll") for (int n = 0; n < 2; ++n) _Pragma("unroll") for (int k = 0; k < 2; ++k) \
;         acc[ai][bj][m][n] = __builtin_amdgcn_mfma_f32_16x16x32_bf16(Bt[n][k], At[m][k], acc[ai][bj][m][n], 0, 0, 0); __builtin_amdgcn_s_setprio(0); } while (0)
; #define PG8_WAIT_V(n) asm volatile("s_waitcnt vmcnt(" #n ")" ::: "memory")
; #define PG8_WAIT_L(n) asm volatile("s_waitcnt lgkmcnt(" #n ")" ::: "memory")
; #define PG8_BAR __builtin_amdgcn_s_barrier()
; #define PG8_SCHED __builtin_amdgcn_sched_barrier(0)
; #define PG8_STAGE(bufoff, gbase, voff) do { _Pragma("unroll") for (int _i = 0; _i < 2; ++_i) \
;         __builtin_amdgcn_global_load_lds((const unsigned*)((const char*)(gbase) + (voff)[_i]), (PG8_LAS unsigned*)(lds + (bufoff) + ldsw + _i * 8192), 16, 0, 0); } while (0)
; template <class Epi, class Sched, bool ALIGN_EPI = false>
; __device__ __forceinline__ void gemm_phase8(PG8_LAS unsigned char* lds, const Gemm g, const Sched& S, const Epi& E) {
;     ...
;             PG8_LDB(B0, 1, 0); PG8_LDB(B1, 1, 1); PG8_SCHED; PG8_LDA(At, 1, 0); PG8_STAGE(PG8_SA(0, 1), a2 + hstepA, voffA);
;             PG8_WAIT_V(8); PG8_WAIT_L(0); PG8_BAR; PG8_MMA(0, 0, At, B0); PG8_MMA(0, 1, At, B1); PG8_BAR; PG8_SCHED;
;             PG8_LDA(At, 1, 1); PG8_STAGE(PG8_SB(1, 0), b3, voffB); PG8_STAGE(PG8_SB(1, 1), b3 + hstepB, voffB); PG8_STAGE(PG8_SA(1, 0), a3, voffA);
;             PG8_WAIT_V(8); PG8_WAIT_L(0); PG8_BAR; PG8_MMA(1, 0, At, B0); PG8_MMA(1, 1, At, B1); PG8_BAR; PG8_SCHED;
;         }
;         if constexpr (ALIGN_EPI) { if (wr == 0) PG8_BAR; }
	s_add_i32 s83, 0, 0x18000
	s_add_i32 s84, 0, 0x1c000
	v_add_u32_e32 v6, s83, v184
	v_add_u32_e32 v14, s83, v185
	v_add_u32_e32 v22, s84, v184
	v_add_u32_e32 v30, s84, v185
	ds_read_b128 v[2:5], v6
	ds_read_b128 v[10:13], v6 offset:2048
	ds_read_b128 v[6:9], v14
	ds_read_b128 v[14:17], v14 offset:2048
	ds_read_b128 v[18:21], v22
	ds_read_b128 v[26:29], v22 offset:2048
	ds_read_b128 v[22:25], v30
	ds_read_b128 v[30:33], v30 offset:2048
	s_add_u32 s40, s40, 0xb0000
	s_addc_u32 s41, s41, 0
	s_mov_b32 m0, s54
	ds_read_b128 v[194:197], v191 offset:32768
	ds_read_b128 v[202:205], v191 offset:34816
	ds_read_b128 v[198:201], v192 offset:32768
	ds_read_b128 v[206:209], v192 offset:34816
	ds_read_b128 v[210:213], v191 offset:36864
	ds_read_b128 v[218:221], v191 offset:38912
	ds_read_b128 v[214:217], v192 offset:36864
	ds_read_b128 v[222:225], v192 offset:38912
	global_load_lds_dwordx4 v162, s[40:41]
	s_mov_b32 m0, s55
	s_nop 0
	global_load_lds_dwordx4 v166, s[40:41]
	s_waitcnt vmcnt(8)
	s_waitcnt lgkmcnt(0)
	s_barrier
	s_setprio 1
	s_waitcnt lgkmcnt(0)
	v_mfma_scale_f32_16x16x128_f8f6f4 v[158:161], v[2:9], v[194:201], v[158:161], v1, v182 op_sel_hi:[0,0,0]
	v_mfma_scale_f32_16x16x128_f8f6f4 v[154:157], v[10:17], v[194:201], v[154:157], v1, v182 op_sel_hi:[0,0,0]
	v_mfma_scale_f32_16x16x128_f8f6f4 v[150:153], v[2:9], v[202:209], v[150:153], v1, v182 op_sel_hi:[0,0,0]
	v_mfma_scale_f32_16x16x128_f8f6f4 v[138:141], v[10:17], v[202:209], v[138:141], v1, v182 op_sel_hi:[0,0,0]
	v_mfma_scale_f32_16x16x128_f8f6f4 v[130:133], v[2:9], v[210:217], v[130:133], v1, v182 op_sel_hi:[0,0,0]
	v_mfma_scale_f32_16x16x128_f8f6f4 v[122:125], v[10:17], v[210:217], v[122:125], v1, v182 op_sel_hi:[0,0,0]
	v_mfma_scale_f32_16x16x128_f8f6f4 v[118:121], v[2:9], v[218:225], v[118:121], v1, v182 op_sel_hi:[0,0,0]
	v_mfma_scale_f32_16x16x128_f8f6f4 v[106:109], v[10:17], v[218:225], v[106:109], v1, v182 op_sel_hi:[0,0,0]
	s_setprio 0
	s_setprio 1
	v_mfma_scale_f32_16x16x128_f8f6f4 v[146:149], v[18:25], v[194:201], v[146:149], v1, v182 op_sel_hi:[0,0,0]
	v_mfma_scale_f32_16x16x128_f8f6f4 v[142:145], v[26:33], v[194:201], v[142:145], v1, v182 op_sel_hi:[0,0,0]
	v_mfma_scale_f32_16x16x128_f8f6f4 v[134:137], v[18:25], v[202:209], v[134:137], v1, v182 op_sel_hi:[0,0,0]
	v_mfma_scale_f32_16x16x128_f8f6f4 v[126:129], v[26:33], v[202:209], v[126:129], v1, v182 op_sel_hi:[0,0,0]
	v_mfma_scale_f32_16x16x128_f8f6f4 v[114:117], v[18:25], v[210:217], v[114:117], v1, v182 op_sel_hi:[0,0,0]
	v_mfma_scale_f32_16x16x128_f8f6f4 v[110:113], v[26:33], v[210:217], v[110:113], v1, v182 op_sel_hi:[0,0,0]
	v_mfma_scale_f32_16x16x128_f8f6f4 v[102:105], v[18:25], v[218:225], v[102:105], v1, v182 op_sel_hi:[0,0,0]
	v_mfma_scale_f32_16x16x128_f8f6f4 v[98:101], v[26:33], v[218:225], v[98:101], v1, v182 op_sel_hi:[0,0,0]
	s_setprio 0
	s_barrier
	s_add_i32 s101, s83, s45
	s_add_u32 s98, s34, s12
	s_addc_u32 s99, s35, s13
	s_mov_b32 m0, s101
	ds_read_b128 v[194:197], v191 offset:49152
	ds_read_b128 v[202:205], v191 offset:51200
	ds_read_b128 v[198:201], v192 offset:49152
	ds_read_b128 v[206:209], v192 offset:51200
	ds_read_b128 v[210:213], v191 offset:53248
	ds_read_b128 v[218:221], v191 offset:55296
	ds_read_b128 v[214:217], v192 offset:53248
	ds_read_b128 v[222:225], v192 offset:55296
	global_load_lds_dwordx4 v164, s[98:99]
	s_add_i32 m0, s101, 0x2000
	s_add_u32 s34, s34, 0xb0080
	s_addc_u32 s35, s35, 0
	s_add_i32 s101, s84, s45
	global_load_lds_dwordx4 v168, s[98:99]
	s_add_u32 s98, s40, s12
	s_addc_u32 s99, s41, s13
	s_sub_u32 s98, s98, 0xb0000
	s_subb_u32 s99, s99, 0
	s_mov_b32 m0, s101
	s_nop 0
	global_load_lds_dwordx4 v164, s[34:35]
	s_add_i32 m0, s101, 0x2000
	s_nop 0
	global_load_lds_dwordx4 v168, s[34:35]
	s_mov_b32 m0, s61
	s_nop 0
	global_load_lds_dwordx4 v162, s[98:99]
	s_mov_b32 m0, s62
	s_nop 0
	global_load_lds_dwordx4 v166, s[98:99]
	s_waitcnt vmcnt(8)
	s_waitcnt lgkmcnt(0)
	s_barrier
	s_setprio 1
	s_waitcnt lgkmcnt(0)
	v_mfma_scale_f32_16x16x128_f8f6f4 v[94:97], v[2:9], v[194:201], v[94:97], v1, v182 op_sel_hi:[0,0,0]
	v_mfma_scale_f32_16x16x128_f8f6f4 v[90:93], v[10:17], v[194:201], v[90:93], v1, v182 op_sel_hi:[0,0,0]
	v_mfma_scale_f32_16x16x128_f8f6f4 v[82:85], v[2:9], v[202:209], v[82:85], v1, v182 op_sel_hi:[0,0,0]
	v_mfma_scale_f32_16x16x128_f8f6f4 v[74:77], v[10:17], v[202:209], v[74:77], v1, v182 op_sel_hi:[0,0,0]
	v_mfma_scale_f32_16x16x128_f8f6f4 v[66:69], v[2:9], v[210:217], v[66:69], v1, v182 op_sel_hi:[0,0,0]
	v_mfma_scale_f32_16x16x128_f8f6f4 v[58:61], v[10:17], v[210:217], v[58:61], v1, v182 op_sel_hi:[0,0,0]
	v_mfma_scale_f32_16x16x128_f8f6f4 v[50:53], v[2:9], v[218:225], v[50:53], v1, v182 op_sel_hi:[0,0,0]
	v_mfma_scale_f32_16x16x128_f8f6f4 v[42:45], v[10:17], v[218:225], v[42:45], v1, v182 op_sel_hi:[0,0,0]
	s_setprio 0
	s_setprio 1
	v_mfma_scale_f32_16x16x128_f8f6f4 v[86:89], v[18:25], v[194:201], v[86:89], v1, v182 op_sel_hi:[0,0,0]
	v_mfma_scale_f32_16x16x128_f8f6f4 v[78:81], v[26:33], v[194:201], v[78:81], v1, v182 op_sel_hi:[0,0,0]
	v_mfma_scale_f32_16x16x128_f8f6f4 v[70:73], v[18:25], v[202:209], v[70:73], v1, v182 op_sel_hi:[0,0,0]
	v_mfma_scale_f32_16x16x128_f8f6f4 v[62:65], v[26:33], v[202:209], v[62:65], v1, v182 op_sel_hi:[0,0,0]
	v_mfma_scale_f32_16x16x128_f8f6f4 v[54:57], v[18:25], v[210:217], v[54:57], v1, v182 op_sel_hi:[0,0,0]
	v_mfma_scale_f32_16x16x128_f8f6f4 v[46:49], v[26:33], v[210:217], v[46:49], v1, v182 op_sel_hi:[0,0,0]
	v_mfma_scale_f32_16x16x128_f8f6f4 v[38:41], v[18:25], v[218:225], v[38:41], v1, v182 op_sel_hi:[0,0,0]
	v_mfma_scale_f32_16x16x128_f8f6f4 v[34:37], v[26:33], v[218:225], v[34:37], v1, v182 op_sel_hi:[0,0,0]
	s_setprio 0
	s_barrier
	s_add_u32 s38, s38, 0x100
	s_addc_u32 s39, s39, 0
	s_add_u32 s80, s80, 0x100
	s_addc_u32 s81, s81, 0
	s_cmp_ge_u32 s82, s31
	s_mov_b32 s40, s82
	s_cbranch_scc0 .LBB0_1511
	s_and_b64 vcc, exec, s[14:15]
	s_cbranch_vccz .LBB0_1514
	s_barrier
